# GEMM K loops: the redundant s_waitcnt lgkmcnt(0) behind each pre-MFMA barrier deleted (repeats the inline-asm wait in front of the barrier); on top of kprio=lo (setprio flips deleted, static raise wav
# speedup vs baseline: 1.0012x; 1.0000x over previous
.Lkprio_311:
.LBB0_311:
	s_add_u32 s4, s62, 0xfffc0080
	s_addc_u32 s5, s63, -1
	s_add_i32 s84, 0, 0x10000
	s_cmp_eq_u32 s82, 12
	s_cselect_b32 s65, s33, s5
	s_cselect_b32 s64, s36, s4
	s_cselect_b32 s35, s53, s79
	s_cselect_b32 s34, s55, s75
	s_add_i32 s4, 0, 0x14000
	v_add_u32_e32 v164, s84, v143
	v_add_u32_e32 v180, s4, v143
	ds_read_b128 v[138:141], v164
	ds_read_b128 v[156:159], v164 offset:1024
	ds_read_b128 v[160:163], v164 offset:2048
	ds_read_b128 v[164:167], v164 offset:3072
	ds_read_b128 v[168:171], v180
	ds_read_b128 v[172:175], v180 offset:1024
	ds_read_b128 v[176:179], v180 offset:2048
	ds_read_b128 v[204:207], v180 offset:3072
	v_lshl_add_u64 v[180:181], s[62:63], 0, v[134:135]
	s_add_i32 m0, s68, 0xc000
	ds_read_b128 v[208:211], v155
	ds_read_b128 v[212:215], v155 offset:1024
	ds_read_b128 v[216:219], v155 offset:2048
	ds_read_b128 v[220:223], v155 offset:3072
	ds_read_b128 v[224:227], v155 offset:4096
	ds_read_b128 v[228:231], v155 offset:5120
	ds_read_b128 v[232:235], v155 offset:6144
	ds_read_b128 v[236:239], v155 offset:7168
	global_load_lds_dwordx4 v[180:181], off
	v_lshl_add_u64 v[180:181], s[62:63], 0, v[136:137]
	s_add_i32 m0, s68, 0xe000
	s_nop 0
	global_load_lds_dwordx4 v[180:181], off
	s_waitcnt vmcnt(8)
	s_waitcnt lgkmcnt(0)
	s_barrier
	v_mfma_f32_16x16x32_bf16 v[124:127], v[138:141], v[208:211], v[124:127]
	v_mfma_f32_16x16x32_bf16 v[120:123], v[160:163], v[208:211], v[120:123]
	v_mfma_f32_16x16x32_bf16 v[108:111], v[138:141], v[216:219], v[108:111]
	v_mfma_f32_16x16x32_bf16 v[104:107], v[160:163], v[216:219], v[104:107]
	v_mfma_f32_16x16x32_bf16 v[92:95], v[138:141], v[224:227], v[92:95]
	v_mfma_f32_16x16x32_bf16 v[88:91], v[160:163], v[224:227], v[88:91]
	v_mfma_f32_16x16x32_bf16 v[76:79], v[138:141], v[232:235], v[76:79]
	v_mfma_f32_16x16x32_bf16 v[72:75], v[160:163], v[232:235], v[72:75]
	v_mfma_f32_16x16x32_bf16 v[124:127], v[156:159], v[212:215], v[124:127]
	v_mfma_f32_16x16x32_bf16 v[120:123], v[164:167], v[212:215], v[120:123]
	v_mfma_f32_16x16x32_bf16 v[108:111], v[156:159], v[220:223], v[108:111]
	v_mfma_f32_16x16x32_bf16 v[104:107], v[164:167], v[220:223], v[104:107]
	v_mfma_f32_16x16x32_bf16 v[92:95], v[156:159], v[228:231], v[92:95]
	v_mfma_f32_16x16x32_bf16 v[88:91], v[164:167], v[228:231], v[88:91]
	v_mfma_f32_16x16x32_bf16 v[76:79], v[156:159], v[236:239], v[76:79]
	v_mfma_f32_16x16x32_bf16 v[72:75], v[164:167], v[236:239], v[72:75]
	v_mfma_f32_16x16x32_bf16 v[116:119], v[168:171], v[208:211], v[116:119]
	v_mfma_f32_16x16x32_bf16 v[112:115], v[176:179], v[208:211], v[112:115]
	v_mfma_f32_16x16x32_bf16 v[100:103], v[168:171], v[216:219], v[100:103]
	v_mfma_f32_16x16x32_bf16 v[96:99], v[176:179], v[216:219], v[96:99]
	v_mfma_f32_16x16x32_bf16 v[84:87], v[168:171], v[224:227], v[84:87]
	v_mfma_f32_16x16x32_bf16 v[80:83], v[176:179], v[224:227], v[80:83]
	v_mfma_f32_16x16x32_bf16 v[68:71], v[168:171], v[232:235], v[68:71]
	v_mfma_f32_16x16x32_bf16 v[64:67], v[176:179], v[232:235], v[64:67]
	v_mfma_f32_16x16x32_bf16 v[116:119], v[172:175], v[212:215], v[116:119]
	v_mfma_f32_16x16x32_bf16 v[112:115], v[204:207], v[212:215], v[112:115]
	v_mfma_f32_16x16x32_bf16 v[100:103], v[172:175], v[220:223], v[100:103]
	v_mfma_f32_16x16x32_bf16 v[96:99], v[204:207], v[220:223], v[96:99]
	v_mfma_f32_16x16x32_bf16 v[84:87], v[172:175], v[228:231], v[84:87]
	v_mfma_f32_16x16x32_bf16 v[80:83], v[204:207], v[228:231], v[80:83]
	v_mfma_f32_16x16x32_bf16 v[68:71], v[172:175], v[236:239], v[68:71]
	v_mfma_f32_16x16x32_bf16 v[64:67], v[204:207], v[236:239], v[64:67]
	s_barrier
	s_add_i32 s5, s84, s28
	v_lshl_add_u64 v[180:181], s[34:35], 0, v[144:145]
	s_mov_b32 m0, s5
	ds_read_b128 v[208:211], v155 offset:16384
	ds_read_b128 v[212:215], v155 offset:17408
	ds_read_b128 v[216:219], v155 offset:18432
	ds_read_b128 v[220:223], v155 offset:19456
	ds_read_b128 v[224:227], v155 offset:20480
	ds_read_b128 v[228:231], v155 offset:21504
	ds_read_b128 v[232:235], v155 offset:22528
	ds_read_b128 v[236:239], v155 offset:23552
	global_load_lds_dwordx4 v[180:181], off
	s_add_i32 m0, s5, 0x2000
	s_add_u32 s88, s34, 0x40000
	v_lshl_add_u64 v[240:241], s[34:35], 0, v[128:129]
	s_addc_u32 s89, s35, 0
	s_add_i32 s4, s4, s28
	global_load_lds_dwordx4 v[240:241], off
	v_lshl_add_u64 v[242:243], s[88:89], 0, v[144:145]
	s_mov_b32 m0, s4
	v_lshl_add_u64 v[244:245], s[64:65], 0, v[130:131]
	global_load_lds_dwordx4 v[242:243], off
	v_lshl_add_u64 v[242:243], s[88:89], 0, v[128:129]
	s_add_i32 m0, s4, 0x2000
	s_nop 0
	global_load_lds_dwordx4 v[242:243], off
	v_lshl_add_u64 v[242:243], s[64:65], 0, v[132:133]
	s_mov_b32 m0, s68
	s_nop 0
	global_load_lds_dwordx4 v[242:243], off
	s_mov_b32 m0, s69
	s_nop 0
	global_load_lds_dwordx4 v[244:245], off
	s_waitcnt vmcnt(8)
	s_waitcnt lgkmcnt(0)
	s_barrier
	v_mfma_f32_16x16x32_bf16 v[60:63], v[138:141], v[208:211], v[60:63]
	v_mfma_f32_16x16x32_bf16 v[56:59], v[160:163], v[208:211], v[56:59]
	v_mfma_f32_16x16x32_bf16 v[44:47], v[138:141], v[216:219], v[44:47]
	v_mfma_f32_16x16x32_bf16 v[40:43], v[160:163], v[216:219], v[40:43]
	v_mfma_f32_16x16x32_bf16 v[28:31], v[138:141], v[224:227], v[28:31]
	v_mfma_f32_16x16x32_bf16 v[24:27], v[160:163], v[224:227], v[24:27]
	v_mfma_f32_16x16x32_bf16 v[12:15], v[138:141], v[232:235], v[12:15]
	v_mfma_f32_16x16x32_bf16 v[8:11], v[160:163], v[232:235], v[8:11]
	v_mfma_f32_16x16x32_bf16 v[60:63], v[156:159], v[212:215], v[60:63]
	v_mfma_f32_16x16x32_bf16 v[56:59], v[164:167], v[212:215], v[56:59]
	v_mfma_f32_16x16x32_bf16 v[44:47], v[156:159], v[220:223], v[44:47]
	v_mfma_f32_16x16x32_bf16 v[40:43], v[164:167], v[220:223], v[40:43]
	v_mfma_f32_16x16x32_bf16 v[28:31], v[156:159], v[228:231], v[28:31]
	v_mfma_f32_16x16x32_bf16 v[24:27], v[164:167], v[228:231], v[24:27]
	v_mfma_f32_16x16x32_bf16 v[12:15], v[156:159], v[236:239], v[12:15]
	v_mfma_f32_16x16x32_bf16 v[8:11], v[164:167], v[236:239], v[8:11]
	v_mfma_f32_16x16x32_bf16 v[52:55], v[168:171], v[208:211], v[52:55]
	v_mfma_f32_16x16x32_bf16 v[48:51], v[176:179], v[208:211], v[48:51]
	v_mfma_f32_16x16x32_bf16 v[36:39], v[168:171], v[216:219], v[36:39]
	v_mfma_f32_16x16x32_bf16 v[32:35], v[176:179], v[216:219], v[32:35]
	v_mfma_f32_16x16x32_bf16 v[20:23], v[168:171], v[224:227], v[20:23]
	v_mfma_f32_16x16x32_bf16 v[16:19], v[176:179], v[224:227], v[16:19]
	v_mfma_f32_16x16x32_bf16 v[4:7], v[168:171], v[232:235], v[4:7]
	v_mfma_f32_16x16x32_bf16 v[0:3], v[176:179], v[232:235], v[0:3]
	v_mfma_f32_16x16x32_bf16 v[52:55], v[172:175], v[212:215], v[52:55]
	v_mfma_f32_16x16x32_bf16 v[48:51], v[204:207], v[212:215], v[48:51]
	v_mfma_f32_16x16x32_bf16 v[36:39], v[172:175], v[220:223], v[36:39]
	v_mfma_f32_16x16x32_bf16 v[32:35], v[204:207], v[220:223], v[32:35]
	v_mfma_f32_16x16x32_bf16 v[20:23], v[172:175], v[228:231], v[20:23]
	v_mfma_f32_16x16x32_bf16 v[16:19], v[204:207], v[228:231], v[16:19]
	v_mfma_f32_16x16x32_bf16 v[4:7], v[172:175], v[236:239], v[4:7]
	v_mfma_f32_16x16x32_bf16 v[0:3], v[204:207], v[236:239], v[0:3]
	s_barrier
	s_add_i32 s4, 0, 0x18000
	s_add_i32 s5, 0, 0x1c000
	v_add_u32_e32 v164, s4, v143
	v_add_u32_e32 v202, s5, v143
	ds_read_b128 v[138:141], v164
	ds_read_b128 v[156:159], v164 offset:1024
	ds_read_b128 v[160:163], v164 offset:2048
	ds_read_b128 v[164:167], v164 offset:3072
	ds_read_b128 v[168:171], v202
	ds_read_b128 v[172:175], v202 offset:1024
	ds_read_b128 v[176:179], v202 offset:2048
	ds_read_b128 v[204:207], v202 offset:3072
	s_add_u32 s64, s64, 0x40000
	s_addc_u32 s65, s65, 0
	s_mov_b32 m0, s70
	v_lshl_add_u64 v[246:247], s[64:65], 0, v[132:133]
	ds_read_b128 v[208:211], v155 offset:32768
	ds_read_b128 v[212:215], v155 offset:33792
	ds_read_b128 v[216:219], v155 offset:34816
	ds_read_b128 v[220:223], v155 offset:35840
	ds_read_b128 v[224:227], v155 offset:36864
	ds_read_b128 v[228:231], v155 offset:37888
	ds_read_b128 v[232:235], v155 offset:38912
	ds_read_b128 v[236:239], v155 offset:39936
	global_load_lds_dwordx4 v[246:247], off
	v_lshl_add_u64 v[246:247], s[64:65], 0, v[130:131]
	s_mov_b32 m0, s71
	s_nop 0
	global_load_lds_dwordx4 v[246:247], off
	s_waitcnt vmcnt(8)
	s_waitcnt lgkmcnt(0)
	s_barrier
	v_mfma_f32_16x16x32_bf16 v[124:127], v[138:141], v[208:211], v[124:127]
	v_mfma_f32_16x16x32_bf16 v[120:123], v[160:163], v[208:211], v[120:123]
	v_mfma_f32_16x16x32_bf16 v[108:111], v[138:141], v[216:219], v[108:111]
	v_mfma_f32_16x16x32_bf16 v[104:107], v[160:163], v[216:219], v[104:107]
	v_mfma_f32_16x16x32_bf16 v[92:95], v[138:141], v[224:227], v[92:95]
	v_mfma_f32_16x16x32_bf16 v[88:91], v[160:163], v[224:227], v[88:91]
	v_mfma_f32_16x16x32_bf16 v[76:79], v[138:141], v[232:235], v[76:79]
	v_mfma_f32_16x16x32_bf16 v[72:75], v[160:163], v[232:235], v[72:75]
	v_mfma_f32_16x16x32_bf16 v[124:127], v[156:159], v[212:215], v[124:127]
	v_mfma_f32_16x16x32_bf16 v[120:123], v[164:167], v[212:215], v[120:123]
	v_mfma_f32_16x16x32_bf16 v[108:111], v[156:159], v[220:223], v[108:111]
	v_mfma_f32_16x16x32_bf16 v[104:107], v[164:167], v[220:223], v[104:107]
	v_mfma_f32_16x16x32_bf16 v[92:95], v[156:159], v[228:231], v[92:95]
	v_mfma_f32_16x16x32_bf16 v[88:91], v[164:167], v[228:231], v[88:91]
	v_mfma_f32_16x16x32_bf16 v[76:79], v[156:159], v[236:239], v[76:79]
	v_mfma_f32_16x16x32_bf16 v[72:75], v[164:167], v[236:239], v[72:75]
	v_mfma_f32_16x16x32_bf16 v[116:119], v[168:171], v[208:211], v[116:119]
	v_mfma_f32_16x16x32_bf16 v[112:115], v[176:179], v[208:211], v[112:115]
	v_mfma_f32_16x16x32_bf16 v[100:103], v[168:171], v[216:219], v[100:103]
	v_mfma_f32_16x16x32_bf16 v[96:99], v[176:179], v[216:219], v[96:99]
	v_mfma_f32_16x16x32_bf16 v[84:87], v[168:171], v[224:227], v[84:87]
	v_mfma_f32_16x16x32_bf16 v[80:83], v[176:179], v[224:227], v[80:83]
	v_mfma_f32_16x16x32_bf16 v[68:71], v[168:171], v[232:235], v[68:71]
	v_mfma_f32_16x16x32_bf16 v[64:67], v[176:179], v[232:235], v[64:67]
	v_mfma_f32_16x16x32_bf16 v[116:119], v[172:175], v[212:215], v[116:119]
	v_mfma_f32_16x16x32_bf16 v[112:115], v[204:207], v[212:215], v[112:115]
	v_mfma_f32_16x16x32_bf16 v[100:103], v[172:175], v[220:223], v[100:103]
	v_mfma_f32_16x16x32_bf16 v[96:99], v[204:207], v[220:223], v[96:99]
	v_mfma_f32_16x16x32_bf16 v[84:87], v[172:175], v[228:231], v[84:87]
	v_mfma_f32_16x16x32_bf16 v[80:83], v[204:207], v[228:231], v[80:83]
	v_mfma_f32_16x16x32_bf16 v[68:71], v[172:175], v[236:239], v[68:71]
	v_mfma_f32_16x16x32_bf16 v[64:67], v[204:207], v[236:239], v[64:67]
	s_barrier
	s_add_i32 s4, s4, s28
	v_lshl_add_u64 v[180:181], v[180:181], 0, s[26:27]
	s_mov_b32 m0, s4
	ds_read_b128 v[208:211], v155 offset:49152
	ds_read_b128 v[212:215], v155 offset:50176
	ds_read_b128 v[216:219], v155 offset:51200
	ds_read_b128 v[220:223], v155 offset:52224
	ds_read_b128 v[224:227], v155 offset:53248
	ds_read_b128 v[228:231], v155 offset:54272
	ds_read_b128 v[232:235], v155 offset:55296
	ds_read_b128 v[236:239], v155 offset:56320
	global_load_lds_dwordx4 v[180:181], off
	s_add_i32 m0, s4, 0x2000
	s_add_u32 s34, s34, 0x40080
	v_lshl_add_u64 v[180:181], v[240:241], 0, s[26:27]
	s_addc_u32 s35, s35, 0
	s_add_i32 s4, s5, s28
	global_load_lds_dwordx4 v[180:181], off
	v_lshl_add_u64 v[180:181], s[34:35], 0, v[144:145]
	s_mov_b32 m0, s4
	s_nop 0
	global_load_lds_dwordx4 v[180:181], off
	v_lshl_add_u64 v[180:181], s[34:35], 0, v[128:129]
	s_add_i32 m0, s4, 0x2000
	s_nop 0
	global_load_lds_dwordx4 v[180:181], off
	v_lshl_add_u64 v[180:181], v[242:243], 0, s[26:27]
	s_mov_b32 m0, s72
	s_nop 0
	global_load_lds_dwordx4 v[180:181], off
	v_lshl_add_u64 v[180:181], v[244:245], 0, s[26:27]
	s_mov_b32 m0, s73
	s_nop 0
	global_load_lds_dwordx4 v[180:181], off
	s_waitcnt vmcnt(8)
	s_waitcnt lgkmcnt(0)
	s_barrier
	v_mfma_f32_16x16x32_bf16 v[60:63], v[138:141], v[208:211], v[60:63]
	v_mfma_f32_16x16x32_bf16 v[56:59], v[160:163], v[208:211], v[56:59]
	v_mfma_f32_16x16x32_bf16 v[44:47], v[138:141], v[216:219], v[44:47]
	v_mfma_f32_16x16x32_bf16 v[40:43], v[160:163], v[216:219], v[40:43]
	v_mfma_f32_16x16x32_bf16 v[28:31], v[138:141], v[224:227], v[28:31]
	v_mfma_f32_16x16x32_bf16 v[24:27], v[160:163], v[224:227], v[24:27]
	v_mfma_f32_16x16x32_bf16 v[12:15], v[138:141], v[232:235], v[12:15]
	v_mfma_f32_16x16x32_bf16 v[8:11], v[160:163], v[232:235], v[8:11]
	v_mfma_f32_16x16x32_bf16 v[60:63], v[156:159], v[212:215], v[60:63]
	v_mfma_f32_16x16x32_bf16 v[56:59], v[164:167], v[212:215], v[56:59]
	v_mfma_f32_16x16x32_bf16 v[44:47], v[156:159], v[220:223], v[44:47]
	v_mfma_f32_16x16x32_bf16 v[40:43], v[164:167], v[220:223], v[40:43]
	v_mfma_f32_16x16x32_bf16 v[28:31], v[156:159], v[228:231], v[28:31]
	v_mfma_f32_16x16x32_bf16 v[24:27], v[164:167], v[228:231], v[24:27]
	v_mfma_f32_16x16x32_bf16 v[12:15], v[156:159], v[236:239], v[12:15]
	v_mfma_f32_16x16x32_bf16 v[8:11], v[164:167], v[236:239], v[8:11]
	v_mfma_f32_16x16x32_bf16 v[52:55], v[168:171], v[208:211], v[52:55]
	v_mfma_f32_16x16x32_bf16 v[48:51], v[176:179], v[208:211], v[48:51]
	v_mfma_f32_16x16x32_bf16 v[36:39], v[168:171], v[216:219], v[36:39]
	v_mfma_f32_16x16x32_bf16 v[32:35], v[176:179], v[216:219], v[32:35]
	v_mfma_f32_16x16x32_bf16 v[20:23], v[168:171], v[224:227], v[20:23]
	v_mfma_f32_16x16x32_bf16 v[16:19], v[176:179], v[224:227], v[16:19]
	v_mfma_f32_16x16x32_bf16 v[4:7], v[168:171], v[232:235], v[4:7]
	v_mfma_f32_16x16x32_bf16 v[0:3], v[176:179], v[232:235], v[0:3]
	v_mfma_f32_16x16x32_bf16 v[52:55], v[172:175], v[212:215], v[52:55]
	v_mfma_f32_16x16x32_bf16 v[48:51], v[204:207], v[212:215], v[48:51]
	v_mfma_f32_16x16x32_bf16 v[36:39], v[172:175], v[220:223], v[36:39]
	v_mfma_f32_16x16x32_bf16 v[32:35], v[204:207], v[220:223], v[32:35]
	v_mfma_f32_16x16x32_bf16 v[20:23], v[172:175], v[228:231], v[20:23]
	v_mfma_f32_16x16x32_bf16 v[16:19], v[204:207], v[228:231], v[16:19]
	v_mfma_f32_16x16x32_bf16 v[4:7], v[172:175], v[236:239], v[4:7]
	v_mfma_f32_16x16x32_bf16 v[0:3], v[204:207], v[236:239], v[0:3]
	s_barrier
	s_add_i32 s82, s82, 2
	s_add_u32 s62, s62, 0x100
	s_addc_u32 s63, s63, 0
	s_add_u32 s75, s75, 0x100
	s_addc_u32 s79, s79, 0
	s_cmp_gt_u32 s82, 13
	s_cbranch_scc0 .LBB0_311
	s_setprio 0
	v_lshl_add_u32 v140, s2, 8, v142
	v_ashrrev_i32_e32 v141, 31, v140
	v_lshl_add_u64 v[156:157], v[140:141], 4, s[48:49]
	global_load_dwordx4 v[208:211], v[156:157], off
	global_load_dwordx4 v[212:215], v[156:157], off offset:256
	global_load_dwordx4 v[216:219], v[156:157], off offset:512
	global_load_dwordx4 v[220:223], v[156:157], off offset:768
	global_load_dwordx4 v[224:227], v[156:157], off offset:2048
	global_load_dwordx4 v[228:231], v[156:157], off offset:2304
	global_load_dwordx4 v[232:235], v[156:157], off offset:2560
	global_load_dwordx4 v[236:239], v[156:157], off offset:2816
	s_and_b64 vcc, exec, s[50:51]
	s_cbranch_vccz .LBB0_314
	s_barrier

.Lkprio_406:
.LBB0_406:
	s_add_u32 s62, s60, 0x100
	s_addc_u32 s63, s61, 0
	s_add_i32 s4, 0, 0x10000
	s_cmp_eq_u32 s29, 40
	s_cselect_b32 s65, s45, s63
	s_cselect_b32 s64, s44, s62
	v_add_u32_e32 v142, s4, v160
	s_cselect_b32 s35, s59, s28
	s_cselect_b32 s34, s58, s3
	s_add_i32 s5, 0, 0x14000
	ds_read_b128 v[138:141], v142
	ds_read_b128 v[154:157], v142 offset:1024
	ds_read_b128 v[172:175], v142 offset:2048
	ds_read_b128 v[176:179], v142 offset:3072
	v_add_u32_e32 v142, s5, v160
	ds_read_b128 v[204:207], v142
	ds_read_b128 v[208:211], v142 offset:1024
	ds_read_b128 v[212:215], v142 offset:2048
	ds_read_b128 v[216:219], v142 offset:3072
	v_lshl_add_u64 v[142:143], s[60:61], 0, v[134:135]
	s_add_i32 m0, s36, 0xc000
	ds_read_b128 v[220:223], v170
	ds_read_b128 v[224:227], v170 offset:1024
	ds_read_b128 v[228:231], v170 offset:2048
	ds_read_b128 v[232:235], v170 offset:3072
	ds_read_b128 v[236:239], v170 offset:4096
	ds_read_b128 v[240:243], v170 offset:5120
	ds_read_b128 v[244:247], v170 offset:6144
	ds_read_b128 v[248:251], v170 offset:7168
	global_load_lds_dwordx4 v[142:143], off
	v_lshl_add_u64 v[142:143], s[60:61], 0, v[136:137]
	s_add_i32 m0, s36, 0xe000
	s_nop 0
	global_load_lds_dwordx4 v[142:143], off
	s_waitcnt vmcnt(8)
	s_waitcnt lgkmcnt(0)
	s_barrier
	v_mfma_f32_16x16x32_bf16 v[124:127], v[138:141], v[220:223], v[124:127]
	v_mfma_f32_16x16x32_bf16 v[120:123], v[172:175], v[220:223], v[120:123]
	v_mfma_f32_16x16x32_bf16 v[108:111], v[138:141], v[228:231], v[108:111]
	v_mfma_f32_16x16x32_bf16 v[104:107], v[172:175], v[228:231], v[104:107]
	v_mfma_f32_16x16x32_bf16 v[92:95], v[138:141], v[236:239], v[92:95]
	v_mfma_f32_16x16x32_bf16 v[88:91], v[172:175], v[236:239], v[88:91]
	v_mfma_f32_16x16x32_bf16 v[76:79], v[138:141], v[244:247], v[76:79]
	v_mfma_f32_16x16x32_bf16 v[72:75], v[172:175], v[244:247], v[72:75]
	v_mfma_f32_16x16x32_bf16 v[124:127], v[154:157], v[224:227], v[124:127]
	v_mfma_f32_16x16x32_bf16 v[120:123], v[176:179], v[224:227], v[120:123]
	v_mfma_f32_16x16x32_bf16 v[108:111], v[154:157], v[232:235], v[108:111]
	v_mfma_f32_16x16x32_bf16 v[104:107], v[176:179], v[232:235], v[104:107]
	v_mfma_f32_16x16x32_bf16 v[92:95], v[154:157], v[240:243], v[92:95]
	v_mfma_f32_16x16x32_bf16 v[88:91], v[176:179], v[240:243], v[88:91]
	v_mfma_f32_16x16x32_bf16 v[76:79], v[154:157], v[248:251], v[76:79]
	v_mfma_f32_16x16x32_bf16 v[72:75], v[176:179], v[248:251], v[72:75]
	v_mfma_f32_16x16x32_bf16 v[116:119], v[204:207], v[220:223], v[116:119]
	v_mfma_f32_16x16x32_bf16 v[112:115], v[212:215], v[220:223], v[112:115]
	v_mfma_f32_16x16x32_bf16 v[100:103], v[204:207], v[228:231], v[100:103]
	v_mfma_f32_16x16x32_bf16 v[96:99], v[212:215], v[228:231], v[96:99]
	v_mfma_f32_16x16x32_bf16 v[84:87], v[204:207], v[236:239], v[84:87]
	v_mfma_f32_16x16x32_bf16 v[80:83], v[212:215], v[236:239], v[80:83]
	v_mfma_f32_16x16x32_bf16 v[68:71], v[204:207], v[244:247], v[68:71]
	v_mfma_f32_16x16x32_bf16 v[64:67], v[212:215], v[244:247], v[64:67]
	v_mfma_f32_16x16x32_bf16 v[116:119], v[208:211], v[224:227], v[116:119]
	v_mfma_f32_16x16x32_bf16 v[112:115], v[216:219], v[224:227], v[112:115]
	v_mfma_f32_16x16x32_bf16 v[100:103], v[208:211], v[232:235], v[100:103]
	v_mfma_f32_16x16x32_bf16 v[96:99], v[216:219], v[232:235], v[96:99]
	v_mfma_f32_16x16x32_bf16 v[84:87], v[208:211], v[240:243], v[84:87]
	v_mfma_f32_16x16x32_bf16 v[80:83], v[216:219], v[240:243], v[80:83]
	v_mfma_f32_16x16x32_bf16 v[68:71], v[208:211], v[248:251], v[68:71]
	v_mfma_f32_16x16x32_bf16 v[64:67], v[216:219], v[248:251], v[64:67]
	s_barrier
	s_add_i32 s4, s4, s33
	v_lshl_add_u64 v[142:143], s[34:35], 0, v[128:129]
	s_mov_b32 m0, s4
	ds_read_b128 v[220:223], v170 offset:16384
	ds_read_b128 v[224:227], v170 offset:17408
	ds_read_b128 v[228:231], v170 offset:18432
	ds_read_b128 v[232:235], v170 offset:19456
	ds_read_b128 v[236:239], v170 offset:20480
	ds_read_b128 v[240:243], v170 offset:21504
	ds_read_b128 v[244:247], v170 offset:22528
	ds_read_b128 v[248:251], v170 offset:23552
	global_load_lds_dwordx4 v[142:143], off
	s_add_i32 m0, s4, 0x2000
	s_add_u32 s60, s34, 0xb0000
	v_lshl_add_u64 v[158:159], s[34:35], 0, v[130:131]
	s_addc_u32 s61, s35, 0
	s_add_i32 s4, s5, s33
	global_load_lds_dwordx4 v[158:159], off
	v_lshl_add_u64 v[180:181], s[60:61], 0, v[128:129]
	s_mov_b32 m0, s4
	v_lshl_add_u64 v[202:203], s[64:65], 0, v[130:131]
	global_load_lds_dwordx4 v[180:181], off
	v_lshl_add_u64 v[180:181], s[60:61], 0, v[130:131]
	s_add_i32 m0, s4, 0x2000
	s_nop 0
	global_load_lds_dwordx4 v[180:181], off
	v_lshl_add_u64 v[180:181], s[64:65], 0, v[128:129]
	s_mov_b32 m0, s36
	s_nop 0
	global_load_lds_dwordx4 v[180:181], off
	s_mov_b32 m0, s70
	s_nop 0
	global_load_lds_dwordx4 v[202:203], off
	s_waitcnt vmcnt(8)
	s_waitcnt lgkmcnt(0)
	s_barrier
	v_mfma_f32_16x16x32_bf16 v[60:63], v[138:141], v[220:223], v[60:63]
	v_mfma_f32_16x16x32_bf16 v[56:59], v[172:175], v[220:223], v[56:59]
	v_mfma_f32_16x16x32_bf16 v[44:47], v[138:141], v[228:231], v[44:47]
	v_mfma_f32_16x16x32_bf16 v[40:43], v[172:175], v[228:231], v[40:43]
	v_mfma_f32_16x16x32_bf16 v[28:31], v[138:141], v[236:239], v[28:31]
	v_mfma_f32_16x16x32_bf16 v[24:27], v[172:175], v[236:239], v[24:27]
	v_mfma_f32_16x16x32_bf16 v[12:15], v[138:141], v[244:247], v[12:15]
	v_mfma_f32_16x16x32_bf16 v[8:11], v[172:175], v[244:247], v[8:11]
	v_mfma_f32_16x16x32_bf16 v[60:63], v[154:157], v[224:227], v[60:63]
	v_mfma_f32_16x16x32_bf16 v[56:59], v[176:179], v[224:227], v[56:59]
	v_mfma_f32_16x16x32_bf16 v[44:47], v[154:157], v[232:235], v[44:47]
	v_mfma_f32_16x16x32_bf16 v[40:43], v[176:179], v[232:235], v[40:43]
	v_mfma_f32_16x16x32_bf16 v[28:31], v[154:157], v[240:243], v[28:31]
	v_mfma_f32_16x16x32_bf16 v[24:27], v[176:179], v[240:243], v[24:27]
	v_mfma_f32_16x16x32_bf16 v[12:15], v[154:157], v[248:251], v[12:15]
	v_mfma_f32_16x16x32_bf16 v[8:11], v[176:179], v[248:251], v[8:11]
	v_mfma_f32_16x16x32_bf16 v[52:55], v[204:207], v[220:223], v[52:55]
	v_mfma_f32_16x16x32_bf16 v[48:51], v[212:215], v[220:223], v[48:51]
	v_mfma_f32_16x16x32_bf16 v[36:39], v[204:207], v[228:231], v[36:39]
	v_mfma_f32_16x16x32_bf16 v[32:35], v[212:215], v[228:231], v[32:35]
	v_mfma_f32_16x16x32_bf16 v[20:23], v[204:207], v[236:239], v[20:23]
	v_mfma_f32_16x16x32_bf16 v[16:19], v[212:215], v[236:239], v[16:19]
	v_mfma_f32_16x16x32_bf16 v[4:7], v[204:207], v[244:247], v[4:7]
	v_mfma_f32_16x16x32_bf16 v[0:3], v[212:215], v[244:247], v[0:3]
	v_mfma_f32_16x16x32_bf16 v[52:55], v[208:211], v[224:227], v[52:55]
	v_mfma_f32_16x16x32_bf16 v[48:51], v[216:219], v[224:227], v[48:51]
	v_mfma_f32_16x16x32_bf16 v[36:39], v[208:211], v[232:235], v[36:39]
	v_mfma_f32_16x16x32_bf16 v[32:35], v[216:219], v[232:235], v[32:35]
	v_mfma_f32_16x16x32_bf16 v[20:23], v[208:211], v[240:243], v[20:23]
	v_mfma_f32_16x16x32_bf16 v[16:19], v[216:219], v[240:243], v[16:19]
	v_mfma_f32_16x16x32_bf16 v[4:7], v[208:211], v[248:251], v[4:7]
	v_mfma_f32_16x16x32_bf16 v[0:3], v[216:219], v[248:251], v[0:3]
	s_barrier
	s_add_i32 s4, 0, 0x18000
	v_add_u32_e32 v144, s4, v160
	s_add_i32 s5, 0, 0x1c000
	ds_read_b128 v[138:141], v144
	ds_read_b128 v[154:157], v144 offset:1024
	ds_read_b128 v[172:175], v144 offset:2048
	ds_read_b128 v[176:179], v144 offset:3072
	v_add_u32_e32 v144, s5, v160
	ds_read_b128 v[204:207], v144
	ds_read_b128 v[208:211], v144 offset:1024
	ds_read_b128 v[212:215], v144 offset:2048
	ds_read_b128 v[216:219], v144 offset:3072
	s_add_u32 s60, s64, 0xb0000
	s_addc_u32 s61, s65, 0
	s_mov_b32 m0, s71
	v_lshl_add_u64 v[252:253], s[60:61], 0, v[128:129]
	ds_read_b128 v[220:223], v170 offset:32768
	ds_read_b128 v[224:227], v170 offset:33792
	ds_read_b128 v[228:231], v170 offset:34816
	ds_read_b128 v[232:235], v170 offset:35840
	ds_read_b128 v[236:239], v170 offset:36864
	ds_read_b128 v[240:243], v170 offset:37888
	ds_read_b128 v[244:247], v170 offset:38912
	ds_read_b128 v[248:251], v170 offset:39936
	global_load_lds_dwordx4 v[252:253], off
	v_lshl_add_u64 v[252:253], s[60:61], 0, v[130:131]
	s_mov_b32 m0, s72
	s_nop 0
	global_load_lds_dwordx4 v[252:253], off
	s_waitcnt vmcnt(8)
	s_waitcnt lgkmcnt(0)
	s_barrier
	v_mfma_f32_16x16x32_bf16 v[124:127], v[138:141], v[220:223], v[124:127]
	v_mfma_f32_16x16x32_bf16 v[120:123], v[172:175], v[220:223], v[120:123]
	v_mfma_f32_16x16x32_bf16 v[108:111], v[138:141], v[228:231], v[108:111]
	v_mfma_f32_16x16x32_bf16 v[104:107], v[172:175], v[228:231], v[104:107]
	v_mfma_f32_16x16x32_bf16 v[92:95], v[138:141], v[236:239], v[92:95]
	v_mfma_f32_16x16x32_bf16 v[88:91], v[172:175], v[236:239], v[88:91]
	v_mfma_f32_16x16x32_bf16 v[76:79], v[138:141], v[244:247], v[76:79]
	v_mfma_f32_16x16x32_bf16 v[72:75], v[172:175], v[244:247], v[72:75]
	v_mfma_f32_16x16x32_bf16 v[124:127], v[154:157], v[224:227], v[124:127]
	v_mfma_f32_16x16x32_bf16 v[120:123], v[176:179], v[224:227], v[120:123]
	v_mfma_f32_16x16x32_bf16 v[108:111], v[154:157], v[232:235], v[108:111]
	v_mfma_f32_16x16x32_bf16 v[104:107], v[176:179], v[232:235], v[104:107]
	v_mfma_f32_16x16x32_bf16 v[92:95], v[154:157], v[240:243], v[92:95]
	v_mfma_f32_16x16x32_bf16 v[88:91], v[176:179], v[240:243], v[88:91]
	v_mfma_f32_16x16x32_bf16 v[76:79], v[154:157], v[248:251], v[76:79]
	v_mfma_f32_16x16x32_bf16 v[72:75], v[176:179], v[248:251], v[72:75]
	v_mfma_f32_16x16x32_bf16 v[116:119], v[204:207], v[220:223], v[116:119]
	v_mfma_f32_16x16x32_bf16 v[112:115], v[212:215], v[220:223], v[112:115]
	v_mfma_f32_16x16x32_bf16 v[100:103], v[204:207], v[228:231], v[100:103]
	v_mfma_f32_16x16x32_bf16 v[96:99], v[212:215], v[228:231], v[96:99]
	v_mfma_f32_16x16x32_bf16 v[84:87], v[204:207], v[236:239], v[84:87]
	v_mfma_f32_16x16x32_bf16 v[80:83], v[212:215], v[236:239], v[80:83]
	v_mfma_f32_16x16x32_bf16 v[68:71], v[204:207], v[244:247], v[68:71]
	v_mfma_f32_16x16x32_bf16 v[64:67], v[212:215], v[244:247], v[64:67]
	v_mfma_f32_16x16x32_bf16 v[116:119], v[208:211], v[224:227], v[116:119]
	v_mfma_f32_16x16x32_bf16 v[112:115], v[216:219], v[224:227], v[112:115]
	v_mfma_f32_16x16x32_bf16 v[100:103], v[208:211], v[232:235], v[100:103]
	v_mfma_f32_16x16x32_bf16 v[96:99], v[216:219], v[232:235], v[96:99]
	v_mfma_f32_16x16x32_bf16 v[84:87], v[208:211], v[240:243], v[84:87]
	v_mfma_f32_16x16x32_bf16 v[80:83], v[216:219], v[240:243], v[80:83]
	v_mfma_f32_16x16x32_bf16 v[68:71], v[208:211], v[248:251], v[68:71]
	v_mfma_f32_16x16x32_bf16 v[64:67], v[216:219], v[248:251], v[64:67]
	s_barrier
	s_add_i32 s4, s4, s33
	v_lshl_add_u64 v[142:143], v[142:143], 0, s[26:27]
	s_mov_b32 m0, s4
	ds_read_b128 v[220:223], v170 offset:49152
	ds_read_b128 v[224:227], v170 offset:50176
	ds_read_b128 v[228:231], v170 offset:51200
	ds_read_b128 v[232:235], v170 offset:52224
	ds_read_b128 v[236:239], v170 offset:53248
	ds_read_b128 v[240:243], v170 offset:54272
	ds_read_b128 v[244:247], v170 offset:55296
	ds_read_b128 v[248:251], v170 offset:56320
	global_load_lds_dwordx4 v[142:143], off
	s_add_i32 m0, s4, 0x2000
	s_add_u32 s34, s34, 0xb0080
	v_lshl_add_u64 v[142:143], v[158:159], 0, s[26:27]
	s_addc_u32 s35, s35, 0
	s_add_i32 s4, s5, s33
	global_load_lds_dwordx4 v[142:143], off
	v_lshl_add_u64 v[142:143], s[34:35], 0, v[128:129]
	s_mov_b32 m0, s4
	s_nop 0
	global_load_lds_dwordx4 v[142:143], off
	v_lshl_add_u64 v[142:143], s[34:35], 0, v[130:131]
	s_add_i32 m0, s4, 0x2000
	s_nop 0
	global_load_lds_dwordx4 v[142:143], off
	v_lshl_add_u64 v[142:143], v[180:181], 0, s[26:27]
	s_mov_b32 m0, s73
	s_nop 0
	global_load_lds_dwordx4 v[142:143], off
	v_lshl_add_u64 v[142:143], v[202:203], 0, s[26:27]
	s_mov_b32 m0, s74
	s_nop 0
	global_load_lds_dwordx4 v[142:143], off
	s_waitcnt vmcnt(8)
	s_waitcnt lgkmcnt(0)
	s_barrier
	v_mfma_f32_16x16x32_bf16 v[60:63], v[138:141], v[220:223], v[60:63]
	v_mfma_f32_16x16x32_bf16 v[56:59], v[172:175], v[220:223], v[56:59]
	v_mfma_f32_16x16x32_bf16 v[44:47], v[138:141], v[228:231], v[44:47]
	v_mfma_f32_16x16x32_bf16 v[40:43], v[172:175], v[228:231], v[40:43]
	v_mfma_f32_16x16x32_bf16 v[28:31], v[138:141], v[236:239], v[28:31]
	v_mfma_f32_16x16x32_bf16 v[24:27], v[172:175], v[236:239], v[24:27]
	v_mfma_f32_16x16x32_bf16 v[12:15], v[138:141], v[244:247], v[12:15]
	v_mfma_f32_16x16x32_bf16 v[8:11], v[172:175], v[244:247], v[8:11]
	v_mfma_f32_16x16x32_bf16 v[60:63], v[154:157], v[224:227], v[60:63]
	v_mfma_f32_16x16x32_bf16 v[56:59], v[176:179], v[224:227], v[56:59]
	v_mfma_f32_16x16x32_bf16 v[44:47], v[154:157], v[232:235], v[44:47]
	v_mfma_f32_16x16x32_bf16 v[40:43], v[176:179], v[232:235], v[40:43]
	v_mfma_f32_16x16x32_bf16 v[28:31], v[154:157], v[240:243], v[28:31]
	v_mfma_f32_16x16x32_bf16 v[24:27], v[176:179], v[240:243], v[24:27]
	v_mfma_f32_16x16x32_bf16 v[12:15], v[154:157], v[248:251], v[12:15]
	v_mfma_f32_16x16x32_bf16 v[8:11], v[176:179], v[248:251], v[8:11]
	v_mfma_f32_16x16x32_bf16 v[52:55], v[204:207], v[220:223], v[52:55]
	v_mfma_f32_16x16x32_bf16 v[48:51], v[212:215], v[220:223], v[48:51]
	v_mfma_f32_16x16x32_bf16 v[36:39], v[204:207], v[228:231], v[36:39]
	v_mfma_f32_16x16x32_bf16 v[32:35], v[212:215], v[228:231], v[32:35]
	v_mfma_f32_16x16x32_bf16 v[20:23], v[204:207], v[236:239], v[20:23]
	v_mfma_f32_16x16x32_bf16 v[16:19], v[212:215], v[236:239], v[16:19]
	v_mfma_f32_16x16x32_bf16 v[4:7], v[204:207], v[244:247], v[4:7]
	v_mfma_f32_16x16x32_bf16 v[0:3], v[212:215], v[244:247], v[0:3]
	v_mfma_f32_16x16x32_bf16 v[52:55], v[208:211], v[224:227], v[52:55]
	v_mfma_f32_16x16x32_bf16 v[48:51], v[216:219], v[224:227], v[48:51]
	v_mfma_f32_16x16x32_bf16 v[36:39], v[208:211], v[232:235], v[36:39]
	v_mfma_f32_16x16x32_bf16 v[32:35], v[216:219], v[232:235], v[32:35]
	v_mfma_f32_16x16x32_bf16 v[20:23], v[208:211], v[240:243], v[20:23]
	v_mfma_f32_16x16x32_bf16 v[16:19], v[216:219], v[240:243], v[16:19]
	v_mfma_f32_16x16x32_bf16 v[4:7], v[208:211], v[248:251], v[4:7]
	v_mfma_f32_16x16x32_bf16 v[0:3], v[216:219], v[248:251], v[0:3]
	s_barrier
	s_add_i32 s29, s29, 2
	s_add_u32 s3, s3, 0x100
	s_addc_u32 s28, s28, 0
	s_cmp_gt_u32 s29, 41
	s_mov_b64 s[60:61], s[62:63]
	s_cbranch_scc0 .LBB0_406
	s_setprio 0
	s_and_b64 vcc, exec, s[54:55]
	s_cbranch_vccz .LBB0_409
	s_barrier

.Lkprio_456:
.LBB0_456:
	s_add_u32 s60, s58, 0x100
	s_addc_u32 s61, s59, 0
	s_add_i32 s4, 0, 0x10000
	s_cmp_eq_u32 s51, 40
	s_cselect_b32 s63, s45, s61
	s_cselect_b32 s62, s44, s60
	s_cselect_b32 s35, s47, s29
	s_cselect_b32 s34, s46, s28
	s_add_i32 s5, 0, 0x14000
	v_add_u32_e32 v140, s4, v166
	v_add_u32_e32 v144, s5, v166
	ds_read_b128 v[128:131], v140
	ds_read_b128 v[132:135], v140 offset:1024
	ds_read_b128 v[136:139], v140 offset:2048
	ds_read_b128 v[140:143], v140 offset:3072
	ds_read_b128 v[178:181], v144
	ds_read_b128 v[204:207], v144 offset:1024
	ds_read_b128 v[208:211], v144 offset:2048
	ds_read_b128 v[212:215], v144 offset:3072
	v_lshl_add_u64 v[164:165], s[58:59], 0, v[160:161]
	s_add_i32 m0, s36, 0xc000
	ds_read_b128 v[216:219], v176
	ds_read_b128 v[220:223], v176 offset:1024
	ds_read_b128 v[224:227], v176 offset:2048
	ds_read_b128 v[228:231], v176 offset:3072
	ds_read_b128 v[232:235], v176 offset:4096
	ds_read_b128 v[236:239], v176 offset:5120
	ds_read_b128 v[240:243], v176 offset:6144
	ds_read_b128 v[244:247], v176 offset:7168
	global_load_lds_dwordx4 v[164:165], off
	v_lshl_add_u64 v[164:165], s[58:59], 0, v[162:163]
	s_add_i32 m0, s36, 0xe000
	s_nop 0
	global_load_lds_dwordx4 v[164:165], off
	s_waitcnt vmcnt(8)
	s_waitcnt lgkmcnt(0)
	s_barrier
	v_mfma_f32_16x16x32_bf16 v[124:127], v[128:131], v[216:219], v[124:127]
	v_mfma_f32_16x16x32_bf16 v[120:123], v[136:139], v[216:219], v[120:123]
	v_mfma_f32_16x16x32_bf16 v[108:111], v[128:131], v[224:227], v[108:111]
	v_mfma_f32_16x16x32_bf16 v[104:107], v[136:139], v[224:227], v[104:107]
	v_mfma_f32_16x16x32_bf16 v[92:95], v[128:131], v[232:235], v[92:95]
	v_mfma_f32_16x16x32_bf16 v[88:91], v[136:139], v[232:235], v[88:91]
	v_mfma_f32_16x16x32_bf16 v[76:79], v[128:131], v[240:243], v[76:79]
	v_mfma_f32_16x16x32_bf16 v[72:75], v[136:139], v[240:243], v[72:75]
	v_mfma_f32_16x16x32_bf16 v[124:127], v[132:135], v[220:223], v[124:127]
	v_mfma_f32_16x16x32_bf16 v[120:123], v[140:143], v[220:223], v[120:123]
	v_mfma_f32_16x16x32_bf16 v[108:111], v[132:135], v[228:231], v[108:111]
	v_mfma_f32_16x16x32_bf16 v[104:107], v[140:143], v[228:231], v[104:107]
	v_mfma_f32_16x16x32_bf16 v[92:95], v[132:135], v[236:239], v[92:95]
	v_mfma_f32_16x16x32_bf16 v[88:91], v[140:143], v[236:239], v[88:91]
	v_mfma_f32_16x16x32_bf16 v[76:79], v[132:135], v[244:247], v[76:79]
	v_mfma_f32_16x16x32_bf16 v[72:75], v[140:143], v[244:247], v[72:75]
	v_mfma_f32_16x16x32_bf16 v[116:119], v[178:181], v[216:219], v[116:119]
	v_mfma_f32_16x16x32_bf16 v[112:115], v[208:211], v[216:219], v[112:115]
	v_mfma_f32_16x16x32_bf16 v[100:103], v[178:181], v[224:227], v[100:103]
	v_mfma_f32_16x16x32_bf16 v[96:99], v[208:211], v[224:227], v[96:99]
	v_mfma_f32_16x16x32_bf16 v[84:87], v[178:181], v[232:235], v[84:87]
	v_mfma_f32_16x16x32_bf16 v[80:83], v[208:211], v[232:235], v[80:83]
	v_mfma_f32_16x16x32_bf16 v[68:71], v[178:181], v[240:243], v[68:71]
	v_mfma_f32_16x16x32_bf16 v[64:67], v[208:211], v[240:243], v[64:67]
	v_mfma_f32_16x16x32_bf16 v[116:119], v[204:207], v[220:223], v[116:119]
	v_mfma_f32_16x16x32_bf16 v[112:115], v[212:215], v[220:223], v[112:115]
	v_mfma_f32_16x16x32_bf16 v[100:103], v[204:207], v[228:231], v[100:103]
	v_mfma_f32_16x16x32_bf16 v[96:99], v[212:215], v[228:231], v[96:99]
	v_mfma_f32_16x16x32_bf16 v[84:87], v[204:207], v[236:239], v[84:87]
	v_mfma_f32_16x16x32_bf16 v[80:83], v[212:215], v[236:239], v[80:83]
	v_mfma_f32_16x16x32_bf16 v[68:71], v[204:207], v[244:247], v[68:71]
	v_mfma_f32_16x16x32_bf16 v[64:67], v[212:215], v[244:247], v[64:67]
	s_barrier
	s_add_i32 s4, s4, s33
	v_lshl_add_u64 v[164:165], s[34:35], 0, v[154:155]
	s_mov_b32 m0, s4
	ds_read_b128 v[216:219], v176 offset:16384
	ds_read_b128 v[220:223], v176 offset:17408
	ds_read_b128 v[224:227], v176 offset:18432
	ds_read_b128 v[228:231], v176 offset:19456
	ds_read_b128 v[232:235], v176 offset:20480
	ds_read_b128 v[236:239], v176 offset:21504
	ds_read_b128 v[240:243], v176 offset:22528
	ds_read_b128 v[244:247], v176 offset:23552
	global_load_lds_dwordx4 v[164:165], off
	s_add_i32 m0, s4, 0x2000
	s_add_u32 s58, s34, 0xb0000
	v_lshl_add_u64 v[248:249], s[34:35], 0, v[156:157]
	s_addc_u32 s59, s35, 0
	s_add_i32 s4, s5, s33
	global_load_lds_dwordx4 v[248:249], off
	v_lshl_add_u64 v[250:251], s[58:59], 0, v[154:155]
	s_mov_b32 m0, s4
	v_lshl_add_u64 v[252:253], s[62:63], 0, v[156:157]
	global_load_lds_dwordx4 v[250:251], off
	v_lshl_add_u64 v[250:251], s[58:59], 0, v[156:157]
	s_add_i32 m0, s4, 0x2000
	s_nop 0
	global_load_lds_dwordx4 v[250:251], off
	v_lshl_add_u64 v[250:251], s[62:63], 0, v[154:155]
	s_mov_b32 m0, s36
	s_nop 0
	global_load_lds_dwordx4 v[250:251], off
	s_mov_b32 m0, s64
	s_nop 0
	global_load_lds_dwordx4 v[252:253], off
	s_waitcnt vmcnt(8)
	s_waitcnt lgkmcnt(0)
	s_barrier
	v_mfma_f32_16x16x32_bf16 v[60:63], v[128:131], v[216:219], v[60:63]
	v_mfma_f32_16x16x32_bf16 v[56:59], v[136:139], v[216:219], v[56:59]
	v_mfma_f32_16x16x32_bf16 v[44:47], v[128:131], v[224:227], v[44:47]
	v_mfma_f32_16x16x32_bf16 v[40:43], v[136:139], v[224:227], v[40:43]
	v_mfma_f32_16x16x32_bf16 v[28:31], v[128:131], v[232:235], v[28:31]
	v_mfma_f32_16x16x32_bf16 v[24:27], v[136:139], v[232:235], v[24:27]
	v_mfma_f32_16x16x32_bf16 v[12:15], v[128:131], v[240:243], v[12:15]
	v_mfma_f32_16x16x32_bf16 v[8:11], v[136:139], v[240:243], v[8:11]
	v_mfma_f32_16x16x32_bf16 v[60:63], v[132:135], v[220:223], v[60:63]
	v_mfma_f32_16x16x32_bf16 v[56:59], v[140:143], v[220:223], v[56:59]
	v_mfma_f32_16x16x32_bf16 v[44:47], v[132:135], v[228:231], v[44:47]
	v_mfma_f32_16x16x32_bf16 v[40:43], v[140:143], v[228:231], v[40:43]
	v_mfma_f32_16x16x32_bf16 v[28:31], v[132:135], v[236:239], v[28:31]
	v_mfma_f32_16x16x32_bf16 v[24:27], v[140:143], v[236:239], v[24:27]
	v_mfma_f32_16x16x32_bf16 v[12:15], v[132:135], v[244:247], v[12:15]
	v_mfma_f32_16x16x32_bf16 v[8:11], v[140:143], v[244:247], v[8:11]
	v_mfma_f32_16x16x32_bf16 v[52:55], v[178:181], v[216:219], v[52:55]
	v_mfma_f32_16x16x32_bf16 v[48:51], v[208:211], v[216:219], v[48:51]
	v_mfma_f32_16x16x32_bf16 v[36:39], v[178:181], v[224:227], v[36:39]
	v_mfma_f32_16x16x32_bf16 v[32:35], v[208:211], v[224:227], v[32:35]
	v_mfma_f32_16x16x32_bf16 v[20:23], v[178:181], v[232:235], v[20:23]
	v_mfma_f32_16x16x32_bf16 v[16:19], v[208:211], v[232:235], v[16:19]
	v_mfma_f32_16x16x32_bf16 v[4:7], v[178:181], v[240:243], v[4:7]
	v_mfma_f32_16x16x32_bf16 v[0:3], v[208:211], v[240:243], v[0:3]
	v_mfma_f32_16x16x32_bf16 v[52:55], v[204:207], v[220:223], v[52:55]
	v_mfma_f32_16x16x32_bf16 v[48:51], v[212:215], v[220:223], v[48:51]
	v_mfma_f32_16x16x32_bf16 v[36:39], v[204:207], v[228:231], v[36:39]
	v_mfma_f32_16x16x32_bf16 v[32:35], v[212:215], v[228:231], v[32:35]
	v_mfma_f32_16x16x32_bf16 v[20:23], v[204:207], v[236:239], v[20:23]
	v_mfma_f32_16x16x32_bf16 v[16:19], v[212:215], v[236:239], v[16:19]
	v_mfma_f32_16x16x32_bf16 v[4:7], v[204:207], v[244:247], v[4:7]
	v_mfma_f32_16x16x32_bf16 v[0:3], v[212:215], v[244:247], v[0:3]
	s_barrier
	s_add_i32 s4, 0, 0x18000
	s_add_i32 s5, 0, 0x1c000
	v_add_u32_e32 v140, s4, v166
	v_add_u32_e32 v144, s5, v166
	ds_read_b128 v[128:131], v140
	ds_read_b128 v[132:135], v140 offset:1024
	ds_read_b128 v[136:139], v140 offset:2048
	ds_read_b128 v[140:143], v140 offset:3072
	ds_read_b128 v[178:181], v144
	ds_read_b128 v[204:207], v144 offset:1024
	ds_read_b128 v[208:211], v144 offset:2048
	ds_read_b128 v[212:215], v144 offset:3072
	s_add_u32 s58, s62, 0xb0000
	s_addc_u32 s59, s63, 0
	s_mov_b32 m0, s65
	v_lshl_add_u64 v[202:203], s[58:59], 0, v[154:155]
	ds_read_b128 v[216:219], v176 offset:32768
	ds_read_b128 v[220:223], v176 offset:33792
	ds_read_b128 v[224:227], v176 offset:34816
	ds_read_b128 v[228:231], v176 offset:35840
	ds_read_b128 v[232:235], v176 offset:36864
	ds_read_b128 v[236:239], v176 offset:37888
	ds_read_b128 v[240:243], v176 offset:38912
	ds_read_b128 v[244:247], v176 offset:39936
	global_load_lds_dwordx4 v[202:203], off
	v_lshl_add_u64 v[202:203], s[58:59], 0, v[156:157]
	s_mov_b32 m0, s70
	s_nop 0
	global_load_lds_dwordx4 v[202:203], off
	s_waitcnt vmcnt(8)
	s_waitcnt lgkmcnt(0)
	s_barrier
	v_mfma_f32_16x16x32_bf16 v[124:127], v[128:131], v[216:219], v[124:127]
	v_mfma_f32_16x16x32_bf16 v[120:123], v[136:139], v[216:219], v[120:123]
	v_mfma_f32_16x16x32_bf16 v[108:111], v[128:131], v[224:227], v[108:111]
	v_mfma_f32_16x16x32_bf16 v[104:107], v[136:139], v[224:227], v[104:107]
	v_mfma_f32_16x16x32_bf16 v[92:95], v[128:131], v[232:235], v[92:95]
	v_mfma_f32_16x16x32_bf16 v[88:91], v[136:139], v[232:235], v[88:91]
	v_mfma_f32_16x16x32_bf16 v[76:79], v[128:131], v[240:243], v[76:79]
	v_mfma_f32_16x16x32_bf16 v[72:75], v[136:139], v[240:243], v[72:75]
	v_mfma_f32_16x16x32_bf16 v[124:127], v[132:135], v[220:223], v[124:127]
	v_mfma_f32_16x16x32_bf16 v[120:123], v[140:143], v[220:223], v[120:123]
	v_mfma_f32_16x16x32_bf16 v[108:111], v[132:135], v[228:231], v[108:111]
	v_mfma_f32_16x16x32_bf16 v[104:107], v[140:143], v[228:231], v[104:107]
	v_mfma_f32_16x16x32_bf16 v[92:95], v[132:135], v[236:239], v[92:95]
	v_mfma_f32_16x16x32_bf16 v[88:91], v[140:143], v[236:239], v[88:91]
	v_mfma_f32_16x16x32_bf16 v[76:79], v[132:135], v[244:247], v[76:79]
	v_mfma_f32_16x16x32_bf16 v[72:75], v[140:143], v[244:247], v[72:75]
	v_mfma_f32_16x16x32_bf16 v[116:119], v[178:181], v[216:219], v[116:119]
	v_mfma_f32_16x16x32_bf16 v[112:115], v[208:211], v[216:219], v[112:115]
	v_mfma_f32_16x16x32_bf16 v[100:103], v[178:181], v[224:227], v[100:103]
	v_mfma_f32_16x16x32_bf16 v[96:99], v[208:211], v[224:227], v[96:99]
	v_mfma_f32_16x16x32_bf16 v[84:87], v[178:181], v[232:235], v[84:87]
	v_mfma_f32_16x16x32_bf16 v[80:83], v[208:211], v[232:235], v[80:83]
	v_mfma_f32_16x16x32_bf16 v[68:71], v[178:181], v[240:243], v[68:71]
	v_mfma_f32_16x16x32_bf16 v[64:67], v[208:211], v[240:243], v[64:67]
	v_mfma_f32_16x16x32_bf16 v[116:119], v[204:207], v[220:223], v[116:119]
	v_mfma_f32_16x16x32_bf16 v[112:115], v[212:215], v[220:223], v[112:115]
	v_mfma_f32_16x16x32_bf16 v[100:103], v[204:207], v[228:231], v[100:103]
	v_mfma_f32_16x16x32_bf16 v[96:99], v[212:215], v[228:231], v[96:99]
	v_mfma_f32_16x16x32_bf16 v[84:87], v[204:207], v[236:239], v[84:87]
	v_mfma_f32_16x16x32_bf16 v[80:83], v[212:215], v[236:239], v[80:83]
	v_mfma_f32_16x16x32_bf16 v[68:71], v[204:207], v[244:247], v[68:71]
	v_mfma_f32_16x16x32_bf16 v[64:67], v[212:215], v[244:247], v[64:67]
	s_barrier
	s_add_i32 s4, s4, s33
	v_lshl_add_u64 v[164:165], v[164:165], 0, s[26:27]
	s_mov_b32 m0, s4
	ds_read_b128 v[216:219], v176 offset:49152
	ds_read_b128 v[220:223], v176 offset:50176
	ds_read_b128 v[224:227], v176 offset:51200
	ds_read_b128 v[228:231], v176 offset:52224
	ds_read_b128 v[232:235], v176 offset:53248
	ds_read_b128 v[236:239], v176 offset:54272
	ds_read_b128 v[240:243], v176 offset:55296
	ds_read_b128 v[244:247], v176 offset:56320
	global_load_lds_dwordx4 v[164:165], off
	s_add_i32 m0, s4, 0x2000
	s_add_u32 s34, s34, 0xb0080
	v_lshl_add_u64 v[164:165], v[248:249], 0, s[26:27]
	s_addc_u32 s35, s35, 0
	s_add_i32 s4, s5, s33
	global_load_lds_dwordx4 v[164:165], off
	v_lshl_add_u64 v[164:165], s[34:35], 0, v[154:155]
	s_mov_b32 m0, s4
	s_nop 0
	global_load_lds_dwordx4 v[164:165], off
	v_lshl_add_u64 v[164:165], s[34:35], 0, v[156:157]
	s_add_i32 m0, s4, 0x2000
	s_nop 0
	global_load_lds_dwordx4 v[164:165], off
	v_lshl_add_u64 v[164:165], v[250:251], 0, s[26:27]
	s_mov_b32 m0, s71
	s_nop 0
	global_load_lds_dwordx4 v[164:165], off
	v_lshl_add_u64 v[164:165], v[252:253], 0, s[26:27]
	s_mov_b32 m0, s72
	s_nop 0
	global_load_lds_dwordx4 v[164:165], off
	s_waitcnt vmcnt(8)
	s_waitcnt lgkmcnt(0)
	s_barrier
	v_mfma_f32_16x16x32_bf16 v[60:63], v[128:131], v[216:219], v[60:63]
	v_mfma_f32_16x16x32_bf16 v[56:59], v[136:139], v[216:219], v[56:59]
	v_mfma_f32_16x16x32_bf16 v[44:47], v[128:131], v[224:227], v[44:47]
	v_mfma_f32_16x16x32_bf16 v[40:43], v[136:139], v[224:227], v[40:43]
	v_mfma_f32_16x16x32_bf16 v[28:31], v[128:131], v[232:235], v[28:31]
	v_mfma_f32_16x16x32_bf16 v[24:27], v[136:139], v[232:235], v[24:27]
	v_mfma_f32_16x16x32_bf16 v[12:15], v[128:131], v[240:243], v[12:15]
	v_mfma_f32_16x16x32_bf16 v[8:11], v[136:139], v[240:243], v[8:11]
	v_mfma_f32_16x16x32_bf16 v[60:63], v[132:135], v[220:223], v[60:63]
	v_mfma_f32_16x16x32_bf16 v[56:59], v[140:143], v[220:223], v[56:59]
	v_mfma_f32_16x16x32_bf16 v[44:47], v[132:135], v[228:231], v[44:47]
	v_mfma_f32_16x16x32_bf16 v[40:43], v[140:143], v[228:231], v[40:43]
	v_mfma_f32_16x16x32_bf16 v[28:31], v[132:135], v[236:239], v[28:31]
	v_mfma_f32_16x16x32_bf16 v[24:27], v[140:143], v[236:239], v[24:27]
	v_mfma_f32_16x16x32_bf16 v[12:15], v[132:135], v[244:247], v[12:15]
	v_mfma_f32_16x16x32_bf16 v[8:11], v[140:143], v[244:247], v[8:11]
	v_mfma_f32_16x16x32_bf16 v[52:55], v[178:181], v[216:219], v[52:55]
	v_mfma_f32_16x16x32_bf16 v[48:51], v[208:211], v[216:219], v[48:51]
	v_mfma_f32_16x16x32_bf16 v[36:39], v[178:181], v[224:227], v[36:39]
	v_mfma_f32_16x16x32_bf16 v[32:35], v[208:211], v[224:227], v[32:35]
	v_mfma_f32_16x16x32_bf16 v[20:23], v[178:181], v[232:235], v[20:23]
	v_mfma_f32_16x16x32_bf16 v[16:19], v[208:211], v[232:235], v[16:19]
	v_mfma_f32_16x16x32_bf16 v[4:7], v[178:181], v[240:243], v[4:7]
	v_mfma_f32_16x16x32_bf16 v[0:3], v[208:211], v[240:243], v[0:3]
	v_mfma_f32_16x16x32_bf16 v[52:55], v[204:207], v[220:223], v[52:55]
	v_mfma_f32_16x16x32_bf16 v[48:51], v[212:215], v[220:223], v[48:51]
	v_mfma_f32_16x16x32_bf16 v[36:39], v[204:207], v[228:231], v[36:39]
	v_mfma_f32_16x16x32_bf16 v[32:35], v[212:215], v[228:231], v[32:35]
	v_mfma_f32_16x16x32_bf16 v[20:23], v[204:207], v[236:239], v[20:23]
	v_mfma_f32_16x16x32_bf16 v[16:19], v[212:215], v[236:239], v[16:19]
	v_mfma_f32_16x16x32_bf16 v[4:7], v[204:207], v[244:247], v[4:7]
	v_mfma_f32_16x16x32_bf16 v[0:3], v[212:215], v[244:247], v[0:3]
	s_barrier
	s_add_i32 s51, s51, 2
	s_add_u32 s28, s28, 0x100
	s_addc_u32 s29, s29, 0
	s_cmp_gt_u32 s51, 41
	s_mov_b64 s[58:59], s[60:61]
	s_cbranch_scc0 .LBB0_456
	s_setprio 0
	s_and_b64 vcc, exec, s[54:55]
	s_cbranch_vccz .LBB0_459
	s_barrier

.Lkprio_605:
.LBB0_605:
	s_add_u32 s4, s0, 0xfffc0080
	s_addc_u32 s5, s1, -1
	s_add_i32 s89, 0, 0x10000
	s_cmp_eq_u32 s88, 12
	s_cselect_b32 s43, s3, s5
	s_cselect_b32 s42, s36, s4
	s_cselect_b32 s35, s39, s84
	s_cselect_b32 s34, s71, s79
	s_add_i32 s4, 0, 0x14000
	v_add_u32_e32 v140, s89, v203
	v_add_u32_e32 v144, s4, v203
	ds_read_b128 v[128:131], v140
	ds_read_b128 v[132:135], v140 offset:1024
	ds_read_b128 v[136:139], v140 offset:2048
	ds_read_b128 v[140:143], v140 offset:3072
	ds_read_b128 v[168:171], v144
	ds_read_b128 v[172:175], v144 offset:1024
	ds_read_b128 v[176:179], v144 offset:2048
	ds_read_b128 v[206:209], v144 offset:3072
	v_lshl_add_u64 v[180:181], s[0:1], 0, v[164:165]
	s_add_i32 m0, s69, 0xc000
	ds_read_b128 v[210:213], v205
	ds_read_b128 v[214:217], v205 offset:1024
	ds_read_b128 v[218:221], v205 offset:2048
	ds_read_b128 v[222:225], v205 offset:3072
	ds_read_b128 v[226:229], v205 offset:4096
	ds_read_b128 v[230:233], v205 offset:5120
	ds_read_b128 v[234:237], v205 offset:6144
	ds_read_b128 v[238:241], v205 offset:7168
	global_load_lds_dwordx4 v[180:181], off
	v_lshl_add_u64 v[180:181], s[0:1], 0, v[166:167]
	s_add_i32 m0, s69, 0xe000
	s_nop 0
	global_load_lds_dwordx4 v[180:181], off
	s_waitcnt vmcnt(8)
	s_waitcnt lgkmcnt(0)
	s_barrier
	v_mfma_f32_16x16x32_bf16 v[124:127], v[128:131], v[210:213], v[124:127]
	v_mfma_f32_16x16x32_bf16 v[120:123], v[136:139], v[210:213], v[120:123]
	v_mfma_f32_16x16x32_bf16 v[112:115], v[128:131], v[218:221], v[112:115]
	v_mfma_f32_16x16x32_bf16 v[108:111], v[136:139], v[218:221], v[108:111]
	v_mfma_f32_16x16x32_bf16 v[100:103], v[128:131], v[226:229], v[100:103]
	v_mfma_f32_16x16x32_bf16 v[92:95], v[136:139], v[226:229], v[92:95]
	v_mfma_f32_16x16x32_bf16 v[84:87], v[128:131], v[234:237], v[84:87]
	v_mfma_f32_16x16x32_bf16 v[76:79], v[136:139], v[234:237], v[76:79]
	v_mfma_f32_16x16x32_bf16 v[124:127], v[132:135], v[214:217], v[124:127]
	v_mfma_f32_16x16x32_bf16 v[120:123], v[140:143], v[214:217], v[120:123]
	v_mfma_f32_16x16x32_bf16 v[112:115], v[132:135], v[222:225], v[112:115]
	v_mfma_f32_16x16x32_bf16 v[108:111], v[140:143], v[222:225], v[108:111]
	v_mfma_f32_16x16x32_bf16 v[100:103], v[132:135], v[230:233], v[100:103]
	v_mfma_f32_16x16x32_bf16 v[92:95], v[140:143], v[230:233], v[92:95]
	v_mfma_f32_16x16x32_bf16 v[84:87], v[132:135], v[238:241], v[84:87]
	v_mfma_f32_16x16x32_bf16 v[76:79], v[140:143], v[238:241], v[76:79]
	v_mfma_f32_16x16x32_bf16 v[116:119], v[168:171], v[210:213], v[116:119]
	v_mfma_f32_16x16x32_bf16 v[104:107], v[176:179], v[210:213], v[104:107]
	v_mfma_f32_16x16x32_bf16 v[96:99], v[168:171], v[218:221], v[96:99]
	v_mfma_f32_16x16x32_bf16 v[88:91], v[176:179], v[218:221], v[88:91]
	v_mfma_f32_16x16x32_bf16 v[80:83], v[168:171], v[226:229], v[80:83]
	v_mfma_f32_16x16x32_bf16 v[72:75], v[176:179], v[226:229], v[72:75]
	v_mfma_f32_16x16x32_bf16 v[68:71], v[168:171], v[234:237], v[68:71]
	v_mfma_f32_16x16x32_bf16 v[64:67], v[176:179], v[234:237], v[64:67]
	v_mfma_f32_16x16x32_bf16 v[116:119], v[172:175], v[214:217], v[116:119]
	v_mfma_f32_16x16x32_bf16 v[104:107], v[206:209], v[214:217], v[104:107]
	v_mfma_f32_16x16x32_bf16 v[96:99], v[172:175], v[222:225], v[96:99]
	v_mfma_f32_16x16x32_bf16 v[88:91], v[206:209], v[222:225], v[88:91]
	v_mfma_f32_16x16x32_bf16 v[80:83], v[172:175], v[230:233], v[80:83]
	v_mfma_f32_16x16x32_bf16 v[72:75], v[206:209], v[230:233], v[72:75]
	v_mfma_f32_16x16x32_bf16 v[68:71], v[172:175], v[238:241], v[68:71]
	v_mfma_f32_16x16x32_bf16 v[64:67], v[206:209], v[238:241], v[64:67]
	s_barrier
	s_add_i32 s5, s89, s28
	v_lshl_add_u64 v[180:181], s[34:35], 0, v[156:157]
	s_mov_b32 m0, s5
	ds_read_b128 v[210:213], v205 offset:16384
	ds_read_b128 v[214:217], v205 offset:17408
	ds_read_b128 v[218:221], v205 offset:18432
	ds_read_b128 v[222:225], v205 offset:19456
	ds_read_b128 v[226:229], v205 offset:20480
	ds_read_b128 v[230:233], v205 offset:21504
	ds_read_b128 v[234:237], v205 offset:22528
	ds_read_b128 v[238:241], v205 offset:23552
	global_load_lds_dwordx4 v[180:181], off
	s_add_i32 m0, s5, 0x2000
	s_add_u32 s90, s34, 0x40000
	v_lshl_add_u64 v[242:243], s[34:35], 0, v[160:161]
	s_addc_u32 s91, s35, 0
	s_add_i32 s4, s4, s28
	global_load_lds_dwordx4 v[242:243], off
	v_lshl_add_u64 v[244:245], s[90:91], 0, v[156:157]
	s_mov_b32 m0, s4
	v_lshl_add_u64 v[246:247], s[42:43], 0, v[158:159]
	global_load_lds_dwordx4 v[244:245], off
	v_lshl_add_u64 v[244:245], s[90:91], 0, v[160:161]
	s_add_i32 m0, s4, 0x2000
	s_nop 0
	global_load_lds_dwordx4 v[244:245], off
	v_lshl_add_u64 v[244:245], s[42:43], 0, v[154:155]
	s_mov_b32 m0, s69
	s_nop 0
	global_load_lds_dwordx4 v[244:245], off
	s_mov_b32 m0, s62
	s_nop 0
	global_load_lds_dwordx4 v[246:247], off
	s_waitcnt vmcnt(8)
	s_waitcnt lgkmcnt(0)
	s_barrier
	v_mfma_f32_16x16x32_bf16 v[60:63], v[128:131], v[210:213], v[60:63]
	v_mfma_f32_16x16x32_bf16 v[56:59], v[136:139], v[210:213], v[56:59]
	v_mfma_f32_16x16x32_bf16 v[52:55], v[128:131], v[218:221], v[52:55]
	v_mfma_f32_16x16x32_bf16 v[44:47], v[136:139], v[218:221], v[44:47]
	v_mfma_f32_16x16x32_bf16 v[36:39], v[128:131], v[226:229], v[36:39]
	v_mfma_f32_16x16x32_bf16 v[28:31], v[136:139], v[226:229], v[28:31]
	v_mfma_f32_16x16x32_bf16 v[20:23], v[128:131], v[234:237], v[20:23]
	v_mfma_f32_16x16x32_bf16 v[12:15], v[136:139], v[234:237], v[12:15]
	v_mfma_f32_16x16x32_bf16 v[60:63], v[132:135], v[214:217], v[60:63]
	v_mfma_f32_16x16x32_bf16 v[56:59], v[140:143], v[214:217], v[56:59]
	v_mfma_f32_16x16x32_bf16 v[52:55], v[132:135], v[222:225], v[52:55]
	v_mfma_f32_16x16x32_bf16 v[44:47], v[140:143], v[222:225], v[44:47]
	v_mfma_f32_16x16x32_bf16 v[36:39], v[132:135], v[230:233], v[36:39]
	v_mfma_f32_16x16x32_bf16 v[28:31], v[140:143], v[230:233], v[28:31]
	v_mfma_f32_16x16x32_bf16 v[20:23], v[132:135], v[238:241], v[20:23]
	v_mfma_f32_16x16x32_bf16 v[12:15], v[140:143], v[238:241], v[12:15]
	v_mfma_f32_16x16x32_bf16 v[48:51], v[168:171], v[210:213], v[48:51]
	v_mfma_f32_16x16x32_bf16 v[40:43], v[176:179], v[210:213], v[40:43]
	v_mfma_f32_16x16x32_bf16 v[32:35], v[168:171], v[218:221], v[32:35]
	v_mfma_f32_16x16x32_bf16 v[24:27], v[176:179], v[218:221], v[24:27]
	v_mfma_f32_16x16x32_bf16 v[16:19], v[168:171], v[226:229], v[16:19]
	v_mfma_f32_16x16x32_bf16 v[8:11], v[176:179], v[226:229], v[8:11]
	v_mfma_f32_16x16x32_bf16 v[4:7], v[168:171], v[234:237], v[4:7]
	v_mfma_f32_16x16x32_bf16 v[0:3], v[176:179], v[234:237], v[0:3]
	v_mfma_f32_16x16x32_bf16 v[48:51], v[172:175], v[214:217], v[48:51]
	v_mfma_f32_16x16x32_bf16 v[40:43], v[206:209], v[214:217], v[40:43]
	v_mfma_f32_16x16x32_bf16 v[32:35], v[172:175], v[222:225], v[32:35]
	v_mfma_f32_16x16x32_bf16 v[24:27], v[206:209], v[222:225], v[24:27]
	v_mfma_f32_16x16x32_bf16 v[16:19], v[172:175], v[230:233], v[16:19]
	v_mfma_f32_16x16x32_bf16 v[8:11], v[206:209], v[230:233], v[8:11]
	v_mfma_f32_16x16x32_bf16 v[4:7], v[172:175], v[238:241], v[4:7]
	v_mfma_f32_16x16x32_bf16 v[0:3], v[206:209], v[238:241], v[0:3]
	s_barrier
	s_add_i32 s4, 0, 0x18000
	s_add_i32 s5, 0, 0x1c000
	v_add_u32_e32 v140, s4, v203
	v_add_u32_e32 v144, s5, v203
	ds_read_b128 v[128:131], v140
	ds_read_b128 v[132:135], v140 offset:1024
	ds_read_b128 v[136:139], v140 offset:2048
	ds_read_b128 v[140:143], v140 offset:3072
	ds_read_b128 v[168:171], v144
	ds_read_b128 v[172:175], v144 offset:1024
	ds_read_b128 v[176:179], v144 offset:2048
	ds_read_b128 v[206:209], v144 offset:3072
	s_add_u32 s42, s42, 0x40000
	s_addc_u32 s43, s43, 0
	s_mov_b32 m0, s63
	v_lshl_add_u64 v[248:249], s[42:43], 0, v[154:155]
	ds_read_b128 v[210:213], v205 offset:32768
	ds_read_b128 v[214:217], v205 offset:33792
	ds_read_b128 v[218:221], v205 offset:34816
	ds_read_b128 v[222:225], v205 offset:35840
	ds_read_b128 v[226:229], v205 offset:36864
	ds_read_b128 v[230:233], v205 offset:37888
	ds_read_b128 v[234:237], v205 offset:38912
	ds_read_b128 v[238:241], v205 offset:39936
	global_load_lds_dwordx4 v[248:249], off
	v_lshl_add_u64 v[248:249], s[42:43], 0, v[158:159]
	s_mov_b32 m0, s50
	s_nop 0
	global_load_lds_dwordx4 v[248:249], off
	s_waitcnt vmcnt(8)
	s_waitcnt lgkmcnt(0)
	s_barrier
	v_mfma_f32_16x16x32_bf16 v[124:127], v[128:131], v[210:213], v[124:127]
	v_mfma_f32_16x16x32_bf16 v[120:123], v[136:139], v[210:213], v[120:123]
	v_mfma_f32_16x16x32_bf16 v[112:115], v[128:131], v[218:221], v[112:115]
	v_mfma_f32_16x16x32_bf16 v[108:111], v[136:139], v[218:221], v[108:111]
	v_mfma_f32_16x16x32_bf16 v[100:103], v[128:131], v[226:229], v[100:103]
	v_mfma_f32_16x16x32_bf16 v[92:95], v[136:139], v[226:229], v[92:95]
	v_mfma_f32_16x16x32_bf16 v[84:87], v[128:131], v[234:237], v[84:87]
	v_mfma_f32_16x16x32_bf16 v[76:79], v[136:139], v[234:237], v[76:79]
	v_mfma_f32_16x16x32_bf16 v[124:127], v[132:135], v[214:217], v[124:127]
	v_mfma_f32_16x16x32_bf16 v[120:123], v[140:143], v[214:217], v[120:123]
	v_mfma_f32_16x16x32_bf16 v[112:115], v[132:135], v[222:225], v[112:115]
	v_mfma_f32_16x16x32_bf16 v[108:111], v[140:143], v[222:225], v[108:111]
	v_mfma_f32_16x16x32_bf16 v[100:103], v[132:135], v[230:233], v[100:103]
	v_mfma_f32_16x16x32_bf16 v[92:95], v[140:143], v[230:233], v[92:95]
	v_mfma_f32_16x16x32_bf16 v[84:87], v[132:135], v[238:241], v[84:87]
	v_mfma_f32_16x16x32_bf16 v[76:79], v[140:143], v[238:241], v[76:79]
	v_mfma_f32_16x16x32_bf16 v[116:119], v[168:171], v[210:213], v[116:119]
	v_mfma_f32_16x16x32_bf16 v[104:107], v[176:179], v[210:213], v[104:107]
	v_mfma_f32_16x16x32_bf16 v[96:99], v[168:171], v[218:221], v[96:99]
	v_mfma_f32_16x16x32_bf16 v[88:91], v[176:179], v[218:221], v[88:91]
	v_mfma_f32_16x16x32_bf16 v[80:83], v[168:171], v[226:229], v[80:83]
	v_mfma_f32_16x16x32_bf16 v[72:75], v[176:179], v[226:229], v[72:75]
	v_mfma_f32_16x16x32_bf16 v[68:71], v[168:171], v[234:237], v[68:71]
	v_mfma_f32_16x16x32_bf16 v[64:67], v[176:179], v[234:237], v[64:67]
	v_mfma_f32_16x16x32_bf16 v[116:119], v[172:175], v[214:217], v[116:119]
	v_mfma_f32_16x16x32_bf16 v[104:107], v[206:209], v[214:217], v[104:107]
	v_mfma_f32_16x16x32_bf16 v[96:99], v[172:175], v[222:225], v[96:99]
	v_mfma_f32_16x16x32_bf16 v[88:91], v[206:209], v[222:225], v[88:91]
	v_mfma_f32_16x16x32_bf16 v[80:83], v[172:175], v[230:233], v[80:83]
	v_mfma_f32_16x16x32_bf16 v[72:75], v[206:209], v[230:233], v[72:75]
	v_mfma_f32_16x16x32_bf16 v[68:71], v[172:175], v[238:241], v[68:71]
	v_mfma_f32_16x16x32_bf16 v[64:67], v[206:209], v[238:241], v[64:67]
	s_barrier
	s_add_i32 s4, s4, s28
	v_lshl_add_u64 v[180:181], v[180:181], 0, s[26:27]
	s_mov_b32 m0, s4
	ds_read_b128 v[210:213], v205 offset:49152
	ds_read_b128 v[214:217], v205 offset:50176
	ds_read_b128 v[218:221], v205 offset:51200
	ds_read_b128 v[222:225], v205 offset:52224
	ds_read_b128 v[226:229], v205 offset:53248
	ds_read_b128 v[230:233], v205 offset:54272
	ds_read_b128 v[234:237], v205 offset:55296
	ds_read_b128 v[238:241], v205 offset:56320
	global_load_lds_dwordx4 v[180:181], off
	s_add_i32 m0, s4, 0x2000
	s_add_u32 s34, s34, 0x40080
	v_lshl_add_u64 v[180:181], v[242:243], 0, s[26:27]
	s_addc_u32 s35, s35, 0
	s_add_i32 s4, s5, s28
	global_load_lds_dwordx4 v[180:181], off
	v_lshl_add_u64 v[180:181], s[34:35], 0, v[156:157]
	s_mov_b32 m0, s4
	s_nop 0
	global_load_lds_dwordx4 v[180:181], off
	v_lshl_add_u64 v[180:181], s[34:35], 0, v[160:161]
	s_add_i32 m0, s4, 0x2000
	s_nop 0
	global_load_lds_dwordx4 v[180:181], off
	v_lshl_add_u64 v[180:181], v[244:245], 0, s[26:27]
	s_mov_b32 m0, s51
	s_nop 0
	global_load_lds_dwordx4 v[180:181], off
	v_lshl_add_u64 v[180:181], v[246:247], 0, s[26:27]
	s_mov_b32 m0, s64
	s_nop 0
	global_load_lds_dwordx4 v[180:181], off
	s_waitcnt vmcnt(8)
	s_waitcnt lgkmcnt(0)
	s_barrier
	v_mfma_f32_16x16x32_bf16 v[60:63], v[128:131], v[210:213], v[60:63]
	v_mfma_f32_16x16x32_bf16 v[56:59], v[136:139], v[210:213], v[56:59]
	v_mfma_f32_16x16x32_bf16 v[52:55], v[128:131], v[218:221], v[52:55]
	v_mfma_f32_16x16x32_bf16 v[44:47], v[136:139], v[218:221], v[44:47]
	v_mfma_f32_16x16x32_bf16 v[36:39], v[128:131], v[226:229], v[36:39]
	v_mfma_f32_16x16x32_bf16 v[28:31], v[136:139], v[226:229], v[28:31]
	v_mfma_f32_16x16x32_bf16 v[20:23], v[128:131], v[234:237], v[20:23]
	v_mfma_f32_16x16x32_bf16 v[12:15], v[136:139], v[234:237], v[12:15]
	v_mfma_f32_16x16x32_bf16 v[60:63], v[132:135], v[214:217], v[60:63]
	v_mfma_f32_16x16x32_bf16 v[56:59], v[140:143], v[214:217], v[56:59]
	v_mfma_f32_16x16x32_bf16 v[52:55], v[132:135], v[222:225], v[52:55]
	v_mfma_f32_16x16x32_bf16 v[44:47], v[140:143], v[222:225], v[44:47]
	v_mfma_f32_16x16x32_bf16 v[36:39], v[132:135], v[230:233], v[36:39]
	v_mfma_f32_16x16x32_bf16 v[28:31], v[140:143], v[230:233], v[28:31]
	v_mfma_f32_16x16x32_bf16 v[20:23], v[132:135], v[238:241], v[20:23]
	v_mfma_f32_16x16x32_bf16 v[12:15], v[140:143], v[238:241], v[12:15]
	v_mfma_f32_16x16x32_bf16 v[48:51], v[168:171], v[210:213], v[48:51]
	v_mfma_f32_16x16x32_bf16 v[40:43], v[176:179], v[210:213], v[40:43]
	v_mfma_f32_16x16x32_bf16 v[32:35], v[168:171], v[218:221], v[32:35]
	v_mfma_f32_16x16x32_bf16 v[24:27], v[176:179], v[218:221], v[24:27]
	v_mfma_f32_16x16x32_bf16 v[16:19], v[168:171], v[226:229], v[16:19]
	v_mfma_f32_16x16x32_bf16 v[8:11], v[176:179], v[226:229], v[8:11]
	v_mfma_f32_16x16x32_bf16 v[4:7], v[168:171], v[234:237], v[4:7]
	v_mfma_f32_16x16x32_bf16 v[0:3], v[176:179], v[234:237], v[0:3]
	v_mfma_f32_16x16x32_bf16 v[48:51], v[172:175], v[214:217], v[48:51]
	v_mfma_f32_16x16x32_bf16 v[40:43], v[206:209], v[214:217], v[40:43]
	v_mfma_f32_16x16x32_bf16 v[32:35], v[172:175], v[222:225], v[32:35]
	v_mfma_f32_16x16x32_bf16 v[24:27], v[206:209], v[222:225], v[24:27]
	v_mfma_f32_16x16x32_bf16 v[16:19], v[172:175], v[230:233], v[16:19]
	v_mfma_f32_16x16x32_bf16 v[8:11], v[206:209], v[230:233], v[8:11]
	v_mfma_f32_16x16x32_bf16 v[4:7], v[172:175], v[238:241], v[4:7]
	v_mfma_f32_16x16x32_bf16 v[0:3], v[206:209], v[238:241], v[0:3]
	s_barrier
	s_add_i32 s88, s88, 2
	s_add_u32 s0, s0, 0x100
	s_addc_u32 s1, s1, 0
	s_add_u32 s79, s79, 0x100
	s_addc_u32 s84, s84, 0
	s_cmp_gt_u32 s88, 13
	s_cbranch_scc0 .LBB0_605
	s_setprio 0
	s_and_b64 vcc, exec, s[66:67]
	s_cbranch_vccz .LBB0_608
	s_barrier

.Lkprio_1005:
.LBB0_1005:
	s_add_u32 s4, s54, 0xfffe0080
	s_addc_u32 s5, s55, -1
	s_add_i32 s72, 0, 0x10000
	s_cmp_eq_u32 s71, 4
	s_cselect_b32 s59, s29, s5
	s_cselect_b32 s58, s47, s4
	v_add_u32_e32 v138, s72, v141
	s_cselect_b32 s35, s45, s70
	s_cselect_b32 s34, s68, s69
	s_add_i32 s73, 0, 0x14000
	ds_read_b128 v[154:157], v138
	ds_read_b128 v[158:161], v138 offset:1024
	ds_read_b128 v[162:165], v138 offset:2048
	ds_read_b128 v[166:169], v138 offset:3072
	v_add_u32_e32 v138, s73, v141
	ds_read_b128 v[170:173], v138
	ds_read_b128 v[174:177], v138 offset:1024
	ds_read_b128 v[178:181], v138 offset:2048
	ds_read_b128 v[204:207], v138 offset:3072
	v_lshl_add_u64 v[138:139], s[54:55], 0, v[134:135]
	s_add_i32 m0, s53, 0xc000
	ds_read_b128 v[208:211], v143
	ds_read_b128 v[212:215], v143 offset:1024
	ds_read_b128 v[216:219], v143 offset:2048
	ds_read_b128 v[220:223], v143 offset:3072
	ds_read_b128 v[224:227], v143 offset:4096
	ds_read_b128 v[228:231], v143 offset:5120
	ds_read_b128 v[232:235], v143 offset:6144
	ds_read_b128 v[236:239], v143 offset:7168
	global_load_lds_dwordx4 v[138:139], off
	v_lshl_add_u64 v[138:139], s[54:55], 0, v[136:137]
	s_add_i32 m0, s53, 0xe000
	s_nop 0
	global_load_lds_dwordx4 v[138:139], off
	s_waitcnt vmcnt(8)
	s_waitcnt lgkmcnt(0)
	s_barrier
	v_mfma_f32_16x16x32_bf16 v[120:123], v[154:157], v[208:211], v[120:123]
	v_mfma_f32_16x16x32_bf16 v[124:127], v[162:165], v[208:211], v[124:127]
	v_mfma_f32_16x16x32_bf16 v[104:107], v[154:157], v[216:219], v[104:107]
	v_mfma_f32_16x16x32_bf16 v[108:111], v[162:165], v[216:219], v[108:111]
	v_mfma_f32_16x16x32_bf16 v[88:91], v[154:157], v[224:227], v[88:91]
	v_mfma_f32_16x16x32_bf16 v[92:95], v[162:165], v[224:227], v[92:95]
	v_mfma_f32_16x16x32_bf16 v[72:75], v[154:157], v[232:235], v[72:75]
	v_mfma_f32_16x16x32_bf16 v[76:79], v[162:165], v[232:235], v[76:79]
	v_mfma_f32_16x16x32_bf16 v[120:123], v[158:161], v[212:215], v[120:123]
	v_mfma_f32_16x16x32_bf16 v[124:127], v[166:169], v[212:215], v[124:127]
	v_mfma_f32_16x16x32_bf16 v[104:107], v[158:161], v[220:223], v[104:107]
	v_mfma_f32_16x16x32_bf16 v[108:111], v[166:169], v[220:223], v[108:111]
	v_mfma_f32_16x16x32_bf16 v[88:91], v[158:161], v[228:231], v[88:91]
	v_mfma_f32_16x16x32_bf16 v[92:95], v[166:169], v[228:231], v[92:95]
	v_mfma_f32_16x16x32_bf16 v[72:75], v[158:161], v[236:239], v[72:75]
	v_mfma_f32_16x16x32_bf16 v[76:79], v[166:169], v[236:239], v[76:79]
	v_mfma_f32_16x16x32_bf16 v[112:115], v[170:173], v[208:211], v[112:115]
	v_mfma_f32_16x16x32_bf16 v[116:119], v[178:181], v[208:211], v[116:119]
	v_mfma_f32_16x16x32_bf16 v[96:99], v[170:173], v[216:219], v[96:99]
	v_mfma_f32_16x16x32_bf16 v[100:103], v[178:181], v[216:219], v[100:103]
	v_mfma_f32_16x16x32_bf16 v[80:83], v[170:173], v[224:227], v[80:83]
	v_mfma_f32_16x16x32_bf16 v[84:87], v[178:181], v[224:227], v[84:87]
	v_mfma_f32_16x16x32_bf16 v[64:67], v[170:173], v[232:235], v[64:67]
	v_mfma_f32_16x16x32_bf16 v[68:71], v[178:181], v[232:235], v[68:71]
	v_mfma_f32_16x16x32_bf16 v[112:115], v[174:177], v[212:215], v[112:115]
	v_mfma_f32_16x16x32_bf16 v[116:119], v[204:207], v[212:215], v[116:119]
	v_mfma_f32_16x16x32_bf16 v[96:99], v[174:177], v[220:223], v[96:99]
	v_mfma_f32_16x16x32_bf16 v[100:103], v[204:207], v[220:223], v[100:103]
	v_mfma_f32_16x16x32_bf16 v[80:83], v[174:177], v[228:231], v[80:83]
	v_mfma_f32_16x16x32_bf16 v[84:87], v[204:207], v[228:231], v[84:87]
	v_mfma_f32_16x16x32_bf16 v[64:67], v[174:177], v[236:239], v[64:67]
	v_mfma_f32_16x16x32_bf16 v[68:71], v[204:207], v[236:239], v[68:71]
	s_barrier
	s_add_i32 s4, s72, s30
	v_lshl_add_u64 v[138:139], s[34:35], 0, v[144:145]
	s_mov_b32 m0, s4
	ds_read_b128 v[208:211], v143 offset:16384
	ds_read_b128 v[212:215], v143 offset:17408
	ds_read_b128 v[216:219], v143 offset:18432
	ds_read_b128 v[220:223], v143 offset:19456
	ds_read_b128 v[224:227], v143 offset:20480
	ds_read_b128 v[228:231], v143 offset:21504
	ds_read_b128 v[232:235], v143 offset:22528
	ds_read_b128 v[236:239], v143 offset:23552
	global_load_lds_dwordx4 v[138:139], off
	s_add_i32 m0, s4, 0x2000
	s_add_u32 s4, s34, 0x20000
	v_lshl_add_u64 v[202:203], s[34:35], 0, v[132:133]
	s_addc_u32 s5, s35, 0
	s_add_i32 s72, s73, s30
	global_load_lds_dwordx4 v[202:203], off
	v_lshl_add_u64 v[240:241], s[4:5], 0, v[144:145]
	s_mov_b32 m0, s72
	v_lshl_add_u64 v[242:243], s[58:59], 0, v[130:131]
	global_load_lds_dwordx4 v[240:241], off
	v_lshl_add_u64 v[240:241], s[4:5], 0, v[132:133]
	s_add_i32 m0, s72, 0x2000
	s_nop 0
	global_load_lds_dwordx4 v[240:241], off
	v_lshl_add_u64 v[240:241], s[58:59], 0, v[128:129]
	s_mov_b32 m0, s53
	s_nop 0
	global_load_lds_dwordx4 v[240:241], off
	s_mov_b32 m0, s62
	s_nop 0
	global_load_lds_dwordx4 v[242:243], off
	s_waitcnt vmcnt(8)
	s_waitcnt lgkmcnt(0)
	s_barrier
	v_mfma_f32_16x16x32_bf16 v[56:59], v[154:157], v[208:211], v[56:59]
	v_mfma_f32_16x16x32_bf16 v[60:63], v[162:165], v[208:211], v[60:63]
	v_mfma_f32_16x16x32_bf16 v[40:43], v[154:157], v[216:219], v[40:43]
	v_mfma_f32_16x16x32_bf16 v[44:47], v[162:165], v[216:219], v[44:47]
	v_mfma_f32_16x16x32_bf16 v[24:27], v[154:157], v[224:227], v[24:27]
	v_mfma_f32_16x16x32_bf16 v[28:31], v[162:165], v[224:227], v[28:31]
	v_mfma_f32_16x16x32_bf16 v[8:11], v[154:157], v[232:235], v[8:11]
	v_mfma_f32_16x16x32_bf16 v[12:15], v[162:165], v[232:235], v[12:15]
	v_mfma_f32_16x16x32_bf16 v[56:59], v[158:161], v[212:215], v[56:59]
	v_mfma_f32_16x16x32_bf16 v[60:63], v[166:169], v[212:215], v[60:63]
	v_mfma_f32_16x16x32_bf16 v[40:43], v[158:161], v[220:223], v[40:43]
	v_mfma_f32_16x16x32_bf16 v[44:47], v[166:169], v[220:223], v[44:47]
	v_mfma_f32_16x16x32_bf16 v[24:27], v[158:161], v[228:231], v[24:27]
	v_mfma_f32_16x16x32_bf16 v[28:31], v[166:169], v[228:231], v[28:31]
	v_mfma_f32_16x16x32_bf16 v[8:11], v[158:161], v[236:239], v[8:11]
	v_mfma_f32_16x16x32_bf16 v[12:15], v[166:169], v[236:239], v[12:15]
	v_mfma_f32_16x16x32_bf16 v[48:51], v[170:173], v[208:211], v[48:51]
	v_mfma_f32_16x16x32_bf16 v[52:55], v[178:181], v[208:211], v[52:55]
	v_mfma_f32_16x16x32_bf16 v[32:35], v[170:173], v[216:219], v[32:35]
	v_mfma_f32_16x16x32_bf16 v[36:39], v[178:181], v[216:219], v[36:39]
	v_mfma_f32_16x16x32_bf16 v[16:19], v[170:173], v[224:227], v[16:19]
	v_mfma_f32_16x16x32_bf16 v[20:23], v[178:181], v[224:227], v[20:23]
	v_mfma_f32_16x16x32_bf16 v[0:3], v[170:173], v[232:235], v[0:3]
	v_mfma_f32_16x16x32_bf16 v[4:7], v[178:181], v[232:235], v[4:7]
	v_mfma_f32_16x16x32_bf16 v[48:51], v[174:177], v[212:215], v[48:51]
	v_mfma_f32_16x16x32_bf16 v[52:55], v[204:207], v[212:215], v[52:55]
	v_mfma_f32_16x16x32_bf16 v[32:35], v[174:177], v[220:223], v[32:35]
	v_mfma_f32_16x16x32_bf16 v[36:39], v[204:207], v[220:223], v[36:39]
	v_mfma_f32_16x16x32_bf16 v[16:19], v[174:177], v[228:231], v[16:19]
	v_mfma_f32_16x16x32_bf16 v[20:23], v[204:207], v[228:231], v[20:23]
	v_mfma_f32_16x16x32_bf16 v[0:3], v[174:177], v[236:239], v[0:3]
	v_mfma_f32_16x16x32_bf16 v[4:7], v[204:207], v[236:239], v[4:7]
	s_barrier
	s_add_i32 s72, 0, 0x18000
	s_add_i32 s73, 0, 0x1c000
	v_add_u32_e32 v166, s72, v141
	v_add_u32_e32 v204, s73, v141
	ds_read_b128 v[154:157], v166
	ds_read_b128 v[158:161], v166 offset:1024
	ds_read_b128 v[162:165], v166 offset:2048
	ds_read_b128 v[166:169], v166 offset:3072
	ds_read_b128 v[170:173], v204
	ds_read_b128 v[174:177], v204 offset:1024
	ds_read_b128 v[178:181], v204 offset:2048
	ds_read_b128 v[204:207], v204 offset:3072
	s_add_u32 s4, s58, 0x20000
	s_addc_u32 s5, s59, 0
	s_mov_b32 m0, s63
	v_lshl_add_u64 v[244:245], s[4:5], 0, v[128:129]
	ds_read_b128 v[208:211], v143 offset:32768
	ds_read_b128 v[212:215], v143 offset:33792
	ds_read_b128 v[216:219], v143 offset:34816
	ds_read_b128 v[220:223], v143 offset:35840
	ds_read_b128 v[224:227], v143 offset:36864
	ds_read_b128 v[228:231], v143 offset:37888
	ds_read_b128 v[232:235], v143 offset:38912
	ds_read_b128 v[236:239], v143 offset:39936
	global_load_lds_dwordx4 v[244:245], off
	v_lshl_add_u64 v[244:245], s[4:5], 0, v[130:131]
	s_mov_b32 m0, s64
	s_nop 0
	global_load_lds_dwordx4 v[244:245], off
	s_waitcnt vmcnt(8)
	s_waitcnt lgkmcnt(0)
	s_barrier
	v_mfma_f32_16x16x32_bf16 v[120:123], v[154:157], v[208:211], v[120:123]
	v_mfma_f32_16x16x32_bf16 v[124:127], v[162:165], v[208:211], v[124:127]
	v_mfma_f32_16x16x32_bf16 v[104:107], v[154:157], v[216:219], v[104:107]
	v_mfma_f32_16x16x32_bf16 v[108:111], v[162:165], v[216:219], v[108:111]
	v_mfma_f32_16x16x32_bf16 v[88:91], v[154:157], v[224:227], v[88:91]
	v_mfma_f32_16x16x32_bf16 v[92:95], v[162:165], v[224:227], v[92:95]
	v_mfma_f32_16x16x32_bf16 v[72:75], v[154:157], v[232:235], v[72:75]
	v_mfma_f32_16x16x32_bf16 v[76:79], v[162:165], v[232:235], v[76:79]
	v_mfma_f32_16x16x32_bf16 v[120:123], v[158:161], v[212:215], v[120:123]
	v_mfma_f32_16x16x32_bf16 v[124:127], v[166:169], v[212:215], v[124:127]
	v_mfma_f32_16x16x32_bf16 v[104:107], v[158:161], v[220:223], v[104:107]
	v_mfma_f32_16x16x32_bf16 v[108:111], v[166:169], v[220:223], v[108:111]
	v_mfma_f32_16x16x32_bf16 v[88:91], v[158:161], v[228:231], v[88:91]
	v_mfma_f32_16x16x32_bf16 v[92:95], v[166:169], v[228:231], v[92:95]
	v_mfma_f32_16x16x32_bf16 v[72:75], v[158:161], v[236:239], v[72:75]
	v_mfma_f32_16x16x32_bf16 v[76:79], v[166:169], v[236:239], v[76:79]
	v_mfma_f32_16x16x32_bf16 v[112:115], v[170:173], v[208:211], v[112:115]
	v_mfma_f32_16x16x32_bf16 v[116:119], v[178:181], v[208:211], v[116:119]
	v_mfma_f32_16x16x32_bf16 v[96:99], v[170:173], v[216:219], v[96:99]
	v_mfma_f32_16x16x32_bf16 v[100:103], v[178:181], v[216:219], v[100:103]
	v_mfma_f32_16x16x32_bf16 v[80:83], v[170:173], v[224:227], v[80:83]
	v_mfma_f32_16x16x32_bf16 v[84:87], v[178:181], v[224:227], v[84:87]
	v_mfma_f32_16x16x32_bf16 v[64:67], v[170:173], v[232:235], v[64:67]
	v_mfma_f32_16x16x32_bf16 v[68:71], v[178:181], v[232:235], v[68:71]
	v_mfma_f32_16x16x32_bf16 v[112:115], v[174:177], v[212:215], v[112:115]
	v_mfma_f32_16x16x32_bf16 v[116:119], v[204:207], v[212:215], v[116:119]
	v_mfma_f32_16x16x32_bf16 v[96:99], v[174:177], v[220:223], v[96:99]
	v_mfma_f32_16x16x32_bf16 v[100:103], v[204:207], v[220:223], v[100:103]
	v_mfma_f32_16x16x32_bf16 v[80:83], v[174:177], v[228:231], v[80:83]
	v_mfma_f32_16x16x32_bf16 v[84:87], v[204:207], v[228:231], v[84:87]
	v_mfma_f32_16x16x32_bf16 v[64:67], v[174:177], v[236:239], v[64:67]
	v_mfma_f32_16x16x32_bf16 v[68:71], v[204:207], v[236:239], v[68:71]
	s_barrier
	s_add_i32 s4, s72, s30
	v_lshl_add_u64 v[138:139], v[138:139], 0, s[26:27]
	s_mov_b32 m0, s4
	ds_read_b128 v[208:211], v143 offset:49152
	ds_read_b128 v[212:215], v143 offset:50176
	ds_read_b128 v[216:219], v143 offset:51200
	ds_read_b128 v[220:223], v143 offset:52224
	ds_read_b128 v[224:227], v143 offset:53248
	ds_read_b128 v[228:231], v143 offset:54272
	ds_read_b128 v[232:235], v143 offset:55296
	ds_read_b128 v[236:239], v143 offset:56320
	global_load_lds_dwordx4 v[138:139], off
	s_add_i32 m0, s4, 0x2000
	s_add_u32 s4, s34, 0x20080
	v_lshl_add_u64 v[138:139], v[202:203], 0, s[26:27]
	s_addc_u32 s5, s35, 0
	s_add_i32 s34, s73, s30
	global_load_lds_dwordx4 v[138:139], off
	v_lshl_add_u64 v[138:139], s[4:5], 0, v[144:145]
	s_mov_b32 m0, s34
	s_nop 0
	global_load_lds_dwordx4 v[138:139], off
	v_lshl_add_u64 v[138:139], s[4:5], 0, v[132:133]
	s_add_i32 m0, s34, 0x2000
	s_nop 0
	global_load_lds_dwordx4 v[138:139], off
	v_lshl_add_u64 v[138:139], v[240:241], 0, s[26:27]
	s_mov_b32 m0, s65
	s_nop 0
	global_load_lds_dwordx4 v[138:139], off
	v_lshl_add_u64 v[138:139], v[242:243], 0, s[26:27]
	s_mov_b32 m0, s66
	s_nop 0
	global_load_lds_dwordx4 v[138:139], off
	s_waitcnt vmcnt(8)
	s_waitcnt lgkmcnt(0)
	s_barrier
	v_mfma_f32_16x16x32_bf16 v[56:59], v[154:157], v[208:211], v[56:59]
	v_mfma_f32_16x16x32_bf16 v[60:63], v[162:165], v[208:211], v[60:63]
	v_mfma_f32_16x16x32_bf16 v[40:43], v[154:157], v[216:219], v[40:43]
	v_mfma_f32_16x16x32_bf16 v[44:47], v[162:165], v[216:219], v[44:47]
	v_mfma_f32_16x16x32_bf16 v[24:27], v[154:157], v[224:227], v[24:27]
	v_mfma_f32_16x16x32_bf16 v[28:31], v[162:165], v[224:227], v[28:31]
	v_mfma_f32_16x16x32_bf16 v[8:11], v[154:157], v[232:235], v[8:11]
	v_mfma_f32_16x16x32_bf16 v[12:15], v[162:165], v[232:235], v[12:15]
	v_mfma_f32_16x16x32_bf16 v[56:59], v[158:161], v[212:215], v[56:59]
	v_mfma_f32_16x16x32_bf16 v[60:63], v[166:169], v[212:215], v[60:63]
	v_mfma_f32_16x16x32_bf16 v[40:43], v[158:161], v[220:223], v[40:43]
	v_mfma_f32_16x16x32_bf16 v[44:47], v[166:169], v[220:223], v[44:47]
	v_mfma_f32_16x16x32_bf16 v[24:27], v[158:161], v[228:231], v[24:27]
	v_mfma_f32_16x16x32_bf16 v[28:31], v[166:169], v[228:231], v[28:31]
	v_mfma_f32_16x16x32_bf16 v[8:11], v[158:161], v[236:239], v[8:11]
	v_mfma_f32_16x16x32_bf16 v[12:15], v[166:169], v[236:239], v[12:15]
	v_mfma_f32_16x16x32_bf16 v[48:51], v[170:173], v[208:211], v[48:51]
	v_mfma_f32_16x16x32_bf16 v[52:55], v[178:181], v[208:211], v[52:55]
	v_mfma_f32_16x16x32_bf16 v[32:35], v[170:173], v[216:219], v[32:35]
	v_mfma_f32_16x16x32_bf16 v[36:39], v[178:181], v[216:219], v[36:39]
	v_mfma_f32_16x16x32_bf16 v[16:19], v[170:173], v[224:227], v[16:19]
	v_mfma_f32_16x16x32_bf16 v[20:23], v[178:181], v[224:227], v[20:23]
	v_mfma_f32_16x16x32_bf16 v[0:3], v[170:173], v[232:235], v[0:3]
	v_mfma_f32_16x16x32_bf16 v[4:7], v[178:181], v[232:235], v[4:7]
	v_mfma_f32_16x16x32_bf16 v[48:51], v[174:177], v[212:215], v[48:51]
	v_mfma_f32_16x16x32_bf16 v[52:55], v[204:207], v[212:215], v[52:55]
	v_mfma_f32_16x16x32_bf16 v[32:35], v[174:177], v[220:223], v[32:35]
	v_mfma_f32_16x16x32_bf16 v[36:39], v[204:207], v[220:223], v[36:39]
	v_mfma_f32_16x16x32_bf16 v[16:19], v[174:177], v[228:231], v[16:19]
	v_mfma_f32_16x16x32_bf16 v[20:23], v[204:207], v[228:231], v[20:23]
	v_mfma_f32_16x16x32_bf16 v[0:3], v[174:177], v[236:239], v[0:3]
	v_mfma_f32_16x16x32_bf16 v[4:7], v[204:207], v[236:239], v[4:7]
	s_barrier
	s_add_i32 s71, s71, 2
	s_add_u32 s54, s54, 0x100
	s_addc_u32 s55, s55, 0
	s_add_u32 s69, s69, 0x100
	s_addc_u32 s70, s70, 0
	s_cmp_gt_u32 s71, 5
	s_cbranch_scc0 .LBB0_1005
	s_setprio 0
	v_readlane_b32 s68, v255, 7
	s_and_b64 vcc, exec, s[42:43]
	v_readlane_b32 s69, v255, 8
	s_cbranch_vccz .LBB0_1008
	s_barrier

.Lkprio_1093:
.LBB0_1093:
	s_add_u32 s4, s58, 0xfffe0080
	s_addc_u32 s5, s59, -1
	s_add_i32 s74, 0, 0x10000
	s_cmp_eq_u32 s73, 4
	s_cselect_b32 s61, s33, s5
	s_cselect_b32 s60, s36, s4
	s_cselect_b32 s35, s49, s72
	s_cselect_b32 s34, s51, s71
	s_add_i32 s75, 0, 0x14000
	v_add_u32_e32 v164, s74, v143
	v_add_u32_e32 v180, s75, v143
	ds_read_b128 v[138:141], v164
	ds_read_b128 v[156:159], v164 offset:1024
	ds_read_b128 v[160:163], v164 offset:2048
	ds_read_b128 v[164:167], v164 offset:3072
	ds_read_b128 v[168:171], v180
	ds_read_b128 v[172:175], v180 offset:1024
	ds_read_b128 v[176:179], v180 offset:2048
	ds_read_b128 v[204:207], v180 offset:3072
	v_lshl_add_u64 v[180:181], s[58:59], 0, v[134:135]
	s_add_i32 m0, s64, 0xc000
	ds_read_b128 v[208:211], v155
	ds_read_b128 v[212:215], v155 offset:1024
	ds_read_b128 v[216:219], v155 offset:2048
	ds_read_b128 v[220:223], v155 offset:3072
	ds_read_b128 v[224:227], v155 offset:4096
	ds_read_b128 v[228:231], v155 offset:5120
	ds_read_b128 v[232:235], v155 offset:6144
	ds_read_b128 v[236:239], v155 offset:7168
	global_load_lds_dwordx4 v[180:181], off
	v_lshl_add_u64 v[180:181], s[58:59], 0, v[136:137]
	s_add_i32 m0, s64, 0xe000
	s_nop 0
	global_load_lds_dwordx4 v[180:181], off
	s_waitcnt vmcnt(8)
	s_waitcnt lgkmcnt(0)
	s_barrier
	v_mfma_f32_16x16x32_bf16 v[124:127], v[138:141], v[208:211], v[124:127]
	v_mfma_f32_16x16x32_bf16 v[120:123], v[160:163], v[208:211], v[120:123]
	v_mfma_f32_16x16x32_bf16 v[108:111], v[138:141], v[216:219], v[108:111]
	v_mfma_f32_16x16x32_bf16 v[104:107], v[160:163], v[216:219], v[104:107]
	v_mfma_f32_16x16x32_bf16 v[92:95], v[138:141], v[224:227], v[92:95]
	v_mfma_f32_16x16x32_bf16 v[88:91], v[160:163], v[224:227], v[88:91]
	v_mfma_f32_16x16x32_bf16 v[76:79], v[138:141], v[232:235], v[76:79]
	v_mfma_f32_16x16x32_bf16 v[72:75], v[160:163], v[232:235], v[72:75]
	v_mfma_f32_16x16x32_bf16 v[124:127], v[156:159], v[212:215], v[124:127]
	v_mfma_f32_16x16x32_bf16 v[120:123], v[164:167], v[212:215], v[120:123]
	v_mfma_f32_16x16x32_bf16 v[108:111], v[156:159], v[220:223], v[108:111]
	v_mfma_f32_16x16x32_bf16 v[104:107], v[164:167], v[220:223], v[104:107]
	v_mfma_f32_16x16x32_bf16 v[92:95], v[156:159], v[228:231], v[92:95]
	v_mfma_f32_16x16x32_bf16 v[88:91], v[164:167], v[228:231], v[88:91]
	v_mfma_f32_16x16x32_bf16 v[76:79], v[156:159], v[236:239], v[76:79]
	v_mfma_f32_16x16x32_bf16 v[72:75], v[164:167], v[236:239], v[72:75]
	v_mfma_f32_16x16x32_bf16 v[116:119], v[168:171], v[208:211], v[116:119]
	v_mfma_f32_16x16x32_bf16 v[112:115], v[176:179], v[208:211], v[112:115]
	v_mfma_f32_16x16x32_bf16 v[100:103], v[168:171], v[216:219], v[100:103]
	v_mfma_f32_16x16x32_bf16 v[96:99], v[176:179], v[216:219], v[96:99]
	v_mfma_f32_16x16x32_bf16 v[84:87], v[168:171], v[224:227], v[84:87]
	v_mfma_f32_16x16x32_bf16 v[80:83], v[176:179], v[224:227], v[80:83]
	v_mfma_f32_16x16x32_bf16 v[68:71], v[168:171], v[232:235], v[68:71]
	v_mfma_f32_16x16x32_bf16 v[64:67], v[176:179], v[232:235], v[64:67]
	v_mfma_f32_16x16x32_bf16 v[116:119], v[172:175], v[212:215], v[116:119]
	v_mfma_f32_16x16x32_bf16 v[112:115], v[204:207], v[212:215], v[112:115]
	v_mfma_f32_16x16x32_bf16 v[100:103], v[172:175], v[220:223], v[100:103]
	v_mfma_f32_16x16x32_bf16 v[96:99], v[204:207], v[220:223], v[96:99]
	v_mfma_f32_16x16x32_bf16 v[84:87], v[172:175], v[228:231], v[84:87]
	v_mfma_f32_16x16x32_bf16 v[80:83], v[204:207], v[228:231], v[80:83]
	v_mfma_f32_16x16x32_bf16 v[68:71], v[172:175], v[236:239], v[68:71]
	v_mfma_f32_16x16x32_bf16 v[64:67], v[204:207], v[236:239], v[64:67]
	s_barrier
	s_add_i32 s4, s74, s28
	v_lshl_add_u64 v[180:181], s[34:35], 0, v[144:145]
	s_mov_b32 m0, s4
	ds_read_b128 v[208:211], v155 offset:16384
	ds_read_b128 v[212:215], v155 offset:17408
	ds_read_b128 v[216:219], v155 offset:18432
	ds_read_b128 v[220:223], v155 offset:19456
	ds_read_b128 v[224:227], v155 offset:20480
	ds_read_b128 v[228:231], v155 offset:21504
	ds_read_b128 v[232:235], v155 offset:22528
	ds_read_b128 v[236:239], v155 offset:23552
	global_load_lds_dwordx4 v[180:181], off
	s_add_i32 m0, s4, 0x2000
	s_add_u32 s4, s34, 0x20000
	v_lshl_add_u64 v[202:203], s[34:35], 0, v[132:133]
	s_addc_u32 s5, s35, 0
	s_add_i32 s74, s75, s28
	global_load_lds_dwordx4 v[202:203], off
	v_lshl_add_u64 v[240:241], s[4:5], 0, v[144:145]
	s_mov_b32 m0, s74
	v_lshl_add_u64 v[242:243], s[60:61], 0, v[130:131]
	global_load_lds_dwordx4 v[240:241], off
	v_lshl_add_u64 v[240:241], s[4:5], 0, v[132:133]
	s_add_i32 m0, s74, 0x2000
	s_nop 0
	global_load_lds_dwordx4 v[240:241], off
	v_lshl_add_u64 v[240:241], s[60:61], 0, v[128:129]
	s_mov_b32 m0, s64
	s_nop 0
	global_load_lds_dwordx4 v[240:241], off
	s_mov_b32 m0, s65
	s_nop 0
	global_load_lds_dwordx4 v[242:243], off
	s_waitcnt vmcnt(8)
	s_waitcnt lgkmcnt(0)
	s_barrier
	v_mfma_f32_16x16x32_bf16 v[60:63], v[138:141], v[208:211], v[60:63]
	v_mfma_f32_16x16x32_bf16 v[56:59], v[160:163], v[208:211], v[56:59]
	v_mfma_f32_16x16x32_bf16 v[44:47], v[138:141], v[216:219], v[44:47]
	v_mfma_f32_16x16x32_bf16 v[40:43], v[160:163], v[216:219], v[40:43]
	v_mfma_f32_16x16x32_bf16 v[28:31], v[138:141], v[224:227], v[28:31]
	v_mfma_f32_16x16x32_bf16 v[24:27], v[160:163], v[224:227], v[24:27]
	v_mfma_f32_16x16x32_bf16 v[12:15], v[138:141], v[232:235], v[12:15]
	v_mfma_f32_16x16x32_bf16 v[8:11], v[160:163], v[232:235], v[8:11]
	v_mfma_f32_16x16x32_bf16 v[60:63], v[156:159], v[212:215], v[60:63]
	v_mfma_f32_16x16x32_bf16 v[56:59], v[164:167], v[212:215], v[56:59]
	v_mfma_f32_16x16x32_bf16 v[44:47], v[156:159], v[220:223], v[44:47]
	v_mfma_f32_16x16x32_bf16 v[40:43], v[164:167], v[220:223], v[40:43]
	v_mfma_f32_16x16x32_bf16 v[28:31], v[156:159], v[228:231], v[28:31]
	v_mfma_f32_16x16x32_bf16 v[24:27], v[164:167], v[228:231], v[24:27]
	v_mfma_f32_16x16x32_bf16 v[12:15], v[156:159], v[236:239], v[12:15]
	v_mfma_f32_16x16x32_bf16 v[8:11], v[164:167], v[236:239], v[8:11]
	v_mfma_f32_16x16x32_bf16 v[52:55], v[168:171], v[208:211], v[52:55]
	v_mfma_f32_16x16x32_bf16 v[48:51], v[176:179], v[208:211], v[48:51]
	v_mfma_f32_16x16x32_bf16 v[36:39], v[168:171], v[216:219], v[36:39]
	v_mfma_f32_16x16x32_bf16 v[32:35], v[176:179], v[216:219], v[32:35]
	v_mfma_f32_16x16x32_bf16 v[20:23], v[168:171], v[224:227], v[20:23]
	v_mfma_f32_16x16x32_bf16 v[16:19], v[176:179], v[224:227], v[16:19]
	v_mfma_f32_16x16x32_bf16 v[4:7], v[168:171], v[232:235], v[4:7]
	v_mfma_f32_16x16x32_bf16 v[0:3], v[176:179], v[232:235], v[0:3]
	v_mfma_f32_16x16x32_bf16 v[52:55], v[172:175], v[212:215], v[52:55]
	v_mfma_f32_16x16x32_bf16 v[48:51], v[204:207], v[212:215], v[48:51]
	v_mfma_f32_16x16x32_bf16 v[36:39], v[172:175], v[220:223], v[36:39]
	v_mfma_f32_16x16x32_bf16 v[32:35], v[204:207], v[220:223], v[32:35]
	v_mfma_f32_16x16x32_bf16 v[20:23], v[172:175], v[228:231], v[20:23]
	v_mfma_f32_16x16x32_bf16 v[16:19], v[204:207], v[228:231], v[16:19]
	v_mfma_f32_16x16x32_bf16 v[4:7], v[172:175], v[236:239], v[4:7]
	v_mfma_f32_16x16x32_bf16 v[0:3], v[204:207], v[236:239], v[0:3]
	s_barrier
	s_add_i32 s74, 0, 0x18000
	s_add_i32 s75, 0, 0x1c000
	v_add_u32_e32 v164, s74, v143
	v_add_u32_e32 v204, s75, v143
	ds_read_b128 v[138:141], v164
	ds_read_b128 v[156:159], v164 offset:1024
	ds_read_b128 v[160:163], v164 offset:2048
	ds_read_b128 v[164:167], v164 offset:3072
	ds_read_b128 v[168:171], v204
	ds_read_b128 v[172:175], v204 offset:1024
	ds_read_b128 v[176:179], v204 offset:2048
	ds_read_b128 v[204:207], v204 offset:3072
	s_add_u32 s4, s60, 0x20000
	s_addc_u32 s5, s61, 0
	s_mov_b32 m0, s66
	v_lshl_add_u64 v[244:245], s[4:5], 0, v[128:129]
	ds_read_b128 v[208:211], v155 offset:32768
	ds_read_b128 v[212:215], v155 offset:33792
	ds_read_b128 v[216:219], v155 offset:34816
	ds_read_b128 v[220:223], v155 offset:35840
	ds_read_b128 v[224:227], v155 offset:36864
	ds_read_b128 v[228:231], v155 offset:37888
	ds_read_b128 v[232:235], v155 offset:38912
	ds_read_b128 v[236:239], v155 offset:39936
	global_load_lds_dwordx4 v[244:245], off
	v_lshl_add_u64 v[244:245], s[4:5], 0, v[130:131]
	s_mov_b32 m0, s67
	s_nop 0
	global_load_lds_dwordx4 v[244:245], off
	s_waitcnt vmcnt(8)
	s_waitcnt lgkmcnt(0)
	s_barrier
	v_mfma_f32_16x16x32_bf16 v[124:127], v[138:141], v[208:211], v[124:127]
	v_mfma_f32_16x16x32_bf16 v[120:123], v[160:163], v[208:211], v[120:123]
	v_mfma_f32_16x16x32_bf16 v[108:111], v[138:141], v[216:219], v[108:111]
	v_mfma_f32_16x16x32_bf16 v[104:107], v[160:163], v[216:219], v[104:107]
	v_mfma_f32_16x16x32_bf16 v[92:95], v[138:141], v[224:227], v[92:95]
	v_mfma_f32_16x16x32_bf16 v[88:91], v[160:163], v[224:227], v[88:91]
	v_mfma_f32_16x16x32_bf16 v[76:79], v[138:141], v[232:235], v[76:79]
	v_mfma_f32_16x16x32_bf16 v[72:75], v[160:163], v[232:235], v[72:75]
	v_mfma_f32_16x16x32_bf16 v[124:127], v[156:159], v[212:215], v[124:127]
	v_mfma_f32_16x16x32_bf16 v[120:123], v[164:167], v[212:215], v[120:123]
	v_mfma_f32_16x16x32_bf16 v[108:111], v[156:159], v[220:223], v[108:111]
	v_mfma_f32_16x16x32_bf16 v[104:107], v[164:167], v[220:223], v[104:107]
	v_mfma_f32_16x16x32_bf16 v[92:95], v[156:159], v[228:231], v[92:95]
	v_mfma_f32_16x16x32_bf16 v[88:91], v[164:167], v[228:231], v[88:91]
	v_mfma_f32_16x16x32_bf16 v[76:79], v[156:159], v[236:239], v[76:79]
	v_mfma_f32_16x16x32_bf16 v[72:75], v[164:167], v[236:239], v[72:75]
	v_mfma_f32_16x16x32_bf16 v[116:119], v[168:171], v[208:211], v[116:119]
	v_mfma_f32_16x16x32_bf16 v[112:115], v[176:179], v[208:211], v[112:115]
	v_mfma_f32_16x16x32_bf16 v[100:103], v[168:171], v[216:219], v[100:103]
	v_mfma_f32_16x16x32_bf16 v[96:99], v[176:179], v[216:219], v[96:99]
	v_mfma_f32_16x16x32_bf16 v[84:87], v[168:171], v[224:227], v[84:87]
	v_mfma_f32_16x16x32_bf16 v[80:83], v[176:179], v[224:227], v[80:83]
	v_mfma_f32_16x16x32_bf16 v[68:71], v[168:171], v[232:235], v[68:71]
	v_mfma_f32_16x16x32_bf16 v[64:67], v[176:179], v[232:235], v[64:67]
	v_mfma_f32_16x16x32_bf16 v[116:119], v[172:175], v[212:215], v[116:119]
	v_mfma_f32_16x16x32_bf16 v[112:115], v[204:207], v[212:215], v[112:115]
	v_mfma_f32_16x16x32_bf16 v[100:103], v[172:175], v[220:223], v[100:103]
	v_mfma_f32_16x16x32_bf16 v[96:99], v[204:207], v[220:223], v[96:99]
	v_mfma_f32_16x16x32_bf16 v[84:87], v[172:175], v[228:231], v[84:87]
	v_mfma_f32_16x16x32_bf16 v[80:83], v[204:207], v[228:231], v[80:83]
	v_mfma_f32_16x16x32_bf16 v[68:71], v[172:175], v[236:239], v[68:71]
	v_mfma_f32_16x16x32_bf16 v[64:67], v[204:207], v[236:239], v[64:67]
	s_barrier
	s_add_i32 s4, s74, s28
	v_lshl_add_u64 v[180:181], v[180:181], 0, s[26:27]
	s_mov_b32 m0, s4
	ds_read_b128 v[208:211], v155 offset:49152
	ds_read_b128 v[212:215], v155 offset:50176
	ds_read_b128 v[216:219], v155 offset:51200
	ds_read_b128 v[220:223], v155 offset:52224
	ds_read_b128 v[224:227], v155 offset:53248
	ds_read_b128 v[228:231], v155 offset:54272
	ds_read_b128 v[232:235], v155 offset:55296
	ds_read_b128 v[236:239], v155 offset:56320
	global_load_lds_dwordx4 v[180:181], off
	s_add_i32 m0, s4, 0x2000
	s_add_u32 s4, s34, 0x20080
	v_lshl_add_u64 v[180:181], v[202:203], 0, s[26:27]
	s_addc_u32 s5, s35, 0
	s_add_i32 s34, s75, s28
	global_load_lds_dwordx4 v[180:181], off
	v_lshl_add_u64 v[180:181], s[4:5], 0, v[144:145]
	s_mov_b32 m0, s34
	s_nop 0
	global_load_lds_dwordx4 v[180:181], off
	v_lshl_add_u64 v[180:181], s[4:5], 0, v[132:133]
	s_add_i32 m0, s34, 0x2000
	s_nop 0
	global_load_lds_dwordx4 v[180:181], off
	v_lshl_add_u64 v[180:181], v[240:241], 0, s[26:27]
	s_mov_b32 m0, s68
	s_nop 0
	global_load_lds_dwordx4 v[180:181], off
	v_lshl_add_u64 v[180:181], v[242:243], 0, s[26:27]
	s_mov_b32 m0, s69
	s_nop 0
	global_load_lds_dwordx4 v[180:181], off
	s_waitcnt vmcnt(8)
	s_waitcnt lgkmcnt(0)
	s_barrier
	v_mfma_f32_16x16x32_bf16 v[60:63], v[138:141], v[208:211], v[60:63]
	v_mfma_f32_16x16x32_bf16 v[56:59], v[160:163], v[208:211], v[56:59]
	v_mfma_f32_16x16x32_bf16 v[44:47], v[138:141], v[216:219], v[44:47]
	v_mfma_f32_16x16x32_bf16 v[40:43], v[160:163], v[216:219], v[40:43]
	v_mfma_f32_16x16x32_bf16 v[28:31], v[138:141], v[224:227], v[28:31]
	v_mfma_f32_16x16x32_bf16 v[24:27], v[160:163], v[224:227], v[24:27]
	v_mfma_f32_16x16x32_bf16 v[12:15], v[138:141], v[232:235], v[12:15]
	v_mfma_f32_16x16x32_bf16 v[8:11], v[160:163], v[232:235], v[8:11]
	v_mfma_f32_16x16x32_bf16 v[60:63], v[156:159], v[212:215], v[60:63]
	v_mfma_f32_16x16x32_bf16 v[56:59], v[164:167], v[212:215], v[56:59]
	v_mfma_f32_16x16x32_bf16 v[44:47], v[156:159], v[220:223], v[44:47]
	v_mfma_f32_16x16x32_bf16 v[40:43], v[164:167], v[220:223], v[40:43]
	v_mfma_f32_16x16x32_bf16 v[28:31], v[156:159], v[228:231], v[28:31]
	v_mfma_f32_16x16x32_bf16 v[24:27], v[164:167], v[228:231], v[24:27]
	v_mfma_f32_16x16x32_bf16 v[12:15], v[156:159], v[236:239], v[12:15]
	v_mfma_f32_16x16x32_bf16 v[8:11], v[164:167], v[236:239], v[8:11]
	v_mfma_f32_16x16x32_bf16 v[52:55], v[168:171], v[208:211], v[52:55]
	v_mfma_f32_16x16x32_bf16 v[48:51], v[176:179], v[208:211], v[48:51]
	v_mfma_f32_16x16x32_bf16 v[36:39], v[168:171], v[216:219], v[36:39]
	v_mfma_f32_16x16x32_bf16 v[32:35], v[176:179], v[216:219], v[32:35]
	v_mfma_f32_16x16x32_bf16 v[20:23], v[168:171], v[224:227], v[20:23]
	v_mfma_f32_16x16x32_bf16 v[16:19], v[176:179], v[224:227], v[16:19]
	v_mfma_f32_16x16x32_bf16 v[4:7], v[168:171], v[232:235], v[4:7]
	v_mfma_f32_16x16x32_bf16 v[0:3], v[176:179], v[232:235], v[0:3]
	v_mfma_f32_16x16x32_bf16 v[52:55], v[172:175], v[212:215], v[52:55]
	v_mfma_f32_16x16x32_bf16 v[48:51], v[204:207], v[212:215], v[48:51]
	v_mfma_f32_16x16x32_bf16 v[36:39], v[172:175], v[220:223], v[36:39]
	v_mfma_f32_16x16x32_bf16 v[32:35], v[204:207], v[220:223], v[32:35]
	v_mfma_f32_16x16x32_bf16 v[20:23], v[172:175], v[228:231], v[20:23]
	v_mfma_f32_16x16x32_bf16 v[16:19], v[204:207], v[228:231], v[16:19]
	v_mfma_f32_16x16x32_bf16 v[4:7], v[172:175], v[236:239], v[4:7]
	v_mfma_f32_16x16x32_bf16 v[0:3], v[204:207], v[236:239], v[0:3]
	s_barrier
	s_add_i32 s73, s73, 2
	s_add_u32 s58, s58, 0x100
	s_addc_u32 s59, s59, 0
	s_add_u32 s71, s71, 0x100
	s_addc_u32 s72, s72, 0
	s_cmp_gt_u32 s73, 5
	s_cbranch_scc0 .LBB0_1093
	s_setprio 0
	s_and_b64 vcc, exec, s[46:47]
	s_cbranch_vccz .LBB0_1096
	s_barrier

.Lkprio_1117:
.LBB0_1117:
	s_add_u32 s4, s54, 0xfffe0080
	s_addc_u32 s5, s55, -1
	s_add_i32 s74, 0, 0x10000
	s_cmp_eq_u32 s73, 4
	s_cselect_b32 s59, s33, s5
	s_cselect_b32 s58, s36, s4
	s_cselect_b32 s35, s47, s72
	s_cselect_b32 s34, s49, s71
	s_add_i32 s75, 0, 0x14000
	v_add_u32_e32 v164, s74, v143
	v_add_u32_e32 v180, s75, v143
	ds_read_b128 v[138:141], v164
	ds_read_b128 v[156:159], v164 offset:1024
	ds_read_b128 v[160:163], v164 offset:2048
	ds_read_b128 v[164:167], v164 offset:3072
	ds_read_b128 v[168:171], v180
	ds_read_b128 v[172:175], v180 offset:1024
	ds_read_b128 v[176:179], v180 offset:2048
	ds_read_b128 v[204:207], v180 offset:3072
	v_lshl_add_u64 v[180:181], s[54:55], 0, v[134:135]
	s_add_i32 m0, s64, 0xc000
	ds_read_b128 v[208:211], v155
	ds_read_b128 v[212:215], v155 offset:1024
	ds_read_b128 v[216:219], v155 offset:2048
	ds_read_b128 v[220:223], v155 offset:3072
	ds_read_b128 v[224:227], v155 offset:4096
	ds_read_b128 v[228:231], v155 offset:5120
	ds_read_b128 v[232:235], v155 offset:6144
	ds_read_b128 v[236:239], v155 offset:7168
	global_load_lds_dwordx4 v[180:181], off
	v_lshl_add_u64 v[180:181], s[54:55], 0, v[136:137]
	s_add_i32 m0, s64, 0xe000
	s_nop 0
	global_load_lds_dwordx4 v[180:181], off
	s_waitcnt vmcnt(8)
	s_waitcnt lgkmcnt(0)
	s_barrier
	v_mfma_f32_16x16x32_bf16 v[124:127], v[138:141], v[208:211], v[124:127]
	v_mfma_f32_16x16x32_bf16 v[120:123], v[160:163], v[208:211], v[120:123]
	v_mfma_f32_16x16x32_bf16 v[108:111], v[138:141], v[216:219], v[108:111]
	v_mfma_f32_16x16x32_bf16 v[104:107], v[160:163], v[216:219], v[104:107]
	v_mfma_f32_16x16x32_bf16 v[92:95], v[138:141], v[224:227], v[92:95]
	v_mfma_f32_16x16x32_bf16 v[88:91], v[160:163], v[224:227], v[88:91]
	v_mfma_f32_16x16x32_bf16 v[76:79], v[138:141], v[232:235], v[76:79]
	v_mfma_f32_16x16x32_bf16 v[72:75], v[160:163], v[232:235], v[72:75]
	v_mfma_f32_16x16x32_bf16 v[124:127], v[156:159], v[212:215], v[124:127]
	v_mfma_f32_16x16x32_bf16 v[120:123], v[164:167], v[212:215], v[120:123]
	v_mfma_f32_16x16x32_bf16 v[108:111], v[156:159], v[220:223], v[108:111]
	v_mfma_f32_16x16x32_bf16 v[104:107], v[164:167], v[220:223], v[104:107]
	v_mfma_f32_16x16x32_bf16 v[92:95], v[156:159], v[228:231], v[92:95]
	v_mfma_f32_16x16x32_bf16 v[88:91], v[164:167], v[228:231], v[88:91]
	v_mfma_f32_16x16x32_bf16 v[76:79], v[156:159], v[236:239], v[76:79]
	v_mfma_f32_16x16x32_bf16 v[72:75], v[164:167], v[236:239], v[72:75]
	v_mfma_f32_16x16x32_bf16 v[116:119], v[168:171], v[208:211], v[116:119]
	v_mfma_f32_16x16x32_bf16 v[112:115], v[176:179], v[208:211], v[112:115]
	v_mfma_f32_16x16x32_bf16 v[100:103], v[168:171], v[216:219], v[100:103]
	v_mfma_f32_16x16x32_bf16 v[96:99], v[176:179], v[216:219], v[96:99]
	v_mfma_f32_16x16x32_bf16 v[84:87], v[168:171], v[224:227], v[84:87]
	v_mfma_f32_16x16x32_bf16 v[80:83], v[176:179], v[224:227], v[80:83]
	v_mfma_f32_16x16x32_bf16 v[68:71], v[168:171], v[232:235], v[68:71]
	v_mfma_f32_16x16x32_bf16 v[64:67], v[176:179], v[232:235], v[64:67]
	v_mfma_f32_16x16x32_bf16 v[116:119], v[172:175], v[212:215], v[116:119]
	v_mfma_f32_16x16x32_bf16 v[112:115], v[204:207], v[212:215], v[112:115]
	v_mfma_f32_16x16x32_bf16 v[100:103], v[172:175], v[220:223], v[100:103]
	v_mfma_f32_16x16x32_bf16 v[96:99], v[204:207], v[220:223], v[96:99]
	v_mfma_f32_16x16x32_bf16 v[84:87], v[172:175], v[228:231], v[84:87]
	v_mfma_f32_16x16x32_bf16 v[80:83], v[204:207], v[228:231], v[80:83]
	v_mfma_f32_16x16x32_bf16 v[68:71], v[172:175], v[236:239], v[68:71]
	v_mfma_f32_16x16x32_bf16 v[64:67], v[204:207], v[236:239], v[64:67]
	s_barrier
	s_add_i32 s4, s74, s63
	v_lshl_add_u64 v[180:181], s[34:35], 0, v[144:145]
	s_mov_b32 m0, s4
	ds_read_b128 v[208:211], v155 offset:16384
	ds_read_b128 v[212:215], v155 offset:17408
	ds_read_b128 v[216:219], v155 offset:18432
	ds_read_b128 v[220:223], v155 offset:19456
	ds_read_b128 v[224:227], v155 offset:20480
	ds_read_b128 v[228:231], v155 offset:21504
	ds_read_b128 v[232:235], v155 offset:22528
	ds_read_b128 v[236:239], v155 offset:23552
	global_load_lds_dwordx4 v[180:181], off
	s_add_i32 m0, s4, 0x2000
	s_add_u32 s4, s34, 0x20000
	v_lshl_add_u64 v[202:203], s[34:35], 0, v[132:133]
	s_addc_u32 s5, s35, 0
	s_add_i32 s74, s75, s63
	global_load_lds_dwordx4 v[202:203], off
	v_lshl_add_u64 v[240:241], s[4:5], 0, v[144:145]
	s_mov_b32 m0, s74
	v_lshl_add_u64 v[242:243], s[58:59], 0, v[130:131]
	global_load_lds_dwordx4 v[240:241], off
	v_lshl_add_u64 v[240:241], s[4:5], 0, v[132:133]
	s_add_i32 m0, s74, 0x2000
	s_nop 0
	global_load_lds_dwordx4 v[240:241], off
	v_lshl_add_u64 v[240:241], s[58:59], 0, v[128:129]
	s_mov_b32 m0, s64
	s_nop 0
	global_load_lds_dwordx4 v[240:241], off
	s_mov_b32 m0, s65
	s_nop 0
	global_load_lds_dwordx4 v[242:243], off
	s_waitcnt vmcnt(8)
	s_waitcnt lgkmcnt(0)
	s_barrier
	v_mfma_f32_16x16x32_bf16 v[60:63], v[138:141], v[208:211], v[60:63]
	v_mfma_f32_16x16x32_bf16 v[56:59], v[160:163], v[208:211], v[56:59]
	v_mfma_f32_16x16x32_bf16 v[44:47], v[138:141], v[216:219], v[44:47]
	v_mfma_f32_16x16x32_bf16 v[40:43], v[160:163], v[216:219], v[40:43]
	v_mfma_f32_16x16x32_bf16 v[28:31], v[138:141], v[224:227], v[28:31]
	v_mfma_f32_16x16x32_bf16 v[24:27], v[160:163], v[224:227], v[24:27]
	v_mfma_f32_16x16x32_bf16 v[12:15], v[138:141], v[232:235], v[12:15]
	v_mfma_f32_16x16x32_bf16 v[8:11], v[160:163], v[232:235], v[8:11]
	v_mfma_f32_16x16x32_bf16 v[60:63], v[156:159], v[212:215], v[60:63]
	v_mfma_f32_16x16x32_bf16 v[56:59], v[164:167], v[212:215], v[56:59]
	v_mfma_f32_16x16x32_bf16 v[44:47], v[156:159], v[220:223], v[44:47]
	v_mfma_f32_16x16x32_bf16 v[40:43], v[164:167], v[220:223], v[40:43]
	v_mfma_f32_16x16x32_bf16 v[28:31], v[156:159], v[228:231], v[28:31]
	v_mfma_f32_16x16x32_bf16 v[24:27], v[164:167], v[228:231], v[24:27]
	v_mfma_f32_16x16x32_bf16 v[12:15], v[156:159], v[236:239], v[12:15]
	v_mfma_f32_16x16x32_bf16 v[8:11], v[164:167], v[236:239], v[8:11]
	v_mfma_f32_16x16x32_bf16 v[52:55], v[168:171], v[208:211], v[52:55]
	v_mfma_f32_16x16x32_bf16 v[48:51], v[176:179], v[208:211], v[48:51]
	v_mfma_f32_16x16x32_bf16 v[36:39], v[168:171], v[216:219], v[36:39]
	v_mfma_f32_16x16x32_bf16 v[32:35], v[176:179], v[216:219], v[32:35]
	v_mfma_f32_16x16x32_bf16 v[20:23], v[168:171], v[224:227], v[20:23]
	v_mfma_f32_16x16x32_bf16 v[16:19], v[176:179], v[224:227], v[16:19]
	v_mfma_f32_16x16x32_bf16 v[4:7], v[168:171], v[232:235], v[4:7]
	v_mfma_f32_16x16x32_bf16 v[0:3], v[176:179], v[232:235], v[0:3]
	v_mfma_f32_16x16x32_bf16 v[52:55], v[172:175], v[212:215], v[52:55]
	v_mfma_f32_16x16x32_bf16 v[48:51], v[204:207], v[212:215], v[48:51]
	v_mfma_f32_16x16x32_bf16 v[36:39], v[172:175], v[220:223], v[36:39]
	v_mfma_f32_16x16x32_bf16 v[32:35], v[204:207], v[220:223], v[32:35]
	v_mfma_f32_16x16x32_bf16 v[20:23], v[172:175], v[228:231], v[20:23]
	v_mfma_f32_16x16x32_bf16 v[16:19], v[204:207], v[228:231], v[16:19]
	v_mfma_f32_16x16x32_bf16 v[4:7], v[172:175], v[236:239], v[4:7]
	v_mfma_f32_16x16x32_bf16 v[0:3], v[204:207], v[236:239], v[0:3]
	s_barrier
	s_add_i32 s74, 0, 0x18000
	s_add_i32 s75, 0, 0x1c000
	v_add_u32_e32 v164, s74, v143
	v_add_u32_e32 v204, s75, v143
	ds_read_b128 v[138:141], v164
	ds_read_b128 v[156:159], v164 offset:1024
	ds_read_b128 v[160:163], v164 offset:2048
	ds_read_b128 v[164:167], v164 offset:3072
	ds_read_b128 v[168:171], v204
	ds_read_b128 v[172:175], v204 offset:1024
	ds_read_b128 v[176:179], v204 offset:2048
	ds_read_b128 v[204:207], v204 offset:3072
	s_add_u32 s4, s58, 0x20000
	s_addc_u32 s5, s59, 0
	s_mov_b32 m0, s66
	v_lshl_add_u64 v[244:245], s[4:5], 0, v[128:129]
	ds_read_b128 v[208:211], v155 offset:32768
	ds_read_b128 v[212:215], v155 offset:33792
	ds_read_b128 v[216:219], v155 offset:34816
	ds_read_b128 v[220:223], v155 offset:35840
	ds_read_b128 v[224:227], v155 offset:36864
	ds_read_b128 v[228:231], v155 offset:37888
	ds_read_b128 v[232:235], v155 offset:38912
	ds_read_b128 v[236:239], v155 offset:39936
	global_load_lds_dwordx4 v[244:245], off
	v_lshl_add_u64 v[244:245], s[4:5], 0, v[130:131]
	s_mov_b32 m0, s67
	s_nop 0
	global_load_lds_dwordx4 v[244:245], off
	s_waitcnt vmcnt(8)
	s_waitcnt lgkmcnt(0)
	s_barrier
	v_mfma_f32_16x16x32_bf16 v[124:127], v[138:141], v[208:211], v[124:127]
	v_mfma_f32_16x16x32_bf16 v[120:123], v[160:163], v[208:211], v[120:123]
	v_mfma_f32_16x16x32_bf16 v[108:111], v[138:141], v[216:219], v[108:111]
	v_mfma_f32_16x16x32_bf16 v[104:107], v[160:163], v[216:219], v[104:107]
	v_mfma_f32_16x16x32_bf16 v[92:95], v[138:141], v[224:227], v[92:95]
	v_mfma_f32_16x16x32_bf16 v[88:91], v[160:163], v[224:227], v[88:91]
	v_mfma_f32_16x16x32_bf16 v[76:79], v[138:141], v[232:235], v[76:79]
	v_mfma_f32_16x16x32_bf16 v[72:75], v[160:163], v[232:235], v[72:75]
	v_mfma_f32_16x16x32_bf16 v[124:127], v[156:159], v[212:215], v[124:127]
	v_mfma_f32_16x16x32_bf16 v[120:123], v[164:167], v[212:215], v[120:123]
	v_mfma_f32_16x16x32_bf16 v[108:111], v[156:159], v[220:223], v[108:111]
	v_mfma_f32_16x16x32_bf16 v[104:107], v[164:167], v[220:223], v[104:107]
	v_mfma_f32_16x16x32_bf16 v[92:95], v[156:159], v[228:231], v[92:95]
	v_mfma_f32_16x16x32_bf16 v[88:91], v[164:167], v[228:231], v[88:91]
	v_mfma_f32_16x16x32_bf16 v[76:79], v[156:159], v[236:239], v[76:79]
	v_mfma_f32_16x16x32_bf16 v[72:75], v[164:167], v[236:239], v[72:75]
	v_mfma_f32_16x16x32_bf16 v[116:119], v[168:171], v[208:211], v[116:119]
	v_mfma_f32_16x16x32_bf16 v[112:115], v[176:179], v[208:211], v[112:115]
	v_mfma_f32_16x16x32_bf16 v[100:103], v[168:171], v[216:219], v[100:103]
	v_mfma_f32_16x16x32_bf16 v[96:99], v[176:179], v[216:219], v[96:99]
	v_mfma_f32_16x16x32_bf16 v[84:87], v[168:171], v[224:227], v[84:87]
	v_mfma_f32_16x16x32_bf16 v[80:83], v[176:179], v[224:227], v[80:83]
	v_mfma_f32_16x16x32_bf16 v[68:71], v[168:171], v[232:235], v[68:71]
	v_mfma_f32_16x16x32_bf16 v[64:67], v[176:179], v[232:235], v[64:67]
	v_mfma_f32_16x16x32_bf16 v[116:119], v[172:175], v[212:215], v[116:119]
	v_mfma_f32_16x16x32_bf16 v[112:115], v[204:207], v[212:215], v[112:115]
	v_mfma_f32_16x16x32_bf16 v[100:103], v[172:175], v[220:223], v[100:103]
	v_mfma_f32_16x16x32_bf16 v[96:99], v[204:207], v[220:223], v[96:99]
	v_mfma_f32_16x16x32_bf16 v[84:87], v[172:175], v[228:231], v[84:87]
	v_mfma_f32_16x16x32_bf16 v[80:83], v[204:207], v[228:231], v[80:83]
	v_mfma_f32_16x16x32_bf16 v[68:71], v[172:175], v[236:239], v[68:71]
	v_mfma_f32_16x16x32_bf16 v[64:67], v[204:207], v[236:239], v[64:67]
	s_barrier
	s_add_i32 s4, s74, s63
	v_lshl_add_u64 v[180:181], v[180:181], 0, s[26:27]
	s_mov_b32 m0, s4
	ds_read_b128 v[208:211], v155 offset:49152
	ds_read_b128 v[212:215], v155 offset:50176
	ds_read_b128 v[216:219], v155 offset:51200
	ds_read_b128 v[220:223], v155 offset:52224
	ds_read_b128 v[224:227], v155 offset:53248
	ds_read_b128 v[228:231], v155 offset:54272
	ds_read_b128 v[232:235], v155 offset:55296
	ds_read_b128 v[236:239], v155 offset:56320
	global_load_lds_dwordx4 v[180:181], off
	s_add_i32 m0, s4, 0x2000
	s_add_u32 s4, s34, 0x20080
	v_lshl_add_u64 v[180:181], v[202:203], 0, s[26:27]
	s_addc_u32 s5, s35, 0
	s_add_i32 s34, s75, s63
	global_load_lds_dwordx4 v[180:181], off
	v_lshl_add_u64 v[180:181], s[4:5], 0, v[144:145]
	s_mov_b32 m0, s34
	s_nop 0
	global_load_lds_dwordx4 v[180:181], off
	v_lshl_add_u64 v[180:181], s[4:5], 0, v[132:133]
	s_add_i32 m0, s34, 0x2000
	s_nop 0
	global_load_lds_dwordx4 v[180:181], off
	v_lshl_add_u64 v[180:181], v[240:241], 0, s[26:27]
	s_mov_b32 m0, s68
	s_nop 0
	global_load_lds_dwordx4 v[180:181], off
	v_lshl_add_u64 v[180:181], v[242:243], 0, s[26:27]
	s_mov_b32 m0, s69
	s_nop 0
	global_load_lds_dwordx4 v[180:181], off
	s_waitcnt vmcnt(8)
	s_waitcnt lgkmcnt(0)
	s_barrier
	v_mfma_f32_16x16x32_bf16 v[60:63], v[138:141], v[208:211], v[60:63]
	v_mfma_f32_16x16x32_bf16 v[56:59], v[160:163], v[208:211], v[56:59]
	v_mfma_f32_16x16x32_bf16 v[44:47], v[138:141], v[216:219], v[44:47]
	v_mfma_f32_16x16x32_bf16 v[40:43], v[160:163], v[216:219], v[40:43]
	v_mfma_f32_16x16x32_bf16 v[28:31], v[138:141], v[224:227], v[28:31]
	v_mfma_f32_16x16x32_bf16 v[24:27], v[160:163], v[224:227], v[24:27]
	v_mfma_f32_16x16x32_bf16 v[12:15], v[138:141], v[232:235], v[12:15]
	v_mfma_f32_16x16x32_bf16 v[8:11], v[160:163], v[232:235], v[8:11]
	v_mfma_f32_16x16x32_bf16 v[60:63], v[156:159], v[212:215], v[60:63]
	v_mfma_f32_16x16x32_bf16 v[56:59], v[164:167], v[212:215], v[56:59]
	v_mfma_f32_16x16x32_bf16 v[44:47], v[156:159], v[220:223], v[44:47]
	v_mfma_f32_16x16x32_bf16 v[40:43], v[164:167], v[220:223], v[40:43]
	v_mfma_f32_16x16x32_bf16 v[28:31], v[156:159], v[228:231], v[28:31]
	v_mfma_f32_16x16x32_bf16 v[24:27], v[164:167], v[228:231], v[24:27]
	v_mfma_f32_16x16x32_bf16 v[12:15], v[156:159], v[236:239], v[12:15]
	v_mfma_f32_16x16x32_bf16 v[8:11], v[164:167], v[236:239], v[8:11]
	v_mfma_f32_16x16x32_bf16 v[52:55], v[168:171], v[208:211], v[52:55]
	v_mfma_f32_16x16x32_bf16 v[48:51], v[176:179], v[208:211], v[48:51]
	v_mfma_f32_16x16x32_bf16 v[36:39], v[168:171], v[216:219], v[36:39]
	v_mfma_f32_16x16x32_bf16 v[32:35], v[176:179], v[216:219], v[32:35]
	v_mfma_f32_16x16x32_bf16 v[20:23], v[168:171], v[224:227], v[20:23]
	v_mfma_f32_16x16x32_bf16 v[16:19], v[176:179], v[224:227], v[16:19]
	v_mfma_f32_16x16x32_bf16 v[4:7], v[168:171], v[232:235], v[4:7]
	v_mfma_f32_16x16x32_bf16 v[0:3], v[176:179], v[232:235], v[0:3]
	v_mfma_f32_16x16x32_bf16 v[52:55], v[172:175], v[212:215], v[52:55]
	v_mfma_f32_16x16x32_bf16 v[48:51], v[204:207], v[212:215], v[48:51]
	v_mfma_f32_16x16x32_bf16 v[36:39], v[172:175], v[220:223], v[36:39]
	v_mfma_f32_16x16x32_bf16 v[32:35], v[204:207], v[220:223], v[32:35]
	v_mfma_f32_16x16x32_bf16 v[20:23], v[172:175], v[228:231], v[20:23]
	v_mfma_f32_16x16x32_bf16 v[16:19], v[204:207], v[228:231], v[16:19]
	v_mfma_f32_16x16x32_bf16 v[4:7], v[172:175], v[236:239], v[4:7]
	v_mfma_f32_16x16x32_bf16 v[0:3], v[204:207], v[236:239], v[0:3]
	s_barrier
	s_add_i32 s73, s73, 2
	s_add_u32 s54, s54, 0x100
	s_addc_u32 s55, s55, 0
	s_add_u32 s71, s71, 0x100
	s_addc_u32 s72, s72, 0
	s_cmp_gt_u32 s73, 5
	s_cbranch_scc0 .LBB0_1117
	s_setprio 0
	s_and_b64 vcc, exec, s[44:45]
	s_cbranch_vccz .LBB0_1120
	s_barrier

.Lkprio_1207:
.LBB0_1207:
	s_add_u32 s62, s60, 0x100
	s_addc_u32 s63, s61, 0
	s_add_i32 s4, 0, 0x10000
	s_cmp_eq_u32 s29, 12
	s_cselect_b32 s65, s55, s63
	s_cselect_b32 s64, s54, s62
	v_add_u32_e32 v142, s4, v160
	s_cselect_b32 s35, s59, s28
	s_cselect_b32 s34, s58, s3
	s_add_i32 s45, 0, 0x14000
	ds_read_b128 v[138:141], v142
	ds_read_b128 v[154:157], v142 offset:1024
	ds_read_b128 v[172:175], v142 offset:2048
	ds_read_b128 v[176:179], v142 offset:3072
	v_add_u32_e32 v142, s45, v160
	ds_read_b128 v[204:207], v142
	ds_read_b128 v[208:211], v142 offset:1024
	ds_read_b128 v[212:215], v142 offset:2048
	ds_read_b128 v[216:219], v142 offset:3072
	v_lshl_add_u64 v[142:143], s[60:61], 0, v[134:135]
	s_add_i32 m0, s69, 0xc000
	ds_read_b128 v[220:223], v170
	ds_read_b128 v[224:227], v170 offset:1024
	ds_read_b128 v[228:231], v170 offset:2048
	ds_read_b128 v[232:235], v170 offset:3072
	ds_read_b128 v[236:239], v170 offset:4096
	ds_read_b128 v[240:243], v170 offset:5120
	ds_read_b128 v[244:247], v170 offset:6144
	ds_read_b128 v[248:251], v170 offset:7168
	global_load_lds_dwordx4 v[142:143], off
	v_lshl_add_u64 v[142:143], s[60:61], 0, v[136:137]
	s_add_i32 m0, s69, 0xe000
	s_nop 0
	global_load_lds_dwordx4 v[142:143], off
	s_waitcnt vmcnt(8)
	s_waitcnt lgkmcnt(0)
	s_barrier
	v_mfma_f32_16x16x32_bf16 v[124:127], v[138:141], v[220:223], v[124:127]
	v_mfma_f32_16x16x32_bf16 v[120:123], v[172:175], v[220:223], v[120:123]
	v_mfma_f32_16x16x32_bf16 v[108:111], v[138:141], v[228:231], v[108:111]
	v_mfma_f32_16x16x32_bf16 v[104:107], v[172:175], v[228:231], v[104:107]
	v_mfma_f32_16x16x32_bf16 v[92:95], v[138:141], v[236:239], v[92:95]
	v_mfma_f32_16x16x32_bf16 v[88:91], v[172:175], v[236:239], v[88:91]
	v_mfma_f32_16x16x32_bf16 v[76:79], v[138:141], v[244:247], v[76:79]
	v_mfma_f32_16x16x32_bf16 v[72:75], v[172:175], v[244:247], v[72:75]
	v_mfma_f32_16x16x32_bf16 v[124:127], v[154:157], v[224:227], v[124:127]
	v_mfma_f32_16x16x32_bf16 v[120:123], v[176:179], v[224:227], v[120:123]
	v_mfma_f32_16x16x32_bf16 v[108:111], v[154:157], v[232:235], v[108:111]
	v_mfma_f32_16x16x32_bf16 v[104:107], v[176:179], v[232:235], v[104:107]
	v_mfma_f32_16x16x32_bf16 v[92:95], v[154:157], v[240:243], v[92:95]
	v_mfma_f32_16x16x32_bf16 v[88:91], v[176:179], v[240:243], v[88:91]
	v_mfma_f32_16x16x32_bf16 v[76:79], v[154:157], v[248:251], v[76:79]
	v_mfma_f32_16x16x32_bf16 v[72:75], v[176:179], v[248:251], v[72:75]
	v_mfma_f32_16x16x32_bf16 v[116:119], v[204:207], v[220:223], v[116:119]
	v_mfma_f32_16x16x32_bf16 v[112:115], v[212:215], v[220:223], v[112:115]
	v_mfma_f32_16x16x32_bf16 v[100:103], v[204:207], v[228:231], v[100:103]
	v_mfma_f32_16x16x32_bf16 v[96:99], v[212:215], v[228:231], v[96:99]
	v_mfma_f32_16x16x32_bf16 v[84:87], v[204:207], v[236:239], v[84:87]
	v_mfma_f32_16x16x32_bf16 v[80:83], v[212:215], v[236:239], v[80:83]
	v_mfma_f32_16x16x32_bf16 v[68:71], v[204:207], v[244:247], v[68:71]
	v_mfma_f32_16x16x32_bf16 v[64:67], v[212:215], v[244:247], v[64:67]
	v_mfma_f32_16x16x32_bf16 v[116:119], v[208:211], v[224:227], v[116:119]
	v_mfma_f32_16x16x32_bf16 v[112:115], v[216:219], v[224:227], v[112:115]
	v_mfma_f32_16x16x32_bf16 v[100:103], v[208:211], v[232:235], v[100:103]
	v_mfma_f32_16x16x32_bf16 v[96:99], v[216:219], v[232:235], v[96:99]
	v_mfma_f32_16x16x32_bf16 v[84:87], v[208:211], v[240:243], v[84:87]
	v_mfma_f32_16x16x32_bf16 v[80:83], v[216:219], v[240:243], v[80:83]
	v_mfma_f32_16x16x32_bf16 v[68:71], v[208:211], v[248:251], v[68:71]
	v_mfma_f32_16x16x32_bf16 v[64:67], v[216:219], v[248:251], v[64:67]
	s_barrier
	s_add_i32 s4, s4, s33
	v_lshl_add_u64 v[142:143], s[34:35], 0, v[128:129]
	s_mov_b32 m0, s4
	ds_read_b128 v[220:223], v170 offset:16384
	ds_read_b128 v[224:227], v170 offset:17408
	ds_read_b128 v[228:231], v170 offset:18432
	ds_read_b128 v[232:235], v170 offset:19456
	ds_read_b128 v[236:239], v170 offset:20480
	ds_read_b128 v[240:243], v170 offset:21504
	ds_read_b128 v[244:247], v170 offset:22528
	ds_read_b128 v[248:251], v170 offset:23552
	global_load_lds_dwordx4 v[142:143], off
	s_add_i32 m0, s4, 0x2000
	s_add_u32 s4, s34, 0x40000
	v_lshl_add_u64 v[158:159], s[34:35], 0, v[130:131]
	s_addc_u32 s5, s35, 0
	s_add_i32 s45, s45, s33
	global_load_lds_dwordx4 v[158:159], off
	v_lshl_add_u64 v[180:181], s[4:5], 0, v[128:129]
	s_mov_b32 m0, s45
	v_lshl_add_u64 v[202:203], s[64:65], 0, v[130:131]
	global_load_lds_dwordx4 v[180:181], off
	v_lshl_add_u64 v[180:181], s[4:5], 0, v[130:131]
	s_add_i32 m0, s45, 0x2000
	s_nop 0
	global_load_lds_dwordx4 v[180:181], off
	v_lshl_add_u64 v[180:181], s[64:65], 0, v[128:129]
	s_mov_b32 m0, s69
	s_nop 0
	global_load_lds_dwordx4 v[180:181], off
	s_mov_b32 m0, s70
	s_nop 0
	global_load_lds_dwordx4 v[202:203], off
	s_waitcnt vmcnt(8)
	s_waitcnt lgkmcnt(0)
	s_barrier
	v_mfma_f32_16x16x32_bf16 v[60:63], v[138:141], v[220:223], v[60:63]
	v_mfma_f32_16x16x32_bf16 v[56:59], v[172:175], v[220:223], v[56:59]
	v_mfma_f32_16x16x32_bf16 v[44:47], v[138:141], v[228:231], v[44:47]
	v_mfma_f32_16x16x32_bf16 v[40:43], v[172:175], v[228:231], v[40:43]
	v_mfma_f32_16x16x32_bf16 v[28:31], v[138:141], v[236:239], v[28:31]
	v_mfma_f32_16x16x32_bf16 v[24:27], v[172:175], v[236:239], v[24:27]
	v_mfma_f32_16x16x32_bf16 v[12:15], v[138:141], v[244:247], v[12:15]
	v_mfma_f32_16x16x32_bf16 v[8:11], v[172:175], v[244:247], v[8:11]
	v_mfma_f32_16x16x32_bf16 v[60:63], v[154:157], v[224:227], v[60:63]
	v_mfma_f32_16x16x32_bf16 v[56:59], v[176:179], v[224:227], v[56:59]
	v_mfma_f32_16x16x32_bf16 v[44:47], v[154:157], v[232:235], v[44:47]
	v_mfma_f32_16x16x32_bf16 v[40:43], v[176:179], v[232:235], v[40:43]
	v_mfma_f32_16x16x32_bf16 v[28:31], v[154:157], v[240:243], v[28:31]
	v_mfma_f32_16x16x32_bf16 v[24:27], v[176:179], v[240:243], v[24:27]
	v_mfma_f32_16x16x32_bf16 v[12:15], v[154:157], v[248:251], v[12:15]
	v_mfma_f32_16x16x32_bf16 v[8:11], v[176:179], v[248:251], v[8:11]
	v_mfma_f32_16x16x32_bf16 v[52:55], v[204:207], v[220:223], v[52:55]
	v_mfma_f32_16x16x32_bf16 v[48:51], v[212:215], v[220:223], v[48:51]
	v_mfma_f32_16x16x32_bf16 v[36:39], v[204:207], v[228:231], v[36:39]
	v_mfma_f32_16x16x32_bf16 v[32:35], v[212:215], v[228:231], v[32:35]
	v_mfma_f32_16x16x32_bf16 v[20:23], v[204:207], v[236:239], v[20:23]
	v_mfma_f32_16x16x32_bf16 v[16:19], v[212:215], v[236:239], v[16:19]
	v_mfma_f32_16x16x32_bf16 v[4:7], v[204:207], v[244:247], v[4:7]
	v_mfma_f32_16x16x32_bf16 v[0:3], v[212:215], v[244:247], v[0:3]
	v_mfma_f32_16x16x32_bf16 v[52:55], v[208:211], v[224:227], v[52:55]
	v_mfma_f32_16x16x32_bf16 v[48:51], v[216:219], v[224:227], v[48:51]
	v_mfma_f32_16x16x32_bf16 v[36:39], v[208:211], v[232:235], v[36:39]
	v_mfma_f32_16x16x32_bf16 v[32:35], v[216:219], v[232:235], v[32:35]
	v_mfma_f32_16x16x32_bf16 v[20:23], v[208:211], v[240:243], v[20:23]
	v_mfma_f32_16x16x32_bf16 v[16:19], v[216:219], v[240:243], v[16:19]
	v_mfma_f32_16x16x32_bf16 v[4:7], v[208:211], v[248:251], v[4:7]
	v_mfma_f32_16x16x32_bf16 v[0:3], v[216:219], v[248:251], v[0:3]
	s_barrier
	s_add_i32 s45, 0, 0x18000
	v_add_u32_e32 v144, s45, v160
	s_add_i32 s51, 0, 0x1c000
	ds_read_b128 v[138:141], v144
	ds_read_b128 v[154:157], v144 offset:1024
	ds_read_b128 v[172:175], v144 offset:2048
	ds_read_b128 v[176:179], v144 offset:3072
	v_add_u32_e32 v144, s51, v160
	ds_read_b128 v[204:207], v144
	ds_read_b128 v[208:211], v144 offset:1024
	ds_read_b128 v[212:215], v144 offset:2048
	ds_read_b128 v[216:219], v144 offset:3072
	s_add_u32 s4, s64, 0x40000
	s_addc_u32 s5, s65, 0
	s_mov_b32 m0, s71
	v_lshl_add_u64 v[252:253], s[4:5], 0, v[128:129]
	ds_read_b128 v[220:223], v170 offset:32768
	ds_read_b128 v[224:227], v170 offset:33792
	ds_read_b128 v[228:231], v170 offset:34816
	ds_read_b128 v[232:235], v170 offset:35840
	ds_read_b128 v[236:239], v170 offset:36864
	ds_read_b128 v[240:243], v170 offset:37888
	ds_read_b128 v[244:247], v170 offset:38912
	ds_read_b128 v[248:251], v170 offset:39936
	global_load_lds_dwordx4 v[252:253], off
	v_lshl_add_u64 v[252:253], s[4:5], 0, v[130:131]
	s_mov_b32 m0, s72
	s_nop 0
	global_load_lds_dwordx4 v[252:253], off
	s_waitcnt vmcnt(8)
	s_waitcnt lgkmcnt(0)
	s_barrier
	v_mfma_f32_16x16x32_bf16 v[124:127], v[138:141], v[220:223], v[124:127]
	v_mfma_f32_16x16x32_bf16 v[120:123], v[172:175], v[220:223], v[120:123]
	v_mfma_f32_16x16x32_bf16 v[108:111], v[138:141], v[228:231], v[108:111]
	v_mfma_f32_16x16x32_bf16 v[104:107], v[172:175], v[228:231], v[104:107]
	v_mfma_f32_16x16x32_bf16 v[92:95], v[138:141], v[236:239], v[92:95]
	v_mfma_f32_16x16x32_bf16 v[88:91], v[172:175], v[236:239], v[88:91]
	v_mfma_f32_16x16x32_bf16 v[76:79], v[138:141], v[244:247], v[76:79]
	v_mfma_f32_16x16x32_bf16 v[72:75], v[172:175], v[244:247], v[72:75]
	v_mfma_f32_16x16x32_bf16 v[124:127], v[154:157], v[224:227], v[124:127]
	v_mfma_f32_16x16x32_bf16 v[120:123], v[176:179], v[224:227], v[120:123]
	v_mfma_f32_16x16x32_bf16 v[108:111], v[154:157], v[232:235], v[108:111]
	v_mfma_f32_16x16x32_bf16 v[104:107], v[176:179], v[232:235], v[104:107]
	v_mfma_f32_16x16x32_bf16 v[92:95], v[154:157], v[240:243], v[92:95]
	v_mfma_f32_16x16x32_bf16 v[88:91], v[176:179], v[240:243], v[88:91]
	v_mfma_f32_16x16x32_bf16 v[76:79], v[154:157], v[248:251], v[76:79]
	v_mfma_f32_16x16x32_bf16 v[72:75], v[176:179], v[248:251], v[72:75]
	v_mfma_f32_16x16x32_bf16 v[116:119], v[204:207], v[220:223], v[116:119]
	v_mfma_f32_16x16x32_bf16 v[112:115], v[212:215], v[220:223], v[112:115]
	v_mfma_f32_16x16x32_bf16 v[100:103], v[204:207], v[228:231], v[100:103]
	v_mfma_f32_16x16x32_bf16 v[96:99], v[212:215], v[228:231], v[96:99]
	v_mfma_f32_16x16x32_bf16 v[84:87], v[204:207], v[236:239], v[84:87]
	v_mfma_f32_16x16x32_bf16 v[80:83], v[212:215], v[236:239], v[80:83]
	v_mfma_f32_16x16x32_bf16 v[68:71], v[204:207], v[244:247], v[68:71]
	v_mfma_f32_16x16x32_bf16 v[64:67], v[212:215], v[244:247], v[64:67]
	v_mfma_f32_16x16x32_bf16 v[116:119], v[208:211], v[224:227], v[116:119]
	v_mfma_f32_16x16x32_bf16 v[112:115], v[216:219], v[224:227], v[112:115]
	v_mfma_f32_16x16x32_bf16 v[100:103], v[208:211], v[232:235], v[100:103]
	v_mfma_f32_16x16x32_bf16 v[96:99], v[216:219], v[232:235], v[96:99]
	v_mfma_f32_16x16x32_bf16 v[84:87], v[208:211], v[240:243], v[84:87]
	v_mfma_f32_16x16x32_bf16 v[80:83], v[216:219], v[240:243], v[80:83]
	v_mfma_f32_16x16x32_bf16 v[68:71], v[208:211], v[248:251], v[68:71]
	v_mfma_f32_16x16x32_bf16 v[64:67], v[216:219], v[248:251], v[64:67]
	s_barrier
	s_add_i32 s4, s45, s33
	v_lshl_add_u64 v[142:143], v[142:143], 0, s[26:27]
	s_mov_b32 m0, s4
	ds_read_b128 v[220:223], v170 offset:49152
	ds_read_b128 v[224:227], v170 offset:50176
	ds_read_b128 v[228:231], v170 offset:51200
	ds_read_b128 v[232:235], v170 offset:52224
	ds_read_b128 v[236:239], v170 offset:53248
	ds_read_b128 v[240:243], v170 offset:54272
	ds_read_b128 v[244:247], v170 offset:55296
	ds_read_b128 v[248:251], v170 offset:56320
	global_load_lds_dwordx4 v[142:143], off
	s_add_i32 m0, s4, 0x2000
	s_add_u32 s4, s34, 0x40080
	v_lshl_add_u64 v[142:143], v[158:159], 0, s[26:27]
	s_addc_u32 s5, s35, 0
	s_add_i32 s34, s51, s33
	global_load_lds_dwordx4 v[142:143], off
	v_lshl_add_u64 v[142:143], s[4:5], 0, v[128:129]
	s_mov_b32 m0, s34
	s_nop 0
	global_load_lds_dwordx4 v[142:143], off
	v_lshl_add_u64 v[142:143], s[4:5], 0, v[130:131]
	s_add_i32 m0, s34, 0x2000
	s_nop 0
	global_load_lds_dwordx4 v[142:143], off
	v_lshl_add_u64 v[142:143], v[180:181], 0, s[26:27]
	s_mov_b32 m0, s73
	s_nop 0
	global_load_lds_dwordx4 v[142:143], off
	v_lshl_add_u64 v[142:143], v[202:203], 0, s[26:27]
	s_mov_b32 m0, s74
	s_nop 0
	global_load_lds_dwordx4 v[142:143], off
	s_waitcnt vmcnt(8)
	s_waitcnt lgkmcnt(0)
	s_barrier
	v_mfma_f32_16x16x32_bf16 v[60:63], v[138:141], v[220:223], v[60:63]
	v_mfma_f32_16x16x32_bf16 v[56:59], v[172:175], v[220:223], v[56:59]
	v_mfma_f32_16x16x32_bf16 v[44:47], v[138:141], v[228:231], v[44:47]
	v_mfma_f32_16x16x32_bf16 v[40:43], v[172:175], v[228:231], v[40:43]
	v_mfma_f32_16x16x32_bf16 v[28:31], v[138:141], v[236:239], v[28:31]
	v_mfma_f32_16x16x32_bf16 v[24:27], v[172:175], v[236:239], v[24:27]
	v_mfma_f32_16x16x32_bf16 v[12:15], v[138:141], v[244:247], v[12:15]
	v_mfma_f32_16x16x32_bf16 v[8:11], v[172:175], v[244:247], v[8:11]
	v_mfma_f32_16x16x32_bf16 v[60:63], v[154:157], v[224:227], v[60:63]
	v_mfma_f32_16x16x32_bf16 v[56:59], v[176:179], v[224:227], v[56:59]
	v_mfma_f32_16x16x32_bf16 v[44:47], v[154:157], v[232:235], v[44:47]
	v_mfma_f32_16x16x32_bf16 v[40:43], v[176:179], v[232:235], v[40:43]
	v_mfma_f32_16x16x32_bf16 v[28:31], v[154:157], v[240:243], v[28:31]
	v_mfma_f32_16x16x32_bf16 v[24:27], v[176:179], v[240:243], v[24:27]
	v_mfma_f32_16x16x32_bf16 v[12:15], v[154:157], v[248:251], v[12:15]
	v_mfma_f32_16x16x32_bf16 v[8:11], v[176:179], v[248:251], v[8:11]
	v_mfma_f32_16x16x32_bf16 v[52:55], v[204:207], v[220:223], v[52:55]
	v_mfma_f32_16x16x32_bf16 v[48:51], v[212:215], v[220:223], v[48:51]
	v_mfma_f32_16x16x32_bf16 v[36:39], v[204:207], v[228:231], v[36:39]
	v_mfma_f32_16x16x32_bf16 v[32:35], v[212:215], v[228:231], v[32:35]
	v_mfma_f32_16x16x32_bf16 v[20:23], v[204:207], v[236:239], v[20:23]
	v_mfma_f32_16x16x32_bf16 v[16:19], v[212:215], v[236:239], v[16:19]
	v_mfma_f32_16x16x32_bf16 v[4:7], v[204:207], v[244:247], v[4:7]
	v_mfma_f32_16x16x32_bf16 v[0:3], v[212:215], v[244:247], v[0:3]
	v_mfma_f32_16x16x32_bf16 v[52:55], v[208:211], v[224:227], v[52:55]
	v_mfma_f32_16x16x32_bf16 v[48:51], v[216:219], v[224:227], v[48:51]
	v_mfma_f32_16x16x32_bf16 v[36:39], v[208:211], v[232:235], v[36:39]
	v_mfma_f32_16x16x32_bf16 v[32:35], v[216:219], v[232:235], v[32:35]
	v_mfma_f32_16x16x32_bf16 v[20:23], v[208:211], v[240:243], v[20:23]
	v_mfma_f32_16x16x32_bf16 v[16:19], v[216:219], v[240:243], v[16:19]
	v_mfma_f32_16x16x32_bf16 v[4:7], v[208:211], v[248:251], v[4:7]
	v_mfma_f32_16x16x32_bf16 v[0:3], v[216:219], v[248:251], v[0:3]
	s_barrier
	s_add_i32 s29, s29, 2
	s_add_u32 s3, s3, 0x100
	s_addc_u32 s28, s28, 0
	s_cmp_gt_u32 s29, 13
	s_mov_b64 s[60:61], s[62:63]
	s_cbranch_scc0 .LBB0_1207
	s_setprio 0
	s_and_b64 vcc, exec, s[48:49]
	s_cbranch_vccz .LBB0_1210
	s_barrier

.Lkprio_1305:
.LBB0_1305:
	s_add_u32 s4, s2, 0xfffc0080
	s_addc_u32 s5, s3, -1
	s_add_i32 s74, 0, 0x10000
	s_cmp_eq_u32 s73, 12
	s_cselect_b32 s61, s36, s5
	s_cselect_b32 s60, s51, s4
	s_cselect_b32 s35, s49, s72
	s_cselect_b32 s34, s70, s71
	s_add_i32 s75, 0, 0x14000
	v_add_u32_e32 v164, s74, v143
	v_add_u32_e32 v180, s75, v143
	ds_read_b128 v[138:141], v164
	ds_read_b128 v[156:159], v164 offset:1024
	ds_read_b128 v[160:163], v164 offset:2048
	ds_read_b128 v[164:167], v164 offset:3072
	ds_read_b128 v[168:171], v180
	ds_read_b128 v[172:175], v180 offset:1024
	ds_read_b128 v[176:179], v180 offset:2048
	ds_read_b128 v[204:207], v180 offset:3072
	v_lshl_add_u64 v[180:181], s[2:3], 0, v[134:135]
	s_add_i32 m0, s59, 0xc000
	ds_read_b128 v[208:211], v155
	ds_read_b128 v[212:215], v155 offset:1024
	ds_read_b128 v[216:219], v155 offset:2048
	ds_read_b128 v[220:223], v155 offset:3072
	ds_read_b128 v[224:227], v155 offset:4096
	ds_read_b128 v[228:231], v155 offset:5120
	ds_read_b128 v[232:235], v155 offset:6144
	ds_read_b128 v[236:239], v155 offset:7168
	global_load_lds_dwordx4 v[180:181], off
	v_lshl_add_u64 v[180:181], s[2:3], 0, v[136:137]
	s_add_i32 m0, s59, 0xe000
	s_nop 0
	global_load_lds_dwordx4 v[180:181], off
	s_waitcnt vmcnt(8)
	s_waitcnt lgkmcnt(0)
	s_barrier
	v_mfma_f32_16x16x32_bf16 v[124:127], v[138:141], v[208:211], v[124:127]
	v_mfma_f32_16x16x32_bf16 v[120:123], v[160:163], v[208:211], v[120:123]
	v_mfma_f32_16x16x32_bf16 v[108:111], v[138:141], v[216:219], v[108:111]
	v_mfma_f32_16x16x32_bf16 v[104:107], v[160:163], v[216:219], v[104:107]
	v_mfma_f32_16x16x32_bf16 v[92:95], v[138:141], v[224:227], v[92:95]
	v_mfma_f32_16x16x32_bf16 v[88:91], v[160:163], v[224:227], v[88:91]
	v_mfma_f32_16x16x32_bf16 v[76:79], v[138:141], v[232:235], v[76:79]
	v_mfma_f32_16x16x32_bf16 v[72:75], v[160:163], v[232:235], v[72:75]
	v_mfma_f32_16x16x32_bf16 v[124:127], v[156:159], v[212:215], v[124:127]
	v_mfma_f32_16x16x32_bf16 v[120:123], v[164:167], v[212:215], v[120:123]
	v_mfma_f32_16x16x32_bf16 v[108:111], v[156:159], v[220:223], v[108:111]
	v_mfma_f32_16x16x32_bf16 v[104:107], v[164:167], v[220:223], v[104:107]
	v_mfma_f32_16x16x32_bf16 v[92:95], v[156:159], v[228:231], v[92:95]
	v_mfma_f32_16x16x32_bf16 v[88:91], v[164:167], v[228:231], v[88:91]
	v_mfma_f32_16x16x32_bf16 v[76:79], v[156:159], v[236:239], v[76:79]
	v_mfma_f32_16x16x32_bf16 v[72:75], v[164:167], v[236:239], v[72:75]
	v_mfma_f32_16x16x32_bf16 v[116:119], v[168:171], v[208:211], v[116:119]
	v_mfma_f32_16x16x32_bf16 v[112:115], v[176:179], v[208:211], v[112:115]
	v_mfma_f32_16x16x32_bf16 v[100:103], v[168:171], v[216:219], v[100:103]
	v_mfma_f32_16x16x32_bf16 v[96:99], v[176:179], v[216:219], v[96:99]
	v_mfma_f32_16x16x32_bf16 v[84:87], v[168:171], v[224:227], v[84:87]
	v_mfma_f32_16x16x32_bf16 v[80:83], v[176:179], v[224:227], v[80:83]
	v_mfma_f32_16x16x32_bf16 v[68:71], v[168:171], v[232:235], v[68:71]
	v_mfma_f32_16x16x32_bf16 v[64:67], v[176:179], v[232:235], v[64:67]
	v_mfma_f32_16x16x32_bf16 v[116:119], v[172:175], v[212:215], v[116:119]
	v_mfma_f32_16x16x32_bf16 v[112:115], v[204:207], v[212:215], v[112:115]
	v_mfma_f32_16x16x32_bf16 v[100:103], v[172:175], v[220:223], v[100:103]
	v_mfma_f32_16x16x32_bf16 v[96:99], v[204:207], v[220:223], v[96:99]
	v_mfma_f32_16x16x32_bf16 v[84:87], v[172:175], v[228:231], v[84:87]
	v_mfma_f32_16x16x32_bf16 v[80:83], v[204:207], v[228:231], v[80:83]
	v_mfma_f32_16x16x32_bf16 v[68:71], v[172:175], v[236:239], v[68:71]
	v_mfma_f32_16x16x32_bf16 v[64:67], v[204:207], v[236:239], v[64:67]
	s_barrier
	s_add_i32 s4, s74, s1
	v_lshl_add_u64 v[180:181], s[34:35], 0, v[144:145]
	s_mov_b32 m0, s4
	ds_read_b128 v[208:211], v155 offset:16384
	ds_read_b128 v[212:215], v155 offset:17408
	ds_read_b128 v[216:219], v155 offset:18432
	ds_read_b128 v[220:223], v155 offset:19456
	ds_read_b128 v[224:227], v155 offset:20480
	ds_read_b128 v[228:231], v155 offset:21504
	ds_read_b128 v[232:235], v155 offset:22528
	ds_read_b128 v[236:239], v155 offset:23552
	global_load_lds_dwordx4 v[180:181], off
	s_add_i32 m0, s4, 0x2000
	s_add_u32 s4, s34, 0x40000
	v_lshl_add_u64 v[202:203], s[34:35], 0, v[128:129]
	s_addc_u32 s5, s35, 0
	s_add_i32 s74, s75, s1
	global_load_lds_dwordx4 v[202:203], off
	v_lshl_add_u64 v[240:241], s[4:5], 0, v[144:145]
	s_mov_b32 m0, s74
	v_lshl_add_u64 v[242:243], s[60:61], 0, v[130:131]
	global_load_lds_dwordx4 v[240:241], off
	v_lshl_add_u64 v[240:241], s[4:5], 0, v[128:129]
	s_add_i32 m0, s74, 0x2000
	s_nop 0
	global_load_lds_dwordx4 v[240:241], off
	v_lshl_add_u64 v[240:241], s[60:61], 0, v[132:133]
	s_mov_b32 m0, s59
	s_nop 0
	global_load_lds_dwordx4 v[240:241], off
	s_mov_b32 m0, s64
	s_nop 0
	global_load_lds_dwordx4 v[242:243], off
	s_waitcnt vmcnt(8)
	s_waitcnt lgkmcnt(0)
	s_barrier
	v_mfma_f32_16x16x32_bf16 v[60:63], v[138:141], v[208:211], v[60:63]
	v_mfma_f32_16x16x32_bf16 v[56:59], v[160:163], v[208:211], v[56:59]
	v_mfma_f32_16x16x32_bf16 v[44:47], v[138:141], v[216:219], v[44:47]
	v_mfma_f32_16x16x32_bf16 v[40:43], v[160:163], v[216:219], v[40:43]
	v_mfma_f32_16x16x32_bf16 v[28:31], v[138:141], v[224:227], v[28:31]
	v_mfma_f32_16x16x32_bf16 v[24:27], v[160:163], v[224:227], v[24:27]
	v_mfma_f32_16x16x32_bf16 v[12:15], v[138:141], v[232:235], v[12:15]
	v_mfma_f32_16x16x32_bf16 v[8:11], v[160:163], v[232:235], v[8:11]
	v_mfma_f32_16x16x32_bf16 v[60:63], v[156:159], v[212:215], v[60:63]
	v_mfma_f32_16x16x32_bf16 v[56:59], v[164:167], v[212:215], v[56:59]
	v_mfma_f32_16x16x32_bf16 v[44:47], v[156:159], v[220:223], v[44:47]
	v_mfma_f32_16x16x32_bf16 v[40:43], v[164:167], v[220:223], v[40:43]
	v_mfma_f32_16x16x32_bf16 v[28:31], v[156:159], v[228:231], v[28:31]
	v_mfma_f32_16x16x32_bf16 v[24:27], v[164:167], v[228:231], v[24:27]
	v_mfma_f32_16x16x32_bf16 v[12:15], v[156:159], v[236:239], v[12:15]
	v_mfma_f32_16x16x32_bf16 v[8:11], v[164:167], v[236:239], v[8:11]
	v_mfma_f32_16x16x32_bf16 v[52:55], v[168:171], v[208:211], v[52:55]
	v_mfma_f32_16x16x32_bf16 v[48:51], v[176:179], v[208:211], v[48:51]
	v_mfma_f32_16x16x32_bf16 v[36:39], v[168:171], v[216:219], v[36:39]
	v_mfma_f32_16x16x32_bf16 v[32:35], v[176:179], v[216:219], v[32:35]
	v_mfma_f32_16x16x32_bf16 v[20:23], v[168:171], v[224:227], v[20:23]
	v_mfma_f32_16x16x32_bf16 v[16:19], v[176:179], v[224:227], v[16:19]
	v_mfma_f32_16x16x32_bf16 v[4:7], v[168:171], v[232:235], v[4:7]
	v_mfma_f32_16x16x32_bf16 v[0:3], v[176:179], v[232:235], v[0:3]
	v_mfma_f32_16x16x32_bf16 v[52:55], v[172:175], v[212:215], v[52:55]
	v_mfma_f32_16x16x32_bf16 v[48:51], v[204:207], v[212:215], v[48:51]
	v_mfma_f32_16x16x32_bf16 v[36:39], v[172:175], v[220:223], v[36:39]
	v_mfma_f32_16x16x32_bf16 v[32:35], v[204:207], v[220:223], v[32:35]
	v_mfma_f32_16x16x32_bf16 v[20:23], v[172:175], v[228:231], v[20:23]
	v_mfma_f32_16x16x32_bf16 v[16:19], v[204:207], v[228:231], v[16:19]
	v_mfma_f32_16x16x32_bf16 v[4:7], v[172:175], v[236:239], v[4:7]
	v_mfma_f32_16x16x32_bf16 v[0:3], v[204:207], v[236:239], v[0:3]
	s_barrier
	s_add_i32 s74, 0, 0x18000
	s_add_i32 s75, 0, 0x1c000
	v_add_u32_e32 v164, s74, v143
	v_add_u32_e32 v204, s75, v143
	ds_read_b128 v[138:141], v164
	ds_read_b128 v[156:159], v164 offset:1024
	ds_read_b128 v[160:163], v164 offset:2048
	ds_read_b128 v[164:167], v164 offset:3072
	ds_read_b128 v[168:171], v204
	ds_read_b128 v[172:175], v204 offset:1024
	ds_read_b128 v[176:179], v204 offset:2048
	ds_read_b128 v[204:207], v204 offset:3072
	s_add_u32 s4, s60, 0x40000
	s_addc_u32 s5, s61, 0
	s_mov_b32 m0, s65
	v_lshl_add_u64 v[244:245], s[4:5], 0, v[132:133]
	ds_read_b128 v[208:211], v155 offset:32768
	ds_read_b128 v[212:215], v155 offset:33792
	ds_read_b128 v[216:219], v155 offset:34816
	ds_read_b128 v[220:223], v155 offset:35840
	ds_read_b128 v[224:227], v155 offset:36864
	ds_read_b128 v[228:231], v155 offset:37888
	ds_read_b128 v[232:235], v155 offset:38912
	ds_read_b128 v[236:239], v155 offset:39936
	global_load_lds_dwordx4 v[244:245], off
	v_lshl_add_u64 v[244:245], s[4:5], 0, v[130:131]
	s_mov_b32 m0, s66
	s_nop 0
	global_load_lds_dwordx4 v[244:245], off
	s_waitcnt vmcnt(8)
	s_waitcnt lgkmcnt(0)
	s_barrier
	v_mfma_f32_16x16x32_bf16 v[124:127], v[138:141], v[208:211], v[124:127]
	v_mfma_f32_16x16x32_bf16 v[120:123], v[160:163], v[208:211], v[120:123]
	v_mfma_f32_16x16x32_bf16 v[108:111], v[138:141], v[216:219], v[108:111]
	v_mfma_f32_16x16x32_bf16 v[104:107], v[160:163], v[216:219], v[104:107]
	v_mfma_f32_16x16x32_bf16 v[92:95], v[138:141], v[224:227], v[92:95]
	v_mfma_f32_16x16x32_bf16 v[88:91], v[160:163], v[224:227], v[88:91]
	v_mfma_f32_16x16x32_bf16 v[76:79], v[138:141], v[232:235], v[76:79]
	v_mfma_f32_16x16x32_bf16 v[72:75], v[160:163], v[232:235], v[72:75]
	v_mfma_f32_16x16x32_bf16 v[124:127], v[156:159], v[212:215], v[124:127]
	v_mfma_f32_16x16x32_bf16 v[120:123], v[164:167], v[212:215], v[120:123]
	v_mfma_f32_16x16x32_bf16 v[108:111], v[156:159], v[220:223], v[108:111]
	v_mfma_f32_16x16x32_bf16 v[104:107], v[164:167], v[220:223], v[104:107]
	v_mfma_f32_16x16x32_bf16 v[92:95], v[156:159], v[228:231], v[92:95]
	v_mfma_f32_16x16x32_bf16 v[88:91], v[164:167], v[228:231], v[88:91]
	v_mfma_f32_16x16x32_bf16 v[76:79], v[156:159], v[236:239], v[76:79]
	v_mfma_f32_16x16x32_bf16 v[72:75], v[164:167], v[236:239], v[72:75]
	v_mfma_f32_16x16x32_bf16 v[116:119], v[168:171], v[208:211], v[116:119]
	v_mfma_f32_16x16x32_bf16 v[112:115], v[176:179], v[208:211], v[112:115]
	v_mfma_f32_16x16x32_bf16 v[100:103], v[168:171], v[216:219], v[100:103]
	v_mfma_f32_16x16x32_bf16 v[96:99], v[176:179], v[216:219], v[96:99]
	v_mfma_f32_16x16x32_bf16 v[84:87], v[168:171], v[224:227], v[84:87]
	v_mfma_f32_16x16x32_bf16 v[80:83], v[176:179], v[224:227], v[80:83]
	v_mfma_f32_16x16x32_bf16 v[68:71], v[168:171], v[232:235], v[68:71]
	v_mfma_f32_16x16x32_bf16 v[64:67], v[176:179], v[232:235], v[64:67]
	v_mfma_f32_16x16x32_bf16 v[116:119], v[172:175], v[212:215], v[116:119]
	v_mfma_f32_16x16x32_bf16 v[112:115], v[204:207], v[212:215], v[112:115]
	v_mfma_f32_16x16x32_bf16 v[100:103], v[172:175], v[220:223], v[100:103]
	v_mfma_f32_16x16x32_bf16 v[96:99], v[204:207], v[220:223], v[96:99]
	v_mfma_f32_16x16x32_bf16 v[84:87], v[172:175], v[228:231], v[84:87]
	v_mfma_f32_16x16x32_bf16 v[80:83], v[204:207], v[228:231], v[80:83]
	v_mfma_f32_16x16x32_bf16 v[68:71], v[172:175], v[236:239], v[68:71]
	v_mfma_f32_16x16x32_bf16 v[64:67], v[204:207], v[236:239], v[64:67]
	s_barrier
	s_add_i32 s4, s74, s1
	v_lshl_add_u64 v[180:181], v[180:181], 0, s[26:27]
	s_mov_b32 m0, s4
	ds_read_b128 v[208:211], v155 offset:49152
	ds_read_b128 v[212:215], v155 offset:50176
	ds_read_b128 v[216:219], v155 offset:51200
	ds_read_b128 v[220:223], v155 offset:52224
	ds_read_b128 v[224:227], v155 offset:53248
	ds_read_b128 v[228:231], v155 offset:54272
	ds_read_b128 v[232:235], v155 offset:55296
	ds_read_b128 v[236:239], v155 offset:56320
	global_load_lds_dwordx4 v[180:181], off
	s_add_i32 m0, s4, 0x2000
	s_add_u32 s4, s34, 0x40080
	v_lshl_add_u64 v[180:181], v[202:203], 0, s[26:27]
	s_addc_u32 s5, s35, 0
	s_add_i32 s34, s75, s1
	global_load_lds_dwordx4 v[180:181], off
	v_lshl_add_u64 v[180:181], s[4:5], 0, v[144:145]
	s_mov_b32 m0, s34
	s_nop 0
	global_load_lds_dwordx4 v[180:181], off
	v_lshl_add_u64 v[180:181], s[4:5], 0, v[128:129]
	s_add_i32 m0, s34, 0x2000
	s_nop 0
	global_load_lds_dwordx4 v[180:181], off
	v_lshl_add_u64 v[180:181], v[240:241], 0, s[26:27]
	s_mov_b32 m0, s67
	s_nop 0
	global_load_lds_dwordx4 v[180:181], off
	v_lshl_add_u64 v[180:181], v[242:243], 0, s[26:27]
	s_mov_b32 m0, s68
	s_nop 0
	global_load_lds_dwordx4 v[180:181], off
	s_waitcnt vmcnt(8)
	s_waitcnt lgkmcnt(0)
	s_barrier
	v_mfma_f32_16x16x32_bf16 v[60:63], v[138:141], v[208:211], v[60:63]
	v_mfma_f32_16x16x32_bf16 v[56:59], v[160:163], v[208:211], v[56:59]
	v_mfma_f32_16x16x32_bf16 v[44:47], v[138:141], v[216:219], v[44:47]
	v_mfma_f32_16x16x32_bf16 v[40:43], v[160:163], v[216:219], v[40:43]
	v_mfma_f32_16x16x32_bf16 v[28:31], v[138:141], v[224:227], v[28:31]
	v_mfma_f32_16x16x32_bf16 v[24:27], v[160:163], v[224:227], v[24:27]
	v_mfma_f32_16x16x32_bf16 v[12:15], v[138:141], v[232:235], v[12:15]
	v_mfma_f32_16x16x32_bf16 v[8:11], v[160:163], v[232:235], v[8:11]
	v_mfma_f32_16x16x32_bf16 v[60:63], v[156:159], v[212:215], v[60:63]
	v_mfma_f32_16x16x32_bf16 v[56:59], v[164:167], v[212:215], v[56:59]
	v_mfma_f32_16x16x32_bf16 v[44:47], v[156:159], v[220:223], v[44:47]
	v_mfma_f32_16x16x32_bf16 v[40:43], v[164:167], v[220:223], v[40:43]
	v_mfma_f32_16x16x32_bf16 v[28:31], v[156:159], v[228:231], v[28:31]
	v_mfma_f32_16x16x32_bf16 v[24:27], v[164:167], v[228:231], v[24:27]
	v_mfma_f32_16x16x32_bf16 v[12:15], v[156:159], v[236:239], v[12:15]
	v_mfma_f32_16x16x32_bf16 v[8:11], v[164:167], v[236:239], v[8:11]
	v_mfma_f32_16x16x32_bf16 v[52:55], v[168:171], v[208:211], v[52:55]
	v_mfma_f32_16x16x32_bf16 v[48:51], v[176:179], v[208:211], v[48:51]
	v_mfma_f32_16x16x32_bf16 v[36:39], v[168:171], v[216:219], v[36:39]
	v_mfma_f32_16x16x32_bf16 v[32:35], v[176:179], v[216:219], v[32:35]
	v_mfma_f32_16x16x32_bf16 v[20:23], v[168:171], v[224:227], v[20:23]
	v_mfma_f32_16x16x32_bf16 v[16:19], v[176:179], v[224:227], v[16:19]
	v_mfma_f32_16x16x32_bf16 v[4:7], v[168:171], v[232:235], v[4:7]
	v_mfma_f32_16x16x32_bf16 v[0:3], v[176:179], v[232:235], v[0:3]
	v_mfma_f32_16x16x32_bf16 v[52:55], v[172:175], v[212:215], v[52:55]
	v_mfma_f32_16x16x32_bf16 v[48:51], v[204:207], v[212:215], v[48:51]
	v_mfma_f32_16x16x32_bf16 v[36:39], v[172:175], v[220:223], v[36:39]
	v_mfma_f32_16x16x32_bf16 v[32:35], v[204:207], v[220:223], v[32:35]
	v_mfma_f32_16x16x32_bf16 v[20:23], v[172:175], v[228:231], v[20:23]
	v_mfma_f32_16x16x32_bf16 v[16:19], v[204:207], v[228:231], v[16:19]
	v_mfma_f32_16x16x32_bf16 v[4:7], v[172:175], v[236:239], v[4:7]
	v_mfma_f32_16x16x32_bf16 v[0:3], v[204:207], v[236:239], v[0:3]
	s_barrier
	s_add_i32 s73, s73, 2
	s_add_u32 s2, s2, 0x100
	s_addc_u32 s3, s3, 0
	s_add_u32 s71, s71, 0x100
	s_addc_u32 s72, s72, 0
	s_cmp_gt_u32 s73, 13
	s_cbranch_scc0 .LBB0_1305
	s_setprio 0
	v_lshl_add_u32 v140, s58, 8, v142
	v_ashrrev_i32_e32 v141, 31, v140
	v_lshl_add_u64 v[156:157], v[140:141], 4, s[44:45]
	global_load_dwordx4 v[208:211], v[156:157], off
	global_load_dwordx4 v[212:215], v[156:157], off offset:256
	global_load_dwordx4 v[216:219], v[156:157], off offset:512
	global_load_dwordx4 v[220:223], v[156:157], off offset:768
	global_load_dwordx4 v[224:227], v[156:157], off offset:2048
	global_load_dwordx4 v[228:231], v[156:157], off offset:2304
	global_load_dwordx4 v[232:235], v[156:157], off offset:2560
	global_load_dwordx4 v[236:239], v[156:157], off offset:2816
	s_and_b64 vcc, exec, s[46:47]
	s_cbranch_vccz .LBB0_1308
	s_barrier

.Lkprio_1399:
.LBB0_1399:
	s_add_u32 s58, s54, 0x100
	s_addc_u32 s59, s55, 0
	s_add_i32 s4, 0, 0x10000
	s_cmp_eq_u32 s29, 40
	s_cselect_b32 s61, s45, s59
	s_cselect_b32 s60, s44, s58
	v_add_u32_e32 v142, s4, v160
	s_cselect_b32 s35, s53, s28
	s_cselect_b32 s34, s52, s3
	s_add_i32 s47, 0, 0x14000
	ds_read_b128 v[138:141], v142
	ds_read_b128 v[154:157], v142 offset:1024
	ds_read_b128 v[172:175], v142 offset:2048
	ds_read_b128 v[176:179], v142 offset:3072
	v_add_u32_e32 v142, s47, v160
	ds_read_b128 v[204:207], v142
	ds_read_b128 v[208:211], v142 offset:1024
	ds_read_b128 v[212:215], v142 offset:2048
	ds_read_b128 v[216:219], v142 offset:3072
	v_lshl_add_u64 v[142:143], s[54:55], 0, v[134:135]
	s_add_i32 m0, s65, 0xc000
	ds_read_b128 v[220:223], v170
	ds_read_b128 v[224:227], v170 offset:1024
	ds_read_b128 v[228:231], v170 offset:2048
	ds_read_b128 v[232:235], v170 offset:3072
	ds_read_b128 v[236:239], v170 offset:4096
	ds_read_b128 v[240:243], v170 offset:5120
	ds_read_b128 v[244:247], v170 offset:6144
	ds_read_b128 v[248:251], v170 offset:7168
	global_load_lds_dwordx4 v[142:143], off
	v_lshl_add_u64 v[142:143], s[54:55], 0, v[136:137]
	s_add_i32 m0, s65, 0xe000
	s_nop 0
	global_load_lds_dwordx4 v[142:143], off
	s_waitcnt vmcnt(8)
	s_waitcnt lgkmcnt(0)
	s_barrier
	v_mfma_f32_16x16x32_bf16 v[124:127], v[138:141], v[220:223], v[124:127]
	v_mfma_f32_16x16x32_bf16 v[120:123], v[172:175], v[220:223], v[120:123]
	v_mfma_f32_16x16x32_bf16 v[108:111], v[138:141], v[228:231], v[108:111]
	v_mfma_f32_16x16x32_bf16 v[104:107], v[172:175], v[228:231], v[104:107]
	v_mfma_f32_16x16x32_bf16 v[92:95], v[138:141], v[236:239], v[92:95]
	v_mfma_f32_16x16x32_bf16 v[88:91], v[172:175], v[236:239], v[88:91]
	v_mfma_f32_16x16x32_bf16 v[76:79], v[138:141], v[244:247], v[76:79]
	v_mfma_f32_16x16x32_bf16 v[72:75], v[172:175], v[244:247], v[72:75]
	v_mfma_f32_16x16x32_bf16 v[124:127], v[154:157], v[224:227], v[124:127]
	v_mfma_f32_16x16x32_bf16 v[120:123], v[176:179], v[224:227], v[120:123]
	v_mfma_f32_16x16x32_bf16 v[108:111], v[154:157], v[232:235], v[108:111]
	v_mfma_f32_16x16x32_bf16 v[104:107], v[176:179], v[232:235], v[104:107]
	v_mfma_f32_16x16x32_bf16 v[92:95], v[154:157], v[240:243], v[92:95]
	v_mfma_f32_16x16x32_bf16 v[88:91], v[176:179], v[240:243], v[88:91]
	v_mfma_f32_16x16x32_bf16 v[76:79], v[154:157], v[248:251], v[76:79]
	v_mfma_f32_16x16x32_bf16 v[72:75], v[176:179], v[248:251], v[72:75]
	v_mfma_f32_16x16x32_bf16 v[116:119], v[204:207], v[220:223], v[116:119]
	v_mfma_f32_16x16x32_bf16 v[112:115], v[212:215], v[220:223], v[112:115]
	v_mfma_f32_16x16x32_bf16 v[100:103], v[204:207], v[228:231], v[100:103]
	v_mfma_f32_16x16x32_bf16 v[96:99], v[212:215], v[228:231], v[96:99]
	v_mfma_f32_16x16x32_bf16 v[84:87], v[204:207], v[236:239], v[84:87]
	v_mfma_f32_16x16x32_bf16 v[80:83], v[212:215], v[236:239], v[80:83]
	v_mfma_f32_16x16x32_bf16 v[68:71], v[204:207], v[244:247], v[68:71]
	v_mfma_f32_16x16x32_bf16 v[64:67], v[212:215], v[244:247], v[64:67]
	v_mfma_f32_16x16x32_bf16 v[116:119], v[208:211], v[224:227], v[116:119]
	v_mfma_f32_16x16x32_bf16 v[112:115], v[216:219], v[224:227], v[112:115]
	v_mfma_f32_16x16x32_bf16 v[100:103], v[208:211], v[232:235], v[100:103]
	v_mfma_f32_16x16x32_bf16 v[96:99], v[216:219], v[232:235], v[96:99]
	v_mfma_f32_16x16x32_bf16 v[84:87], v[208:211], v[240:243], v[84:87]
	v_mfma_f32_16x16x32_bf16 v[80:83], v[216:219], v[240:243], v[80:83]
	v_mfma_f32_16x16x32_bf16 v[68:71], v[208:211], v[248:251], v[68:71]
	v_mfma_f32_16x16x32_bf16 v[64:67], v[216:219], v[248:251], v[64:67]
	s_barrier
	s_add_i32 s4, s4, s33
	v_lshl_add_u64 v[142:143], s[34:35], 0, v[128:129]
	s_mov_b32 m0, s4
	ds_read_b128 v[220:223], v170 offset:16384
	ds_read_b128 v[224:227], v170 offset:17408
	ds_read_b128 v[228:231], v170 offset:18432
	ds_read_b128 v[232:235], v170 offset:19456
	ds_read_b128 v[236:239], v170 offset:20480
	ds_read_b128 v[240:243], v170 offset:21504
	ds_read_b128 v[244:247], v170 offset:22528
	ds_read_b128 v[248:251], v170 offset:23552
	global_load_lds_dwordx4 v[142:143], off
	s_add_i32 m0, s4, 0x2000
	s_add_u32 s4, s34, 0xb0000
	v_lshl_add_u64 v[158:159], s[34:35], 0, v[130:131]
	s_addc_u32 s5, s35, 0
	s_add_i32 s47, s47, s33
	global_load_lds_dwordx4 v[158:159], off
	v_lshl_add_u64 v[180:181], s[4:5], 0, v[128:129]
	s_mov_b32 m0, s47
	v_lshl_add_u64 v[202:203], s[60:61], 0, v[130:131]
	global_load_lds_dwordx4 v[180:181], off
	v_lshl_add_u64 v[180:181], s[4:5], 0, v[130:131]
	s_add_i32 m0, s47, 0x2000
	s_nop 0
	global_load_lds_dwordx4 v[180:181], off
	v_lshl_add_u64 v[180:181], s[60:61], 0, v[128:129]
	s_mov_b32 m0, s65
	s_nop 0
	global_load_lds_dwordx4 v[180:181], off
	s_mov_b32 m0, s66
	s_nop 0
	global_load_lds_dwordx4 v[202:203], off
	s_waitcnt vmcnt(8)
	s_waitcnt lgkmcnt(0)
	s_barrier
	v_mfma_f32_16x16x32_bf16 v[60:63], v[138:141], v[220:223], v[60:63]
	v_mfma_f32_16x16x32_bf16 v[56:59], v[172:175], v[220:223], v[56:59]
	v_mfma_f32_16x16x32_bf16 v[44:47], v[138:141], v[228:231], v[44:47]
	v_mfma_f32_16x16x32_bf16 v[40:43], v[172:175], v[228:231], v[40:43]
	v_mfma_f32_16x16x32_bf16 v[28:31], v[138:141], v[236:239], v[28:31]
	v_mfma_f32_16x16x32_bf16 v[24:27], v[172:175], v[236:239], v[24:27]
	v_mfma_f32_16x16x32_bf16 v[12:15], v[138:141], v[244:247], v[12:15]
	v_mfma_f32_16x16x32_bf16 v[8:11], v[172:175], v[244:247], v[8:11]
	v_mfma_f32_16x16x32_bf16 v[60:63], v[154:157], v[224:227], v[60:63]
	v_mfma_f32_16x16x32_bf16 v[56:59], v[176:179], v[224:227], v[56:59]
	v_mfma_f32_16x16x32_bf16 v[44:47], v[154:157], v[232:235], v[44:47]
	v_mfma_f32_16x16x32_bf16 v[40:43], v[176:179], v[232:235], v[40:43]
	v_mfma_f32_16x16x32_bf16 v[28:31], v[154:157], v[240:243], v[28:31]
	v_mfma_f32_16x16x32_bf16 v[24:27], v[176:179], v[240:243], v[24:27]
	v_mfma_f32_16x16x32_bf16 v[12:15], v[154:157], v[248:251], v[12:15]
	v_mfma_f32_16x16x32_bf16 v[8:11], v[176:179], v[248:251], v[8:11]
	v_mfma_f32_16x16x32_bf16 v[52:55], v[204:207], v[220:223], v[52:55]
	v_mfma_f32_16x16x32_bf16 v[48:51], v[212:215], v[220:223], v[48:51]
	v_mfma_f32_16x16x32_bf16 v[36:39], v[204:207], v[228:231], v[36:39]
	v_mfma_f32_16x16x32_bf16 v[32:35], v[212:215], v[228:231], v[32:35]
	v_mfma_f32_16x16x32_bf16 v[20:23], v[204:207], v[236:239], v[20:23]
	v_mfma_f32_16x16x32_bf16 v[16:19], v[212:215], v[236:239], v[16:19]
	v_mfma_f32_16x16x32_bf16 v[4:7], v[204:207], v[244:247], v[4:7]
	v_mfma_f32_16x16x32_bf16 v[0:3], v[212:215], v[244:247], v[0:3]
	v_mfma_f32_16x16x32_bf16 v[52:55], v[208:211], v[224:227], v[52:55]
	v_mfma_f32_16x16x32_bf16 v[48:51], v[216:219], v[224:227], v[48:51]
	v_mfma_f32_16x16x32_bf16 v[36:39], v[208:211], v[232:235], v[36:39]
	v_mfma_f32_16x16x32_bf16 v[32:35], v[216:219], v[232:235], v[32:35]
	v_mfma_f32_16x16x32_bf16 v[20:23], v[208:211], v[240:243], v[20:23]
	v_mfma_f32_16x16x32_bf16 v[16:19], v[216:219], v[240:243], v[16:19]
	v_mfma_f32_16x16x32_bf16 v[4:7], v[208:211], v[248:251], v[4:7]
	v_mfma_f32_16x16x32_bf16 v[0:3], v[216:219], v[248:251], v[0:3]
	s_barrier
	s_add_i32 s47, 0, 0x18000
	v_add_u32_e32 v144, s47, v160
	s_add_i32 s54, 0, 0x1c000
	ds_read_b128 v[138:141], v144
	ds_read_b128 v[154:157], v144 offset:1024
	ds_read_b128 v[172:175], v144 offset:2048
	ds_read_b128 v[176:179], v144 offset:3072
	v_add_u32_e32 v144, s54, v160
	ds_read_b128 v[204:207], v144
	ds_read_b128 v[208:211], v144 offset:1024
	ds_read_b128 v[212:215], v144 offset:2048
	ds_read_b128 v[216:219], v144 offset:3072
	s_add_u32 s4, s60, 0xb0000
	s_addc_u32 s5, s61, 0
	s_mov_b32 m0, s67
	v_lshl_add_u64 v[252:253], s[4:5], 0, v[128:129]
	ds_read_b128 v[220:223], v170 offset:32768
	ds_read_b128 v[224:227], v170 offset:33792
	ds_read_b128 v[228:231], v170 offset:34816
	ds_read_b128 v[232:235], v170 offset:35840
	ds_read_b128 v[236:239], v170 offset:36864
	ds_read_b128 v[240:243], v170 offset:37888
	ds_read_b128 v[244:247], v170 offset:38912
	ds_read_b128 v[248:251], v170 offset:39936
	global_load_lds_dwordx4 v[252:253], off
	v_lshl_add_u64 v[252:253], s[4:5], 0, v[130:131]
	s_mov_b32 m0, s68
	s_nop 0
	global_load_lds_dwordx4 v[252:253], off
	s_waitcnt vmcnt(8)
	s_waitcnt lgkmcnt(0)
	s_barrier
	v_mfma_f32_16x16x32_bf16 v[124:127], v[138:141], v[220:223], v[124:127]
	v_mfma_f32_16x16x32_bf16 v[120:123], v[172:175], v[220:223], v[120:123]
	v_mfma_f32_16x16x32_bf16 v[108:111], v[138:141], v[228:231], v[108:111]
	v_mfma_f32_16x16x32_bf16 v[104:107], v[172:175], v[228:231], v[104:107]
	v_mfma_f32_16x16x32_bf16 v[92:95], v[138:141], v[236:239], v[92:95]
	v_mfma_f32_16x16x32_bf16 v[88:91], v[172:175], v[236:239], v[88:91]
	v_mfma_f32_16x16x32_bf16 v[76:79], v[138:141], v[244:247], v[76:79]
	v_mfma_f32_16x16x32_bf16 v[72:75], v[172:175], v[244:247], v[72:75]
	v_mfma_f32_16x16x32_bf16 v[124:127], v[154:157], v[224:227], v[124:127]
	v_mfma_f32_16x16x32_bf16 v[120:123], v[176:179], v[224:227], v[120:123]
	v_mfma_f32_16x16x32_bf16 v[108:111], v[154:157], v[232:235], v[108:111]
	v_mfma_f32_16x16x32_bf16 v[104:107], v[176:179], v[232:235], v[104:107]
	v_mfma_f32_16x16x32_bf16 v[92:95], v[154:157], v[240:243], v[92:95]
	v_mfma_f32_16x16x32_bf16 v[88:91], v[176:179], v[240:243], v[88:91]
	v_mfma_f32_16x16x32_bf16 v[76:79], v[154:157], v[248:251], v[76:79]
	v_mfma_f32_16x16x32_bf16 v[72:75], v[176:179], v[248:251], v[72:75]
	v_mfma_f32_16x16x32_bf16 v[116:119], v[204:207], v[220:223], v[116:119]
	v_mfma_f32_16x16x32_bf16 v[112:115], v[212:215], v[220:223], v[112:115]
	v_mfma_f32_16x16x32_bf16 v[100:103], v[204:207], v[228:231], v[100:103]
	v_mfma_f32_16x16x32_bf16 v[96:99], v[212:215], v[228:231], v[96:99]
	v_mfma_f32_16x16x32_bf16 v[84:87], v[204:207], v[236:239], v[84:87]
	v_mfma_f32_16x16x32_bf16 v[80:83], v[212:215], v[236:239], v[80:83]
	v_mfma_f32_16x16x32_bf16 v[68:71], v[204:207], v[244:247], v[68:71]
	v_mfma_f32_16x16x32_bf16 v[64:67], v[212:215], v[244:247], v[64:67]
	v_mfma_f32_16x16x32_bf16 v[116:119], v[208:211], v[224:227], v[116:119]
	v_mfma_f32_16x16x32_bf16 v[112:115], v[216:219], v[224:227], v[112:115]
	v_mfma_f32_16x16x32_bf16 v[100:103], v[208:211], v[232:235], v[100:103]
	v_mfma_f32_16x16x32_bf16 v[96:99], v[216:219], v[232:235], v[96:99]
	v_mfma_f32_16x16x32_bf16 v[84:87], v[208:211], v[240:243], v[84:87]
	v_mfma_f32_16x16x32_bf16 v[80:83], v[216:219], v[240:243], v[80:83]
	v_mfma_f32_16x16x32_bf16 v[68:71], v[208:211], v[248:251], v[68:71]
	v_mfma_f32_16x16x32_bf16 v[64:67], v[216:219], v[248:251], v[64:67]
	s_barrier
	s_add_i32 s4, s47, s33
	v_lshl_add_u64 v[142:143], v[142:143], 0, s[26:27]
	s_mov_b32 m0, s4
	ds_read_b128 v[220:223], v170 offset:49152
	ds_read_b128 v[224:227], v170 offset:50176
	ds_read_b128 v[228:231], v170 offset:51200
	ds_read_b128 v[232:235], v170 offset:52224
	ds_read_b128 v[236:239], v170 offset:53248
	ds_read_b128 v[240:243], v170 offset:54272
	ds_read_b128 v[244:247], v170 offset:55296
	ds_read_b128 v[248:251], v170 offset:56320
	global_load_lds_dwordx4 v[142:143], off
	s_add_i32 m0, s4, 0x2000
	s_add_u32 s4, s34, 0xb0080
	v_lshl_add_u64 v[142:143], v[158:159], 0, s[26:27]
	s_addc_u32 s5, s35, 0
	s_add_i32 s34, s54, s33
	global_load_lds_dwordx4 v[142:143], off
	v_lshl_add_u64 v[142:143], s[4:5], 0, v[128:129]
	s_mov_b32 m0, s34
	s_nop 0
	global_load_lds_dwordx4 v[142:143], off
	v_lshl_add_u64 v[142:143], s[4:5], 0, v[130:131]
	s_add_i32 m0, s34, 0x2000
	s_nop 0
	global_load_lds_dwordx4 v[142:143], off
	v_lshl_add_u64 v[142:143], v[180:181], 0, s[26:27]
	s_mov_b32 m0, s69
	s_nop 0
	global_load_lds_dwordx4 v[142:143], off
	v_lshl_add_u64 v[142:143], v[202:203], 0, s[26:27]
	s_mov_b32 m0, s70
	s_nop 0
	global_load_lds_dwordx4 v[142:143], off
	s_waitcnt vmcnt(8)
	s_waitcnt lgkmcnt(0)
	s_barrier
	v_mfma_f32_16x16x32_bf16 v[60:63], v[138:141], v[220:223], v[60:63]
	v_mfma_f32_16x16x32_bf16 v[56:59], v[172:175], v[220:223], v[56:59]
	v_mfma_f32_16x16x32_bf16 v[44:47], v[138:141], v[228:231], v[44:47]
	v_mfma_f32_16x16x32_bf16 v[40:43], v[172:175], v[228:231], v[40:43]
	v_mfma_f32_16x16x32_bf16 v[28:31], v[138:141], v[236:239], v[28:31]
	v_mfma_f32_16x16x32_bf16 v[24:27], v[172:175], v[236:239], v[24:27]
	v_mfma_f32_16x16x32_bf16 v[12:15], v[138:141], v[244:247], v[12:15]
	v_mfma_f32_16x16x32_bf16 v[8:11], v[172:175], v[244:247], v[8:11]
	v_mfma_f32_16x16x32_bf16 v[60:63], v[154:157], v[224:227], v[60:63]
	v_mfma_f32_16x16x32_bf16 v[56:59], v[176:179], v[224:227], v[56:59]
	v_mfma_f32_16x16x32_bf16 v[44:47], v[154:157], v[232:235], v[44:47]
	v_mfma_f32_16x16x32_bf16 v[40:43], v[176:179], v[232:235], v[40:43]
	v_mfma_f32_16x16x32_bf16 v[28:31], v[154:157], v[240:243], v[28:31]
	v_mfma_f32_16x16x32_bf16 v[24:27], v[176:179], v[240:243], v[24:27]
	v_mfma_f32_16x16x32_bf16 v[12:15], v[154:157], v[248:251], v[12:15]
	v_mfma_f32_16x16x32_bf16 v[8:11], v[176:179], v[248:251], v[8:11]
	v_mfma_f32_16x16x32_bf16 v[52:55], v[204:207], v[220:223], v[52:55]
	v_mfma_f32_16x16x32_bf16 v[48:51], v[212:215], v[220:223], v[48:51]
	v_mfma_f32_16x16x32_bf16 v[36:39], v[204:207], v[228:231], v[36:39]
	v_mfma_f32_16x16x32_bf16 v[32:35], v[212:215], v[228:231], v[32:35]
	v_mfma_f32_16x16x32_bf16 v[20:23], v[204:207], v[236:239], v[20:23]
	v_mfma_f32_16x16x32_bf16 v[16:19], v[212:215], v[236:239], v[16:19]
	v_mfma_f32_16x16x32_bf16 v[4:7], v[204:207], v[244:247], v[4:7]
	v_mfma_f32_16x16x32_bf16 v[0:3], v[212:215], v[244:247], v[0:3]
	v_mfma_f32_16x16x32_bf16 v[52:55], v[208:211], v[224:227], v[52:55]
	v_mfma_f32_16x16x32_bf16 v[48:51], v[216:219], v[224:227], v[48:51]
	v_mfma_f32_16x16x32_bf16 v[36:39], v[208:211], v[232:235], v[36:39]
	v_mfma_f32_16x16x32_bf16 v[32:35], v[216:219], v[232:235], v[32:35]
	v_mfma_f32_16x16x32_bf16 v[20:23], v[208:211], v[240:243], v[20:23]
	v_mfma_f32_16x16x32_bf16 v[16:19], v[216:219], v[240:243], v[16:19]
	v_mfma_f32_16x16x32_bf16 v[4:7], v[208:211], v[248:251], v[4:7]
	v_mfma_f32_16x16x32_bf16 v[0:3], v[216:219], v[248:251], v[0:3]
	s_barrier
	s_add_i32 s29, s29, 2
	s_add_u32 s3, s3, 0x100
	s_addc_u32 s28, s28, 0
	s_cmp_gt_u32 s29, 41
	s_mov_b64 s[54:55], s[58:59]
	s_cbranch_scc0 .LBB0_1399
	s_setprio 0
	s_and_b64 vcc, exec, s[50:51]
	s_cbranch_vccz .LBB0_1402
	s_barrier
